# GEMM epilogues: residual-add base loads batched ahead (P2,P8,P11,P13) and rms row-scale loads hoisted (P3,P9,P12); deleted instructions replaced by s_nop to keep store-data wait states
# speedup vs baseline: 1.0383x; 1.0030x over previous
; __device__ __forceinline__ unsigned pk2(float lo, float hi) { f32x2_t v = {lo, hi}; bf16x2_t b = __builtin_convertvector(v, bf16x2_t); return __builtin_bit_cast(unsigned, b); }
; __device__ __forceinline__ float xor16_sum(float v) { float a = v, b = v; swap16(a, b); return a + b; }
; __device__ __forceinline__ float xor32_sum(float v) { float a = v, b = v; swap32(a, b); return a + b; }
;     __device__ __forceinline__ void operator()(const f32x4 (&acc)[2][2][4][2], const Unit& u, int wr, int wc, int fr, int fq) const {
;         const int row0 = u.pm * BM + wr * 64 + fr; constexpr int ldc = 2048; constexpr float alpha = 0.5f * ALPHA2;
;         bf16_t* const xb = (bf16_t*)(ws + XBOFF); __attribute__((address_space(1))) float* const ss = (__attribute__((address_space(1))) float*)(ws + SSOFF);
; #pragma unroll
;         for (int ai = 0; ai < 2; ++ai)
; #pragma unroll
;             for (int m = 0; m < 4; ++m) {
;                 const int row = row0 + ai * HALF + m * 16; float sq = 0.f;
; #pragma unroll
;                 for (int bj = 0; bj < 2; ++bj)
; #pragma unroll
;                     for (int n = 0; n < 2; ++n) {
;                         const size_t idx = (size_t)row * ldc + u.pn * BM + bj * HALF + wc * 32 + 8 * fq + 4 * n;
;                         const f32x4 b = *(const f32x4*)(base + idx);
;                         const f32x4 v = b + acc[ai][bj][m][n] * alpha;
;                         *(f32x4*)(out + idx) = v;
;                         if (NORM) { u32x2 w; w.x = pk2(v[0], v[1]); w.y = pk2(v[2], v[3]); *(u32x2*)(xb + idx) = w; sq += (v[0] * v[0] + v[1] * v[1]) + (v[2] * v[2] + v[3] * v[3]); }
;                     }
;                 if (NORM) { sq = xor16_sum(sq); sq = xor32_sum(sq); if (fq == 0) __hip_atomic_fetch_add(ss + row, sq, __ATOMIC_RELAXED, __HIP_MEMORY_SCOPE_AGENT); }
.LBB0_423:
	v_lshl_add_u32 v148, s14, 8, v137
	s_lshl_b32 s12, s16, 8
	s_ashr_i32 s13, s12, 31
	v_ashrrev_i32_e32 v149, 31, v148
	v_mov_b32_e32 v147, s13
	v_or_b32_e32 v146, s12, v136
	v_lshlrev_b64 v[154:155], 11, v[148:149]
	v_lshl_add_u64 v[158:159], v[154:155], 0, v[146:147]
	v_lshlrev_b64 v[160:161], 2, v[158:159]
	v_lshl_add_u64 v[162:163], s[52:53], 0, v[160:161]
	v_mov_b32_e32 v232, v162
	v_mov_b32_e32 v233, v163
	v_mov_b32_e32 v231, 0
	v_mov_b32_e32 v230, 0x0
	v_lshl_add_u64 v[228:229], v[232:233], 0, v[230:231]
	global_load_dwordx4 v[164:167], v[228:229], off
	global_load_dwordx4 v[168:171], v[228:229], off offset:16
	global_load_dwordx4 v[172:175], v[228:229], off offset:512
	global_load_dwordx4 v[176:179], v[228:229], off offset:528
	v_mov_b32_e32 v230, 0x20000
	v_lshl_add_u64 v[228:229], v[232:233], 0, v[230:231]
	global_load_dwordx4 v[180:183], v[228:229], off
	global_load_dwordx4 v[188:191], v[228:229], off offset:16
	global_load_dwordx4 v[192:195], v[228:229], off offset:512
	global_load_dwordx4 v[196:199], v[228:229], off offset:528
	v_mov_b32_e32 v230, 0x40000
	v_lshl_add_u64 v[228:229], v[232:233], 0, v[230:231]
	global_load_dwordx4 v[200:203], v[228:229], off
	global_load_dwordx4 v[204:207], v[228:229], off offset:16
	global_load_dwordx4 v[208:211], v[228:229], off offset:512
	global_load_dwordx4 v[212:215], v[228:229], off offset:528
	v_mov_b32_e32 v230, 0x60000
	v_lshl_add_u64 v[228:229], v[232:233], 0, v[230:231]
	global_load_dwordx4 v[216:219], v[228:229], off
	global_load_dwordx4 v[220:223], v[228:229], off offset:16
	global_load_dwordx4 v[224:227], v[228:229], off offset:512
	global_load_dwordx4 v[234:237], v[228:229], off offset:528
	s_nop 0
	v_lshlrev_b64 v[158:159], 1, v[158:159]
	s_nop 0
	s_waitcnt vmcnt(12)
	v_pk_fma_f32 v[126:127], v[126:127], 0.5, v[166:167] op_sel_hi:[1,0,1]
	v_pk_fma_f32 v[124:125], v[124:125], 0.5, v[164:165] op_sel_hi:[1,0,1]
	v_lshl_add_u64 v[154:155], s[30:31], 0, v[160:161]
	global_store_dwordx4 v[154:155], v[124:127], off
	v_cvt_pk_bf16_f32 v156, v124, v125
	v_cvt_pk_bf16_f32 v157, v126, v127
	v_mul_f32_e32 v125, v125, v125
	v_lshl_add_u64 v[160:161], s[40:41], 0, v[158:159]
	v_fmac_f32_e32 v125, v124, v124
	v_mul_f32_e32 v124, v127, v127
	global_store_dwordx2 v[160:161], v[156:157], off
	v_fmac_f32_e32 v124, v126, v126
	v_add_f32_e32 v156, v125, v124
	s_nop 0
	s_nop 0
	v_pk_fma_f32 v[122:123], v[122:123], 0.5, v[170:171] op_sel_hi:[1,0,1]
	v_pk_fma_f32 v[120:121], v[120:121], 0.5, v[168:169] op_sel_hi:[1,0,1]
	global_store_dwordx4 v[154:155], v[120:123], off offset:16
	v_cvt_pk_bf16_f32 v124, v120, v121
	v_or_b32_e32 v126, 8, v158
	v_mul_f32_e32 v121, v121, v121
	v_mov_b32_e32 v127, v159
	v_fmac_f32_e32 v121, v120, v120
	v_mul_f32_e32 v120, v123, v123
	v_cvt_pk_bf16_f32 v125, v122, v123
	v_lshl_add_u64 v[126:127], s[40:41], 0, v[126:127]
	v_fmac_f32_e32 v120, v122, v122
	global_store_dwordx2 v[126:127], v[124:125], off
	v_add_f32_e32 v120, v121, v120
	v_add_f32_e32 v124, v156, v120
	s_nop 0
	s_nop 0
	v_pk_fma_f32 v[118:119], v[118:119], 0.5, v[174:175] op_sel_hi:[1,0,1]
	v_pk_fma_f32 v[116:117], v[116:117], 0.5, v[172:173] op_sel_hi:[1,0,1]
	global_store_dwordx4 v[154:155], v[116:119], off offset:512
	v_cvt_pk_bf16_f32 v120, v116, v117
	v_or_b32_e32 v122, 0x100, v158
	v_mul_f32_e32 v117, v117, v117
	v_mov_b32_e32 v123, v159
	v_fmac_f32_e32 v117, v116, v116
	v_mul_f32_e32 v116, v119, v119
	v_cvt_pk_bf16_f32 v121, v118, v119
	v_lshl_add_u64 v[122:123], s[40:41], 0, v[122:123]
	v_fmac_f32_e32 v116, v118, v118
	global_store_dwordx2 v[122:123], v[120:121], off
	v_add_f32_e32 v116, v117, v116
	v_add_f32_e32 v120, v124, v116
	s_nop 0
	v_or_b32_e32 v158, 0x108, v158
	s_nop 0
	v_pk_fma_f32 v[114:115], v[114:115], 0.5, v[178:179] op_sel_hi:[1,0,1]
	v_pk_fma_f32 v[112:113], v[112:113], 0.5, v[176:177] op_sel_hi:[1,0,1]
	v_mov_b32_e32 v230, 0x100000
	v_lshl_add_u64 v[228:229], v[232:233], 0, v[230:231]
	global_load_dwordx4 v[164:167], v[228:229], off
	global_load_dwordx4 v[168:171], v[228:229], off offset:16
	global_load_dwordx4 v[172:175], v[228:229], off offset:512
	global_load_dwordx4 v[176:179], v[228:229], off offset:528
	global_store_dwordx4 v[154:155], v[112:115], off offset:528
	v_cvt_pk_bf16_f32 v116, v112, v113
	v_cvt_pk_bf16_f32 v117, v114, v115
	v_mul_f32_e32 v113, v113, v113
	v_fmac_f32_e32 v113, v112, v112
	v_mul_f32_e32 v112, v115, v115
	v_fmac_f32_e32 v112, v114, v114
	v_add_f32_e32 v112, v113, v112
	v_add_f32_e32 v112, v120, v112
	v_mov_b32_e32 v113, v112
	s_nop 1
	v_permlane16_swap_b32 v112, v113
	v_lshl_add_u64 v[118:119], s[40:41], 0, v[158:159]
	v_add_f32_e32 v112, v112, v113
	v_mov_b32_e32 v113, v112
	global_store_dwordx2 v[118:119], v[116:117], off
	s_nop 1
	v_permlane32_swap_b32 v112, v113
	s_and_saveexec_b64 s[12:13], s[2:3]
	s_cbranch_execz .LBB0_425
	v_lshl_add_u64 v[114:115], v[148:149], 2, s[90:91]
	v_add_f32_e32 v112, v112, v113
	global_atomic_add_f32 v[114:115], v112, off
; __device__ __forceinline__ unsigned pk2(float lo, float hi) { f32x2_t v = {lo, hi}; bf16x2_t b = __builtin_convertvector(v, bf16x2_t); return __builtin_bit_cast(unsigned, b); }
; __device__ __forceinline__ float xor16_sum(float v) { float a = v, b = v; swap16(a, b); return a + b; }
; __device__ __forceinline__ float xor32_sum(float v) { float a = v, b = v; swap32(a, b); return a + b; }
;     __device__ __forceinline__ void operator()(const f32x4 (&acc)[2][2][4][2], const Unit& u, int wr, int wc, int fr, int fq) const {
;     ...
;                 const int row = row0 + ai * HALF + m * 16; float sq = 0.f;
; #pragma unroll
;                 for (int bj = 0; bj < 2; ++bj)
; #pragma unroll
;                     for (int n = 0; n < 2; ++n) {
;                         const size_t idx = (size_t)row * ldc + u.pn * BM + bj * HALF + wc * 32 + 8 * fq + 4 * n;
;                         const f32x4 b = *(const f32x4*)(base + idx);
;                         const f32x4 v = b + acc[ai][bj][m][n] * alpha;
;                         *(f32x4*)(out + idx) = v;
;                         if (NORM) { u32x2 w; w.x = pk2(v[0], v[1]); w.y = pk2(v[2], v[3]); *(u32x2*)(xb + idx) = w; sq += (v[0] * v[0] + v[1] * v[1]) + (v[2] * v[2] + v[3] * v[3]); }
;                     }
;                 if (NORM) { sq = xor16_sum(sq); sq = xor32_sum(sq); if (fq == 0) __hip_atomic_fetch_add(ss + row, sq, __ATOMIC_RELAXED, __HIP_MEMORY_SCOPE_AGENT); }
.LBB0_425:
	s_or_b64 exec, exec, s[12:13]
	v_or_b32_e32 v112, 16, v148
	v_ashrrev_i32_e32 v113, 31, v112
	v_lshlrev_b64 v[114:115], 11, v[112:113]
	v_lshl_add_u64 v[118:119], v[114:115], 0, v[146:147]
	v_lshlrev_b64 v[120:121], 2, v[118:119]
	v_lshl_add_u64 v[122:123], s[52:53], 0, v[120:121]
	s_nop 0
	v_lshlrev_b64 v[118:119], 1, v[118:119]
	s_nop 0
	s_waitcnt vmcnt(20)
	v_pk_fma_f32 v[110:111], v[110:111], 0.5, v[182:183] op_sel_hi:[1,0,1]
	v_pk_fma_f32 v[108:109], v[108:109], 0.5, v[180:181] op_sel_hi:[1,0,1]
	v_lshl_add_u64 v[114:115], s[30:31], 0, v[120:121]
	global_store_dwordx4 v[114:115], v[108:111], off
	v_cvt_pk_bf16_f32 v116, v108, v109
	v_cvt_pk_bf16_f32 v117, v110, v111
	v_mul_f32_e32 v109, v109, v109
	v_lshl_add_u64 v[120:121], s[40:41], 0, v[118:119]
	v_fmac_f32_e32 v109, v108, v108
	v_mul_f32_e32 v108, v111, v111
	global_store_dwordx2 v[120:121], v[116:117], off
	v_fmac_f32_e32 v108, v110, v110
	v_add_f32_e32 v116, v109, v108
	s_nop 0
	s_nop 0
	v_pk_fma_f32 v[106:107], v[106:107], 0.5, v[190:191] op_sel_hi:[1,0,1]
	v_pk_fma_f32 v[104:105], v[104:105], 0.5, v[188:189] op_sel_hi:[1,0,1]
	global_store_dwordx4 v[114:115], v[104:107], off offset:16
	v_cvt_pk_bf16_f32 v108, v104, v105
	v_or_b32_e32 v110, 8, v118
	v_mul_f32_e32 v105, v105, v105
	v_mov_b32_e32 v111, v119
	v_fmac_f32_e32 v105, v104, v104
	v_mul_f32_e32 v104, v107, v107
	v_cvt_pk_bf16_f32 v109, v106, v107
	v_lshl_add_u64 v[110:111], s[40:41], 0, v[110:111]
	v_fmac_f32_e32 v104, v106, v106
	global_store_dwordx2 v[110:111], v[108:109], off
	v_add_f32_e32 v104, v105, v104
	v_add_f32_e32 v108, v116, v104
	s_nop 0
	s_nop 0
	v_pk_fma_f32 v[102:103], v[102:103], 0.5, v[194:195] op_sel_hi:[1,0,1]
	v_pk_fma_f32 v[100:101], v[100:101], 0.5, v[192:193] op_sel_hi:[1,0,1]
	global_store_dwordx4 v[114:115], v[100:103], off offset:512
	v_cvt_pk_bf16_f32 v104, v100, v101
	v_or_b32_e32 v106, 0x100, v118
	v_mul_f32_e32 v101, v101, v101
	v_mov_b32_e32 v107, v119
	v_fmac_f32_e32 v101, v100, v100
	v_mul_f32_e32 v100, v103, v103
	v_cvt_pk_bf16_f32 v105, v102, v103
	v_lshl_add_u64 v[106:107], s[40:41], 0, v[106:107]
	v_fmac_f32_e32 v100, v102, v102
	global_store_dwordx2 v[106:107], v[104:105], off
	v_add_f32_e32 v100, v101, v100
	v_add_f32_e32 v104, v108, v100
	s_nop 0
	v_or_b32_e32 v118, 0x108, v118
	s_nop 0
	v_pk_fma_f32 v[98:99], v[98:99], 0.5, v[198:199] op_sel_hi:[1,0,1]
	v_pk_fma_f32 v[96:97], v[96:97], 0.5, v[196:197] op_sel_hi:[1,0,1]
	v_mov_b32_e32 v230, 0x120000
	v_lshl_add_u64 v[228:229], v[232:233], 0, v[230:231]
	global_load_dwordx4 v[180:183], v[228:229], off
	global_load_dwordx4 v[188:191], v[228:229], off offset:16
	global_load_dwordx4 v[192:195], v[228:229], off offset:512
	global_load_dwordx4 v[196:199], v[228:229], off offset:528
	global_store_dwordx4 v[114:115], v[96:99], off offset:528
	v_cvt_pk_bf16_f32 v100, v96, v97
	v_cvt_pk_bf16_f32 v101, v98, v99
	v_mul_f32_e32 v97, v97, v97
	v_fmac_f32_e32 v97, v96, v96
	v_mul_f32_e32 v96, v99, v99
	v_fmac_f32_e32 v96, v98, v98
	v_add_f32_e32 v96, v97, v96
	v_add_f32_e32 v96, v104, v96
	v_mov_b32_e32 v97, v96
	s_nop 1
	v_permlane16_swap_b32 v96, v97
	v_lshl_add_u64 v[102:103], s[40:41], 0, v[118:119]
	v_add_f32_e32 v96, v96, v97
	v_mov_b32_e32 v97, v96
	global_store_dwordx2 v[102:103], v[100:101], off
	s_nop 1
	v_permlane32_swap_b32 v96, v97
	s_and_saveexec_b64 s[12:13], s[2:3]
	s_cbranch_execz .LBB0_427
	v_lshl_add_u64 v[98:99], v[112:113], 2, s[90:91]
	v_add_f32_e32 v96, v96, v97
	global_atomic_add_f32 v[98:99], v96, off
.LBB0_427:
	s_or_b64 exec, exec, s[12:13]
	v_or_b32_e32 v96, 32, v148
	v_ashrrev_i32_e32 v97, 31, v96
	v_lshlrev_b64 v[98:99], 11, v[96:97]
	v_lshl_add_u64 v[102:103], v[98:99], 0, v[146:147]
	v_lshlrev_b64 v[104:105], 2, v[102:103]
	v_lshl_add_u64 v[106:107], s[52:53], 0, v[104:105]
	s_nop 0
	v_lshlrev_b64 v[102:103], 1, v[102:103]
	s_nop 0
	s_waitcnt vmcnt(28)
	v_pk_fma_f32 v[94:95], v[94:95], 0.5, v[202:203] op_sel_hi:[1,0,1]
	v_pk_fma_f32 v[92:93], v[92:93], 0.5, v[200:201] op_sel_hi:[1,0,1]
	v_lshl_add_u64 v[98:99], s[30:31], 0, v[104:105]
	global_store_dwordx4 v[98:99], v[92:95], off
	v_cvt_pk_bf16_f32 v100, v92, v93
	v_cvt_pk_bf16_f32 v101, v94, v95
	v_mul_f32_e32 v93, v93, v93
	v_lshl_add_u64 v[104:105], s[40:41], 0, v[102:103]
	v_fmac_f32_e32 v93, v92, v92
	v_mul_f32_e32 v92, v95, v95
	global_store_dwordx2 v[104:105], v[100:101], off
	v_fmac_f32_e32 v92, v94, v94
	v_add_f32_e32 v100, v93, v92
	s_nop 0
	s_nop 0
	v_pk_fma_f32 v[90:91], v[90:91], 0.5, v[206:207] op_sel_hi:[1,0,1]
	v_pk_fma_f32 v[88:89], v[88:89], 0.5, v[204:205] op_sel_hi:[1,0,1]
	global_store_dwordx4 v[98:99], v[88:91], off offset:16
	v_cvt_pk_bf16_f32 v92, v88, v89
	v_or_b32_e32 v94, 8, v102
	v_mul_f32_e32 v89, v89, v89
	v_mov_b32_e32 v95, v103
	v_fmac_f32_e32 v89, v88, v88
	v_mul_f32_e32 v88, v91, v91
	v_cvt_pk_bf16_f32 v93, v90, v91
	v_lshl_add_u64 v[94:95], s[40:41], 0, v[94:95]
	v_fmac_f32_e32 v88, v90, v90
	global_store_dwordx2 v[94:95], v[92:93], off
	v_add_f32_e32 v88, v89, v88
	v_add_f32_e32 v92, v100, v88
	s_nop 0
	s_nop 0
	v_pk_fma_f32 v[86:87], v[86:87], 0.5, v[210:211] op_sel_hi:[1,0,1]
	v_pk_fma_f32 v[84:85], v[84:85], 0.5, v[208:209] op_sel_hi:[1,0,1]
	global_store_dwordx4 v[98:99], v[84:87], off offset:512
	v_cvt_pk_bf16_f32 v88, v84, v85
	v_or_b32_e32 v90, 0x100, v102
	v_mul_f32_e32 v85, v85, v85
	v_mov_b32_e32 v91, v103
	v_fmac_f32_e32 v85, v84, v84
	v_mul_f32_e32 v84, v87, v87
	v_cvt_pk_bf16_f32 v89, v86, v87
	v_lshl_add_u64 v[90:91], s[40:41], 0, v[90:91]
	v_fmac_f32_e32 v84, v86, v86
	global_store_dwordx2 v[90:91], v[88:89], off
	v_add_f32_e32 v84, v85, v84
	v_add_f32_e32 v88, v92, v84
	s_nop 0
	v_or_b32_e32 v102, 0x108, v102
	s_nop 0
	v_pk_fma_f32 v[82:83], v[82:83], 0.5, v[214:215] op_sel_hi:[1,0,1]
	v_pk_fma_f32 v[80:81], v[80:81], 0.5, v[212:213] op_sel_hi:[1,0,1]
	v_mov_b32_e32 v230, 0x140000
	v_lshl_add_u64 v[228:229], v[232:233], 0, v[230:231]
	global_load_dwordx4 v[200:203], v[228:229], off
	global_load_dwordx4 v[204:207], v[228:229], off offset:16
	global_load_dwordx4 v[208:211], v[228:229], off offset:512
	global_load_dwordx4 v[212:215], v[228:229], off offset:528
	global_store_dwordx4 v[98:99], v[80:83], off offset:528
	v_cvt_pk_bf16_f32 v84, v80, v81
	v_cvt_pk_bf16_f32 v85, v82, v83
	v_mul_f32_e32 v81, v81, v81
	v_fmac_f32_e32 v81, v80, v80
	v_mul_f32_e32 v80, v83, v83
	v_fmac_f32_e32 v80, v82, v82
	v_add_f32_e32 v80, v81, v80
	v_add_f32_e32 v80, v88, v80
	v_mov_b32_e32 v81, v80
	s_nop 1
	v_permlane16_swap_b32 v80, v81
	v_lshl_add_u64 v[86:87], s[40:41], 0, v[102:103]
	v_add_f32_e32 v80, v80, v81
	v_mov_b32_e32 v81, v80
	global_store_dwordx2 v[86:87], v[84:85], off
	s_nop 1
	v_permlane32_swap_b32 v80, v81
	s_and_saveexec_b64 s[12:13], s[2:3]
	s_cbranch_execz .LBB0_429
	v_lshl_add_u64 v[82:83], v[96:97], 2, s[90:91]
	v_add_f32_e32 v80, v80, v81
	global_atomic_add_f32 v[82:83], v80, off
; __device__ __forceinline__ unsigned pk2(float lo, float hi) { f32x2_t v = {lo, hi}; bf16x2_t b = __builtin_convertvector(v, bf16x2_t); return __builtin_bit_cast(unsigned, b); }
; __device__ __forceinline__ float xor16_sum(float v) { float a = v, b = v; swap16(a, b); return a + b; }
; __device__ __forceinline__ float xor32_sum(float v) { float a = v, b = v; swap32(a, b); return a + b; }
;     __device__ __forceinline__ void operator()(const f32x4 (&acc)[2][2][4][2], const Unit& u, int wr, int wc, int fr, int fq) const {
;     ...
;         for (int ai = 0; ai < 2; ++ai)
; #pragma unroll
;             for (int m = 0; m < 4; ++m) {
;                 const int row = row0 + ai * HALF + m * 16; float sq = 0.f;
; #pragma unroll
;                 for (int bj = 0; bj < 2; ++bj)
; #pragma unroll
;                     for (int n = 0; n < 2; ++n) {
;                         const size_t idx = (size_t)row * ldc + u.pn * BM + bj * HALF + wc * 32 + 8 * fq + 4 * n;
;                         const f32x4 b = *(const f32x4*)(base + idx);
;                         const f32x4 v = b + acc[ai][bj][m][n] * alpha;
;                         *(f32x4*)(out + idx) = v;
;                         if (NORM) { u32x2 w; w.x = pk2(v[0], v[1]); w.y = pk2(v[2], v[3]); *(u32x2*)(xb + idx) = w; sq += (v[0] * v[0] + v[1] * v[1]) + (v[2] * v[2] + v[3] * v[3]); }
;                     }
;                 if (NORM) { sq = xor16_sum(sq); sq = xor32_sum(sq); if (fq == 0) __hip_atomic_fetch_add(ss + row, sq, __ATOMIC_RELAXED, __HIP_MEMORY_SCOPE_AGENT); }
.LBB0_429:
	s_or_b64 exec, exec, s[12:13]
	v_or_b32_e32 v80, 48, v148
	v_ashrrev_i32_e32 v81, 31, v80
	v_lshlrev_b64 v[82:83], 11, v[80:81]
	v_lshl_add_u64 v[86:87], v[82:83], 0, v[146:147]
	v_lshlrev_b64 v[88:89], 2, v[86:87]
	v_lshl_add_u64 v[90:91], s[52:53], 0, v[88:89]
	s_nop 0
	v_lshlrev_b64 v[86:87], 1, v[86:87]
	s_nop 0
	s_waitcnt vmcnt(36)
	v_pk_fma_f32 v[78:79], v[78:79], 0.5, v[218:219] op_sel_hi:[1,0,1]
	v_pk_fma_f32 v[76:77], v[76:77], 0.5, v[216:217] op_sel_hi:[1,0,1]
	v_lshl_add_u64 v[82:83], s[30:31], 0, v[88:89]
	global_store_dwordx4 v[82:83], v[76:79], off
	v_cvt_pk_bf16_f32 v84, v76, v77
	v_cvt_pk_bf16_f32 v85, v78, v79
	v_mul_f32_e32 v77, v77, v77
	v_lshl_add_u64 v[88:89], s[40:41], 0, v[86:87]
	v_fmac_f32_e32 v77, v76, v76
	v_mul_f32_e32 v76, v79, v79
	global_store_dwordx2 v[88:89], v[84:85], off
	v_fmac_f32_e32 v76, v78, v78
	v_add_f32_e32 v84, v77, v76
	s_nop 0
	s_nop 0
	v_pk_fma_f32 v[74:75], v[74:75], 0.5, v[222:223] op_sel_hi:[1,0,1]
	v_pk_fma_f32 v[72:73], v[72:73], 0.5, v[220:221] op_sel_hi:[1,0,1]
	global_store_dwordx4 v[82:83], v[72:75], off offset:16
	v_cvt_pk_bf16_f32 v76, v72, v73
	v_or_b32_e32 v78, 8, v86
	v_mul_f32_e32 v73, v73, v73
	v_mov_b32_e32 v79, v87
	v_fmac_f32_e32 v73, v72, v72
	v_mul_f32_e32 v72, v75, v75
	v_cvt_pk_bf16_f32 v77, v74, v75
	v_lshl_add_u64 v[78:79], s[40:41], 0, v[78:79]
	v_fmac_f32_e32 v72, v74, v74
	global_store_dwordx2 v[78:79], v[76:77], off
	v_add_f32_e32 v72, v73, v72
	v_add_f32_e32 v76, v84, v72
	s_nop 0
	s_nop 0
	v_pk_fma_f32 v[70:71], v[70:71], 0.5, v[226:227] op_sel_hi:[1,0,1]
	v_pk_fma_f32 v[68:69], v[68:69], 0.5, v[224:225] op_sel_hi:[1,0,1]
	global_store_dwordx4 v[82:83], v[68:71], off offset:512
	v_cvt_pk_bf16_f32 v72, v68, v69
	v_or_b32_e32 v74, 0x100, v86
	v_mul_f32_e32 v69, v69, v69
	v_mov_b32_e32 v75, v87
	v_fmac_f32_e32 v69, v68, v68
	v_mul_f32_e32 v68, v71, v71
	v_cvt_pk_bf16_f32 v73, v70, v71
	v_lshl_add_u64 v[74:75], s[40:41], 0, v[74:75]
	v_fmac_f32_e32 v68, v70, v70
	global_store_dwordx2 v[74:75], v[72:73], off
	v_add_f32_e32 v68, v69, v68
	v_add_f32_e32 v72, v76, v68
	s_nop 0
	v_or_b32_e32 v86, 0x108, v86
	s_nop 0
	v_pk_fma_f32 v[66:67], v[66:67], 0.5, v[236:237] op_sel_hi:[1,0,1]
	v_pk_fma_f32 v[64:65], v[64:65], 0.5, v[234:235] op_sel_hi:[1,0,1]
	v_mov_b32_e32 v230, 0x160000
	v_lshl_add_u64 v[228:229], v[232:233], 0, v[230:231]
	global_load_dwordx4 v[216:219], v[228:229], off
	global_load_dwordx4 v[220:223], v[228:229], off offset:16
	global_load_dwordx4 v[224:227], v[228:229], off offset:512
	global_load_dwordx4 v[234:237], v[228:229], off offset:528
	global_store_dwordx4 v[82:83], v[64:67], off offset:528
	v_cvt_pk_bf16_f32 v68, v64, v65
	v_cvt_pk_bf16_f32 v69, v66, v67
	v_mul_f32_e32 v65, v65, v65
	v_fmac_f32_e32 v65, v64, v64
	v_mul_f32_e32 v64, v67, v67
	v_fmac_f32_e32 v64, v66, v66
	v_add_f32_e32 v64, v65, v64
	v_add_f32_e32 v64, v72, v64
	v_mov_b32_e32 v65, v64
	s_nop 1
	v_permlane16_swap_b32 v64, v65
	v_lshl_add_u64 v[70:71], s[40:41], 0, v[86:87]
	v_add_f32_e32 v64, v64, v65
	v_mov_b32_e32 v65, v64
	global_store_dwordx2 v[70:71], v[68:69], off
	s_nop 1
	v_permlane32_swap_b32 v64, v65
	s_and_saveexec_b64 s[12:13], s[2:3]
	s_cbranch_execz .LBB0_431
	v_lshl_add_u64 v[66:67], v[80:81], 2, s[90:91]
	v_add_f32_e32 v64, v64, v65
	global_atomic_add_f32 v[66:67], v64, off
.LBB0_431:
	s_or_b64 exec, exec, s[12:13]
	v_add_u32_e32 v64, 0x80, v148
	v_ashrrev_i32_e32 v65, 31, v64
	v_lshlrev_b64 v[66:67], 11, v[64:65]
	v_lshl_add_u64 v[70:71], v[66:67], 0, v[146:147]
	v_lshlrev_b64 v[72:73], 2, v[70:71]
	v_lshl_add_u64 v[74:75], s[52:53], 0, v[72:73]
	s_nop 0
	v_lshlrev_b64 v[70:71], 1, v[70:71]
	s_nop 0
	s_waitcnt vmcnt(38)
	v_pk_fma_f32 v[62:63], v[62:63], 0.5, v[166:167] op_sel_hi:[1,0,1]
	v_pk_fma_f32 v[60:61], v[60:61], 0.5, v[164:165] op_sel_hi:[1,0,1]
	v_lshl_add_u64 v[66:67], s[30:31], 0, v[72:73]
	global_store_dwordx4 v[66:67], v[60:63], off
	v_cvt_pk_bf16_f32 v68, v60, v61
	v_cvt_pk_bf16_f32 v69, v62, v63
	v_mul_f32_e32 v61, v61, v61
	v_lshl_add_u64 v[72:73], s[40:41], 0, v[70:71]
	v_fmac_f32_e32 v61, v60, v60
	v_mul_f32_e32 v60, v63, v63
	global_store_dwordx2 v[72:73], v[68:69], off
	v_fmac_f32_e32 v60, v62, v62
	v_add_f32_e32 v68, v61, v60
	s_nop 0
	s_nop 0
	v_pk_fma_f32 v[58:59], v[58:59], 0.5, v[170:171] op_sel_hi:[1,0,1]
	v_pk_fma_f32 v[56:57], v[56:57], 0.5, v[168:169] op_sel_hi:[1,0,1]
	global_store_dwordx4 v[66:67], v[56:59], off offset:16
	v_cvt_pk_bf16_f32 v60, v56, v57
	v_or_b32_e32 v62, 8, v70
	v_mul_f32_e32 v57, v57, v57
	v_mov_b32_e32 v63, v71
	v_fmac_f32_e32 v57, v56, v56
	v_mul_f32_e32 v56, v59, v59
	v_cvt_pk_bf16_f32 v61, v58, v59
	v_lshl_add_u64 v[62:63], s[40:41], 0, v[62:63]
	v_fmac_f32_e32 v56, v58, v58
	global_store_dwordx2 v[62:63], v[60:61], off
	v_add_f32_e32 v56, v57, v56
	v_add_f32_e32 v60, v68, v56
	s_nop 0
	s_nop 0
	v_pk_fma_f32 v[54:55], v[54:55], 0.5, v[174:175] op_sel_hi:[1,0,1]
	v_pk_fma_f32 v[52:53], v[52:53], 0.5, v[172:173] op_sel_hi:[1,0,1]
	global_store_dwordx4 v[66:67], v[52:55], off offset:512
	v_cvt_pk_bf16_f32 v56, v52, v53
	v_or_b32_e32 v58, 0x100, v70
	v_mul_f32_e32 v53, v53, v53
	v_mov_b32_e32 v59, v71
	v_fmac_f32_e32 v53, v52, v52
	v_mul_f32_e32 v52, v55, v55
	v_cvt_pk_bf16_f32 v57, v54, v55
	v_lshl_add_u64 v[58:59], s[40:41], 0, v[58:59]
	v_fmac_f32_e32 v52, v54, v54
	global_store_dwordx2 v[58:59], v[56:57], off
	v_add_f32_e32 v52, v53, v52
	v_add_f32_e32 v56, v60, v52
	s_nop 0
	v_or_b32_e32 v70, 0x108, v70
	s_nop 0
	v_pk_fma_f32 v[50:51], v[50:51], 0.5, v[178:179] op_sel_hi:[1,0,1]
	v_pk_fma_f32 v[48:49], v[48:49], 0.5, v[176:177] op_sel_hi:[1,0,1]
	global_store_dwordx4 v[66:67], v[48:51], off offset:528
	v_cvt_pk_bf16_f32 v52, v48, v49
	v_cvt_pk_bf16_f32 v53, v50, v51
	v_mul_f32_e32 v49, v49, v49
	v_fmac_f32_e32 v49, v48, v48
	v_mul_f32_e32 v48, v51, v51
	v_fmac_f32_e32 v48, v50, v50
	v_add_f32_e32 v48, v49, v48
	v_add_f32_e32 v48, v56, v48
	v_mov_b32_e32 v49, v48
	s_nop 1
	v_permlane16_swap_b32 v49, v48
	v_lshl_add_u64 v[54:55], s[40:41], 0, v[70:71]
	v_add_f32_e32 v48, v49, v48
	v_mov_b32_e32 v49, v48
	global_store_dwordx2 v[54:55], v[52:53], off
	s_nop 1
	v_permlane32_swap_b32 v49, v48
	s_and_saveexec_b64 s[12:13], s[2:3]
	s_cbranch_execz .LBB0_433
	v_lshl_add_u64 v[50:51], v[64:65], 2, s[90:91]
	v_add_f32_e32 v48, v49, v48
	global_atomic_add_f32 v[50:51], v48, off
; __device__ __forceinline__ unsigned pk2(float lo, float hi) { f32x2_t v = {lo, hi}; bf16x2_t b = __builtin_convertvector(v, bf16x2_t); return __builtin_bit_cast(unsigned, b); }
; __device__ __forceinline__ float xor16_sum(float v) { float a = v, b = v; swap16(a, b); return a + b; }
; __device__ __forceinline__ float xor32_sum(float v) { float a = v, b = v; swap32(a, b); return a + b; }
;     __device__ __forceinline__ void operator()(const f32x4 (&acc)[2][2][4][2], const Unit& u, int wr, int wc, int fr, int fq) const {
;     ...
;         for (int ai = 0; ai < 2; ++ai)
; #pragma unroll
;             for (int m = 0; m < 4; ++m) {
;                 const int row = row0 + ai * HALF + m * 16; float sq = 0.f;
; #pragma unroll
;                 for (int bj = 0; bj < 2; ++bj)
; #pragma unroll
;                     for (int n = 0; n < 2; ++n) {
;                         const size_t idx = (size_t)row * ldc + u.pn * BM + bj * HALF + wc * 32 + 8 * fq + 4 * n;
;                         const f32x4 b = *(const f32x4*)(base + idx);
;                         const f32x4 v = b + acc[ai][bj][m][n] * alpha;
;                         *(f32x4*)(out + idx) = v;
;                         if (NORM) { u32x2 w; w.x = pk2(v[0], v[1]); w.y = pk2(v[2], v[3]); *(u32x2*)(xb + idx) = w; sq += (v[0] * v[0] + v[1] * v[1]) + (v[2] * v[2] + v[3] * v[3]); }
;                     }
;                 if (NORM) { sq = xor16_sum(sq); sq = xor32_sum(sq); if (fq == 0) __hip_atomic_fetch_add(ss + row, sq, __ATOMIC_RELAXED, __HIP_MEMORY_SCOPE_AGENT); }
.LBB0_433:
	s_or_b64 exec, exec, s[12:13]
	v_add_u32_e32 v48, 0x90, v148
	v_ashrrev_i32_e32 v49, 31, v48
	v_lshlrev_b64 v[50:51], 11, v[48:49]
	v_lshl_add_u64 v[54:55], v[50:51], 0, v[146:147]
	v_lshlrev_b64 v[56:57], 2, v[54:55]
	v_lshl_add_u64 v[58:59], s[52:53], 0, v[56:57]
	s_nop 0
	v_lshlrev_b64 v[54:55], 1, v[54:55]
	s_nop 0
	s_waitcnt vmcnt(34)
	v_pk_fma_f32 v[46:47], v[46:47], 0.5, v[182:183] op_sel_hi:[1,0,1]
	v_pk_fma_f32 v[44:45], v[44:45], 0.5, v[180:181] op_sel_hi:[1,0,1]
	v_lshl_add_u64 v[50:51], s[30:31], 0, v[56:57]
	global_store_dwordx4 v[50:51], v[44:47], off
	v_cvt_pk_bf16_f32 v52, v44, v45
	v_cvt_pk_bf16_f32 v53, v46, v47
	v_mul_f32_e32 v45, v45, v45
	v_lshl_add_u64 v[56:57], s[40:41], 0, v[54:55]
	v_fmac_f32_e32 v45, v44, v44
	v_mul_f32_e32 v44, v47, v47
	global_store_dwordx2 v[56:57], v[52:53], off
	v_fmac_f32_e32 v44, v46, v46
	v_add_f32_e32 v52, v45, v44
	s_nop 0
	s_nop 0
	v_pk_fma_f32 v[42:43], v[42:43], 0.5, v[190:191] op_sel_hi:[1,0,1]
	v_pk_fma_f32 v[40:41], v[40:41], 0.5, v[188:189] op_sel_hi:[1,0,1]
	global_store_dwordx4 v[50:51], v[40:43], off offset:16
	v_cvt_pk_bf16_f32 v44, v40, v41
	v_or_b32_e32 v46, 8, v54
	v_mul_f32_e32 v41, v41, v41
	v_mov_b32_e32 v47, v55
	v_fmac_f32_e32 v41, v40, v40
	v_mul_f32_e32 v40, v43, v43
	v_cvt_pk_bf16_f32 v45, v42, v43
	v_lshl_add_u64 v[46:47], s[40:41], 0, v[46:47]
	v_fmac_f32_e32 v40, v42, v42
	global_store_dwordx2 v[46:47], v[44:45], off
	v_add_f32_e32 v40, v41, v40
	v_add_f32_e32 v44, v52, v40
	s_nop 0
	s_nop 0
	v_pk_fma_f32 v[38:39], v[38:39], 0.5, v[194:195] op_sel_hi:[1,0,1]
	v_pk_fma_f32 v[36:37], v[36:37], 0.5, v[192:193] op_sel_hi:[1,0,1]
	global_store_dwordx4 v[50:51], v[36:39], off offset:512
	v_cvt_pk_bf16_f32 v40, v36, v37
	v_or_b32_e32 v42, 0x100, v54
	v_mul_f32_e32 v37, v37, v37
	v_mov_b32_e32 v43, v55
	v_fmac_f32_e32 v37, v36, v36
	v_mul_f32_e32 v36, v39, v39
	v_cvt_pk_bf16_f32 v41, v38, v39
	v_lshl_add_u64 v[42:43], s[40:41], 0, v[42:43]
	v_fmac_f32_e32 v36, v38, v38
	global_store_dwordx2 v[42:43], v[40:41], off
	v_add_f32_e32 v36, v37, v36
	v_add_f32_e32 v40, v44, v36
	s_nop 0
	v_or_b32_e32 v54, 0x108, v54
	s_nop 0
	v_pk_fma_f32 v[34:35], v[34:35], 0.5, v[198:199] op_sel_hi:[1,0,1]
	v_pk_fma_f32 v[32:33], v[32:33], 0.5, v[196:197] op_sel_hi:[1,0,1]
	global_store_dwordx4 v[50:51], v[32:35], off offset:528
	v_cvt_pk_bf16_f32 v36, v32, v33
	v_cvt_pk_bf16_f32 v37, v34, v35
	v_mul_f32_e32 v33, v33, v33
	v_fmac_f32_e32 v33, v32, v32
	v_mul_f32_e32 v32, v35, v35
	v_fmac_f32_e32 v32, v34, v34
	v_add_f32_e32 v32, v33, v32
	v_add_f32_e32 v32, v40, v32
	v_mov_b32_e32 v33, v32
	s_nop 1
	v_permlane16_swap_b32 v32, v33
	v_lshl_add_u64 v[38:39], s[40:41], 0, v[54:55]
	v_add_f32_e32 v32, v32, v33
	v_mov_b32_e32 v33, v32
	global_store_dwordx2 v[38:39], v[36:37], off
	s_nop 1
	v_permlane32_swap_b32 v32, v33
	s_and_saveexec_b64 s[12:13], s[2:3]
	s_cbranch_execz .LBB0_435
	v_lshl_add_u64 v[34:35], v[48:49], 2, s[90:91]
	v_add_f32_e32 v32, v32, v33
	global_atomic_add_f32 v[34:35], v32, off
; __device__ __forceinline__ unsigned pk2(float lo, float hi) { f32x2_t v = {lo, hi}; bf16x2_t b = __builtin_convertvector(v, bf16x2_t); return __builtin_bit_cast(unsigned, b); }
; __device__ __forceinline__ float xor16_sum(float v) { float a = v, b = v; swap16(a, b); return a + b; }
; __device__ __forceinline__ float xor32_sum(float v) { float a = v, b = v; swap32(a, b); return a + b; }
;     __device__ __forceinline__ void operator()(const f32x4 (&acc)[2][2][4][2], const Unit& u, int wr, int wc, int fr, int fq) const {
;     ...
;         for (int ai = 0; ai < 2; ++ai)
; #pragma unroll
;             for (int m = 0; m < 4; ++m) {
;                 const int row = row0 + ai * HALF + m * 16; float sq = 0.f;
; #pragma unroll
;                 for (int bj = 0; bj < 2; ++bj)
; #pragma unroll
;                     for (int n = 0; n < 2; ++n) {
;                         const size_t idx = (size_t)row * ldc + u.pn * BM + bj * HALF + wc * 32 + 8 * fq + 4 * n;
;                         const f32x4 b = *(const f32x4*)(base + idx);
;                         const f32x4 v = b + acc[ai][bj][m][n] * alpha;
;                         *(f32x4*)(out + idx) = v;
;                         if (NORM) { u32x2 w; w.x = pk2(v[0], v[1]); w.y = pk2(v[2], v[3]); *(u32x2*)(xb + idx) = w; sq += (v[0] * v[0] + v[1] * v[1]) + (v[2] * v[2] + v[3] * v[3]); }
;                     }
;                 if (NORM) { sq = xor16_sum(sq); sq = xor32_sum(sq); if (fq == 0) __hip_atomic_fetch_add(ss + row, sq, __ATOMIC_RELAXED, __HIP_MEMORY_SCOPE_AGENT); }
.LBB0_435:
	s_or_b64 exec, exec, s[12:13]
	v_add_u32_e32 v32, 0xa0, v148
	v_ashrrev_i32_e32 v33, 31, v32
	v_lshlrev_b64 v[34:35], 11, v[32:33]
	v_lshl_add_u64 v[38:39], v[34:35], 0, v[146:147]
	v_lshlrev_b64 v[40:41], 2, v[38:39]
	v_lshl_add_u64 v[42:43], s[52:53], 0, v[40:41]
	s_nop 0
	v_lshlrev_b64 v[38:39], 1, v[38:39]
	s_nop 0
	s_waitcnt vmcnt(30)
	v_pk_fma_f32 v[30:31], v[30:31], 0.5, v[202:203] op_sel_hi:[1,0,1]
	v_pk_fma_f32 v[28:29], v[28:29], 0.5, v[200:201] op_sel_hi:[1,0,1]
	v_lshl_add_u64 v[34:35], s[30:31], 0, v[40:41]
	global_store_dwordx4 v[34:35], v[28:31], off
	v_cvt_pk_bf16_f32 v36, v28, v29
	v_cvt_pk_bf16_f32 v37, v30, v31
	v_mul_f32_e32 v29, v29, v29
	v_lshl_add_u64 v[40:41], s[40:41], 0, v[38:39]
	v_fmac_f32_e32 v29, v28, v28
	v_mul_f32_e32 v28, v31, v31
	global_store_dwordx2 v[40:41], v[36:37], off
	v_fmac_f32_e32 v28, v30, v30
	v_add_f32_e32 v36, v29, v28
	s_nop 0
	s_nop 0
	v_pk_fma_f32 v[26:27], v[26:27], 0.5, v[206:207] op_sel_hi:[1,0,1]
	v_pk_fma_f32 v[24:25], v[24:25], 0.5, v[204:205] op_sel_hi:[1,0,1]
	global_store_dwordx4 v[34:35], v[24:27], off offset:16
	v_cvt_pk_bf16_f32 v28, v24, v25
	v_or_b32_e32 v30, 8, v38
	v_mul_f32_e32 v25, v25, v25
	v_mov_b32_e32 v31, v39
	v_fmac_f32_e32 v25, v24, v24
	v_mul_f32_e32 v24, v27, v27
	v_cvt_pk_bf16_f32 v29, v26, v27
	v_lshl_add_u64 v[30:31], s[40:41], 0, v[30:31]
	v_fmac_f32_e32 v24, v26, v26
	global_store_dwordx2 v[30:31], v[28:29], off
	v_add_f32_e32 v24, v25, v24
	v_add_f32_e32 v28, v36, v24
	s_nop 0
	s_nop 0
	v_pk_fma_f32 v[22:23], v[22:23], 0.5, v[210:211] op_sel_hi:[1,0,1]
	v_pk_fma_f32 v[20:21], v[20:21], 0.5, v[208:209] op_sel_hi:[1,0,1]
	global_store_dwordx4 v[34:35], v[20:23], off offset:512
	v_cvt_pk_bf16_f32 v24, v20, v21
	v_or_b32_e32 v26, 0x100, v38
	v_mul_f32_e32 v21, v21, v21
	v_mov_b32_e32 v27, v39
	v_fmac_f32_e32 v21, v20, v20
	v_mul_f32_e32 v20, v23, v23
	v_cvt_pk_bf16_f32 v25, v22, v23
	v_lshl_add_u64 v[26:27], s[40:41], 0, v[26:27]
	v_fmac_f32_e32 v20, v22, v22
	global_store_dwordx2 v[26:27], v[24:25], off
	v_add_f32_e32 v20, v21, v20
	v_add_f32_e32 v24, v28, v20
	s_nop 0
	v_or_b32_e32 v38, 0x108, v38
	s_nop 0
	v_pk_fma_f32 v[18:19], v[18:19], 0.5, v[214:215] op_sel_hi:[1,0,1]
	v_pk_fma_f32 v[16:17], v[16:17], 0.5, v[212:213] op_sel_hi:[1,0,1]
	global_store_dwordx4 v[34:35], v[16:19], off offset:528
	v_cvt_pk_bf16_f32 v20, v16, v17
	v_cvt_pk_bf16_f32 v21, v18, v19
	v_mul_f32_e32 v17, v17, v17
	v_fmac_f32_e32 v17, v16, v16
	v_mul_f32_e32 v16, v19, v19
	v_fmac_f32_e32 v16, v18, v18
	v_add_f32_e32 v16, v17, v16
	v_add_f32_e32 v16, v24, v16
	v_mov_b32_e32 v17, v16
	s_nop 1
	v_permlane16_swap_b32 v16, v17
	v_lshl_add_u64 v[22:23], s[40:41], 0, v[38:39]
	v_add_f32_e32 v16, v16, v17
	v_mov_b32_e32 v17, v16
	global_store_dwordx2 v[22:23], v[20:21], off
	s_nop 1
	v_permlane32_swap_b32 v16, v17
	s_and_saveexec_b64 s[12:13], s[2:3]
	s_cbranch_execz .LBB0_437
	v_lshl_add_u64 v[18:19], v[32:33], 2, s[90:91]
	v_add_f32_e32 v16, v16, v17
	global_atomic_add_f32 v[18:19], v16, off
.LBB0_437:
	s_or_b64 exec, exec, s[12:13]
	v_add_u32_e32 v16, 0xb0, v148
	v_ashrrev_i32_e32 v17, 31, v16
	v_lshlrev_b64 v[18:19], 11, v[16:17]
	v_lshl_add_u64 v[22:23], v[18:19], 0, v[146:147]
	v_lshlrev_b64 v[24:25], 2, v[22:23]
	v_lshl_add_u64 v[26:27], s[52:53], 0, v[24:25]
	s_nop 0
	v_lshlrev_b64 v[22:23], 1, v[22:23]
	s_nop 0
	s_waitcnt vmcnt(26)
	v_pk_fma_f32 v[14:15], v[14:15], 0.5, v[218:219] op_sel_hi:[1,0,1]
	v_pk_fma_f32 v[12:13], v[12:13], 0.5, v[216:217] op_sel_hi:[1,0,1]
	v_lshl_add_u64 v[18:19], s[30:31], 0, v[24:25]
	global_store_dwordx4 v[18:19], v[12:15], off
	v_cvt_pk_bf16_f32 v20, v12, v13
	v_cvt_pk_bf16_f32 v21, v14, v15
	v_mul_f32_e32 v13, v13, v13
	v_lshl_add_u64 v[24:25], s[40:41], 0, v[22:23]
	v_fmac_f32_e32 v13, v12, v12
	v_mul_f32_e32 v12, v15, v15
	global_store_dwordx2 v[24:25], v[20:21], off
	v_fmac_f32_e32 v12, v14, v14
	v_add_f32_e32 v20, v13, v12
	s_nop 0
	s_nop 0
	v_pk_fma_f32 v[10:11], v[10:11], 0.5, v[222:223] op_sel_hi:[1,0,1]
	v_pk_fma_f32 v[8:9], v[8:9], 0.5, v[220:221] op_sel_hi:[1,0,1]
	global_store_dwordx4 v[18:19], v[8:11], off offset:16
	v_cvt_pk_bf16_f32 v12, v8, v9
	v_or_b32_e32 v14, 8, v22
	v_mul_f32_e32 v9, v9, v9
	v_mov_b32_e32 v15, v23
	v_fmac_f32_e32 v9, v8, v8
	v_mul_f32_e32 v8, v11, v11
	v_cvt_pk_bf16_f32 v13, v10, v11
	v_lshl_add_u64 v[14:15], s[40:41], 0, v[14:15]
	v_fmac_f32_e32 v8, v10, v10
	global_store_dwordx2 v[14:15], v[12:13], off
	v_add_f32_e32 v8, v9, v8
	v_add_f32_e32 v12, v20, v8
	s_nop 0
	s_nop 0
	v_pk_fma_f32 v[6:7], v[6:7], 0.5, v[226:227] op_sel_hi:[1,0,1]
	v_pk_fma_f32 v[4:5], v[4:5], 0.5, v[224:225] op_sel_hi:[1,0,1]
	global_store_dwordx4 v[18:19], v[4:7], off offset:512
	v_cvt_pk_bf16_f32 v8, v4, v5
	v_or_b32_e32 v10, 0x100, v22
	v_mul_f32_e32 v5, v5, v5
	v_mov_b32_e32 v11, v23
	v_fmac_f32_e32 v5, v4, v4
	v_mul_f32_e32 v4, v7, v7
	v_cvt_pk_bf16_f32 v9, v6, v7
	v_lshl_add_u64 v[10:11], s[40:41], 0, v[10:11]
	v_fmac_f32_e32 v4, v6, v6
	global_store_dwordx2 v[10:11], v[8:9], off
	v_add_f32_e32 v4, v5, v4
	v_add_f32_e32 v8, v12, v4
	s_nop 0
	v_or_b32_e32 v22, 0x108, v22
	s_nop 0
	v_pk_fma_f32 v[2:3], v[2:3], 0.5, v[236:237] op_sel_hi:[1,0,1]
	v_pk_fma_f32 v[0:1], v[0:1], 0.5, v[234:235] op_sel_hi:[1,0,1]
	global_store_dwordx4 v[18:19], v[0:3], off offset:528
	v_cvt_pk_bf16_f32 v4, v0, v1
	v_cvt_pk_bf16_f32 v5, v2, v3
	v_mul_f32_e32 v1, v1, v1
	v_fmac_f32_e32 v1, v0, v0
	v_mul_f32_e32 v0, v3, v3
	v_fmac_f32_e32 v0, v2, v2
	v_add_f32_e32 v0, v1, v0
	v_add_f32_e32 v0, v8, v0
	v_mov_b32_e32 v1, v0
	s_nop 1
	v_permlane16_swap_b32 v0, v1
	v_lshl_add_u64 v[6:7], s[40:41], 0, v[22:23]
	v_add_f32_e32 v0, v0, v1
	v_mov_b32_e32 v1, v0
	global_store_dwordx2 v[6:7], v[4:5], off
	s_nop 1
	v_permlane32_swap_b32 v0, v1
	s_and_saveexec_b64 s[12:13], s[2:3]
	s_cbranch_execz .LBB0_439
	v_lshl_add_u64 v[2:3], v[16:17], 2, s[90:91]
	v_add_f32_e32 v0, v0, v1
	global_atomic_add_f32 v[2:3], v0, off

; __device__ __forceinline__ unsigned pk2(float lo, float hi) { f32x2_t v = {lo, hi}; bf16x2_t b = __builtin_convertvector(v, bf16x2_t); return __builtin_bit_cast(unsigned, b); }
;     __device__ __forceinline__ void operator()(const f32x4 (&acc)[2][2][4][2], const Unit& u, int wr, int wc, int fr, int fq) const {
;     ...
;         for (int bj = 0; bj < 2; ++bj) {
;             const int c = u.pn * BM + bj * HALF + wc * 32 + 8 * fq; const int dc = remap ? (c >> 7) * 192 + (c & 127) : c;
;             f32x4 cs0 = (f32x4){1.f, 1.f, 1.f, 1.f}, cs1 = cs0;
;             if (smode == 2) { const f32x4 t0 = *(const f32x4*)(ss + c), t1 = *(const f32x4*)(ss + c + 4);
; #pragma unroll
;                 for (int e = 0; e < 4; ++e) { cs0[e] = rsqrtf(t0[e] * (1.f / 2048.f) + EPS); cs1[e] = rsqrtf(t1[e] * (1.f / 2048.f) + EPS); } }
; #pragma unroll
;             for (int ai = 0; ai < 2; ++ai)
; #pragma unroll
;                 for (int m = 0; m < 4; ++m) {
;                     const int row = row0 + ai * HALF + m * 16;
;                     const float rs = (smode == 1) ? rsqrtf(ss[row] * (1.f / 2048.f) + EPS) : 1.f;
;                     const f32x4 v0 = acc[ai][bj][m][0] * cs0 * rs, v1 = acc[ai][bj][m][1] * cs1 * rs; u32x4 w;
;                     w.x = pk2(v0[0], v0[1]); w.y = pk2(v0[2], v0[3]); w.z = pk2(v1[0], v1[1]); w.w = pk2(v1[2], v1[3]);
;                     size_t off = (size_t)row * ldc + dc;
;                     if (remap == 3) {
;                         const int b_ = c >> 11, ch_ = (c >> 6) & 31, s_ = (c >> 5) & 1, fq_ = (c >> 3) & 3, h_ = row >> 8, vs_ = (row >> 5) & 7, n_ = (row >> 4) & 1, fr_ = row & 15;
;                         off = ((((size_t)((b_ * 4 + h_) * 8 + vs_) * 32 + ch_) * 4 + n_ * 2 + s_) * 64 + fq_ * 16 + fr_) * 8; }
;                     *(u32x4*)(O + off) = w;
.LBB0_510:
	v_lshl_add_u32 v146, s12, 8, v155
	v_ashrrev_i32_e32 v147, 31, v146
	v_lshl_add_u64 v[144:145], v[146:147], 2, s[90:91]
	global_load_dword v230, v[144:145], off
	global_load_dword v231, v[144:145], off offset:64
	global_load_dword v232, v[144:145], off offset:128
	global_load_dword v233, v[144:145], off offset:192
	global_load_dword v234, v[144:145], off offset:512
	global_load_dword v235, v[144:145], off offset:576
	global_load_dword v236, v[144:145], off offset:640
	global_load_dword v237, v[144:145], off offset:704
	s_nop 0
	v_lshl_or_b32 v168, s13, 8, v157
	v_readlane_b32 s12, v238, 55
	v_readlane_b32 s13, v238, 56
	v_ashrrev_i32_e32 v169, 31, v168
	s_waitcnt vmcnt(7)
	v_fmamk_f32 v147, v230, 0x3a000000, v163
	v_cmp_gt_f32_e32 vcc, s74, v147
	v_mul_f32_e32 v164, 0x4b800000, v147
	s_nop 0
	v_cndmask_b32_e32 v147, v147, v164, vcc
	v_rsq_f32_e32 v147, v147
	s_nop 0
	v_mul_f32_e32 v164, 0x45800000, v147
	v_cndmask_b32_e32 v164, v147, v164, vcc
	v_pk_mul_f32 v[124:125], v[124:125], v[164:165] op_sel_hi:[1,0]
	v_pk_mul_f32 v[126:127], v[126:127], v[164:165] op_sel_hi:[1,0]
	v_pk_mul_f32 v[122:123], v[122:123], v[164:165] op_sel_hi:[1,0]
	v_pk_mul_f32 v[120:121], v[120:121], v[164:165] op_sel_hi:[1,0]
	v_cvt_pk_bf16_f32 v164, v124, v125
	v_mov_b64_e32 v[124:125], s[12:13]
	v_cvt_pk_bf16_f32 v165, v126, v127
	v_cvt_pk_bf16_f32 v166, v120, v121
	v_mad_i64_i32 v[120:121], s[12:13], v146, s75, v[124:125]
	v_lshlrev_b64 v[126:127], 1, v[168:169]
	v_cvt_pk_bf16_f32 v167, v122, v123
	v_lshl_add_u64 v[120:121], v[120:121], 0, v[126:127]
	global_store_dwordx4 v[120:121], v[164:167], off
	s_nop 1
	v_or_b32_e32 v164, 16, v146
	v_ashrrev_i32_e32 v165, 31, v164
	v_lshl_add_u64 v[122:123], v[164:165], 2, s[90:91]
	s_nop 0
	s_waitcnt vmcnt(7)
	v_fmamk_f32 v147, v231, 0x3a000000, v163
	v_cmp_gt_f32_e32 vcc, s74, v147
	v_mul_f32_e32 v165, 0x4b800000, v147
	s_nop 0
	v_cndmask_b32_e32 v147, v147, v165, vcc
	v_rsq_f32_e32 v147, v147
	s_nop 0
	v_mul_f32_e32 v165, 0x45800000, v147
	v_cndmask_b32_e32 v166, v147, v165, vcc
	v_pk_mul_f32 v[116:117], v[116:117], v[166:167] op_sel_hi:[1,0]
	v_pk_mul_f32 v[112:113], v[112:113], v[166:167] op_sel_hi:[1,0]
	v_pk_mul_f32 v[118:119], v[118:119], v[166:167] op_sel_hi:[1,0]
	v_pk_mul_f32 v[168:169], v[114:115], v[166:167] op_sel_hi:[1,0]
	v_cvt_pk_bf16_f32 v114, v116, v117
	v_cvt_pk_bf16_f32 v116, v112, v113
	v_mad_i64_i32 v[112:113], s[12:13], v164, s75, v[124:125]
	v_cvt_pk_bf16_f32 v115, v118, v119
	v_cvt_pk_bf16_f32 v117, v168, v169
	v_lshl_add_u64 v[112:113], v[112:113], 0, v[126:127]
	global_store_dwordx4 v[112:113], v[114:117], off
	s_nop 1
	v_or_b32_e32 v116, 32, v146
	v_ashrrev_i32_e32 v117, 31, v116
	v_lshl_add_u64 v[114:115], v[116:117], 2, s[90:91]
	s_nop 0
	s_waitcnt vmcnt(7)
	v_fmamk_f32 v117, v232, 0x3a000000, v163
	v_cmp_gt_f32_e32 vcc, s74, v117
	v_mul_f32_e32 v118, 0x4b800000, v117
	s_nop 0
	v_cndmask_b32_e32 v117, v117, v118, vcc
	v_rsq_f32_e32 v117, v117
	s_nop 0
	v_mul_f32_e32 v118, 0x45800000, v117
	v_cndmask_b32_e32 v118, v117, v118, vcc
	v_pk_mul_f32 v[108:109], v[108:109], v[118:119] op_sel_hi:[1,0]
	v_pk_mul_f32 v[104:105], v[104:105], v[118:119] op_sel_hi:[1,0]
	v_pk_mul_f32 v[110:111], v[110:111], v[118:119] op_sel_hi:[1,0]
	v_pk_mul_f32 v[164:165], v[106:107], v[118:119] op_sel_hi:[1,0]
	v_cvt_pk_bf16_f32 v106, v108, v109
	v_cvt_pk_bf16_f32 v108, v104, v105
	v_mad_i64_i32 v[104:105], s[12:13], v116, s75, v[124:125]
	v_cvt_pk_bf16_f32 v107, v110, v111
	v_cvt_pk_bf16_f32 v109, v164, v165
	v_lshl_add_u64 v[104:105], v[104:105], 0, v[126:127]
	global_store_dwordx4 v[104:105], v[106:109], off
	s_nop 1
	v_or_b32_e32 v108, 48, v146
	v_ashrrev_i32_e32 v109, 31, v108
	v_lshl_add_u64 v[106:107], v[108:109], 2, s[90:91]
	s_nop 0
	s_waitcnt vmcnt(7)
	v_fmamk_f32 v109, v233, 0x3a000000, v163
	v_cmp_gt_f32_e32 vcc, s74, v109
	v_mul_f32_e32 v110, 0x4b800000, v109
	s_nop 0
	v_cndmask_b32_e32 v109, v109, v110, vcc
	v_rsq_f32_e32 v109, v109
	s_nop 0
	v_mul_f32_e32 v110, 0x45800000, v109
	v_cndmask_b32_e32 v110, v109, v110, vcc
	v_pk_mul_f32 v[100:101], v[100:101], v[110:111] op_sel_hi:[1,0]
	v_pk_mul_f32 v[96:97], v[96:97], v[110:111] op_sel_hi:[1,0]
	v_pk_mul_f32 v[102:103], v[102:103], v[110:111] op_sel_hi:[1,0]
	v_pk_mul_f32 v[116:117], v[98:99], v[110:111] op_sel_hi:[1,0]
	v_cvt_pk_bf16_f32 v98, v100, v101
	v_cvt_pk_bf16_f32 v100, v96, v97
	v_mad_i64_i32 v[96:97], s[12:13], v108, s75, v[124:125]
	v_cvt_pk_bf16_f32 v99, v102, v103
	v_cvt_pk_bf16_f32 v101, v116, v117
	v_lshl_add_u64 v[96:97], v[96:97], 0, v[126:127]
	global_store_dwordx4 v[96:97], v[98:101], off
	s_nop 0
	s_nop 0
	v_add_u32_e32 v99, 0x80, v146
	s_waitcnt vmcnt(7)
	v_fmamk_f32 v98, v234, 0x3a000000, v163
	v_cmp_gt_f32_e32 vcc, s74, v98
	v_mul_f32_e32 v100, 0x4b800000, v98
	s_nop 0
	v_cndmask_b32_e32 v98, v98, v100, vcc
	v_rsq_f32_e32 v98, v98
	s_nop 0
	v_mul_f32_e32 v100, 0x45800000, v98
	v_cndmask_b32_e32 v98, v98, v100, vcc
	v_pk_mul_f32 v[92:93], v[92:93], v[98:99] op_sel_hi:[1,0]
	v_pk_mul_f32 v[88:89], v[88:89], v[98:99] op_sel_hi:[1,0]
	v_pk_mul_f32 v[94:95], v[94:95], v[98:99] op_sel_hi:[1,0]
	v_pk_mul_f32 v[100:101], v[90:91], v[98:99] op_sel_hi:[1,0]
	v_cvt_pk_bf16_f32 v90, v92, v93
	v_cvt_pk_bf16_f32 v92, v88, v89
	v_mad_i64_i32 v[88:89], s[12:13], v99, s75, v[124:125]
	v_cvt_pk_bf16_f32 v91, v94, v95
	v_cvt_pk_bf16_f32 v93, v100, v101
	v_lshl_add_u64 v[88:89], v[88:89], 0, v[126:127]
	global_store_dwordx4 v[88:89], v[90:93], off
	s_nop 0
	s_nop 0
	v_add_u32_e32 v91, 0x90, v146
	s_waitcnt vmcnt(7)
; __device__ __forceinline__ unsigned pk2(float lo, float hi) { f32x2_t v = {lo, hi}; bf16x2_t b = __builtin_convertvector(v, bf16x2_t); return __builtin_bit_cast(unsigned, b); }
;     __device__ __forceinline__ void operator()(const f32x4 (&acc)[2][2][4][2], const Unit& u, int wr, int wc, int fr, int fq) const {
;     ...
;         for (int bj = 0; bj < 2; ++bj) {
;             const int c = u.pn * BM + bj * HALF + wc * 32 + 8 * fq; const int dc = remap ? (c >> 7) * 192 + (c & 127) : c;
;             f32x4 cs0 = (f32x4){1.f, 1.f, 1.f, 1.f}, cs1 = cs0;
;             if (smode == 2) { const f32x4 t0 = *(const f32x4*)(ss + c), t1 = *(const f32x4*)(ss + c + 4);
; #pragma unroll
;                 for (int e = 0; e < 4; ++e) { cs0[e] = rsqrtf(t0[e] * (1.f / 2048.f) + EPS); cs1[e] = rsqrtf(t1[e] * (1.f / 2048.f) + EPS); } }
; #pragma unroll
;             for (int ai = 0; ai < 2; ++ai)
; #pragma unroll
;                 for (int m = 0; m < 4; ++m) {
;                     const int row = row0 + ai * HALF + m * 16;
;                     const float rs = (smode == 1) ? rsqrtf(ss[row] * (1.f / 2048.f) + EPS) : 1.f;
;                     const f32x4 v0 = acc[ai][bj][m][0] * cs0 * rs, v1 = acc[ai][bj][m][1] * cs1 * rs; u32x4 w;
;                     w.x = pk2(v0[0], v0[1]); w.y = pk2(v0[2], v0[3]); w.z = pk2(v1[0], v1[1]); w.w = pk2(v1[2], v1[3]);
;                     size_t off = (size_t)row * ldc + dc;
;                     if (remap == 3) {
;                         const int b_ = c >> 11, ch_ = (c >> 6) & 31, s_ = (c >> 5) & 1, fq_ = (c >> 3) & 3, h_ = row >> 8, vs_ = (row >> 5) & 7, n_ = (row >> 4) & 1, fr_ = row & 15;
;                         off = ((((size_t)((b_ * 4 + h_) * 8 + vs_) * 32 + ch_) * 4 + n_ * 2 + s_) * 64 + fq_ * 16 + fr_) * 8; }
;                     *(u32x4*)(O + off) = w;
	v_fmamk_f32 v90, v235, 0x3a000000, v163
	v_cmp_gt_f32_e32 vcc, s74, v90
	v_mul_f32_e32 v92, 0x4b800000, v90
	s_nop 0
	v_cndmask_b32_e32 v90, v90, v92, vcc
	v_rsq_f32_e32 v90, v90
	s_nop 0
	v_mul_f32_e32 v92, 0x45800000, v90
	v_cndmask_b32_e32 v90, v90, v92, vcc
	v_pk_mul_f32 v[84:85], v[84:85], v[90:91] op_sel_hi:[1,0]
	v_pk_mul_f32 v[80:81], v[80:81], v[90:91] op_sel_hi:[1,0]
	v_pk_mul_f32 v[86:87], v[86:87], v[90:91] op_sel_hi:[1,0]
	v_pk_mul_f32 v[92:93], v[82:83], v[90:91] op_sel_hi:[1,0]
	v_cvt_pk_bf16_f32 v82, v84, v85
	v_cvt_pk_bf16_f32 v84, v80, v81
	v_mad_i64_i32 v[80:81], s[12:13], v91, s75, v[124:125]
	v_cvt_pk_bf16_f32 v83, v86, v87
	v_cvt_pk_bf16_f32 v85, v92, v93
	v_lshl_add_u64 v[80:81], v[80:81], 0, v[126:127]
	global_store_dwordx4 v[80:81], v[82:85], off
	s_nop 0
	s_nop 0
	v_add_u32_e32 v83, 0xa0, v146
	s_waitcnt vmcnt(7)
	v_fmamk_f32 v82, v236, 0x3a000000, v163
	v_cmp_gt_f32_e32 vcc, s74, v82
	v_mul_f32_e32 v84, 0x4b800000, v82
	s_nop 0
	v_cndmask_b32_e32 v82, v82, v84, vcc
	v_rsq_f32_e32 v82, v82
	s_nop 0
	v_mul_f32_e32 v84, 0x45800000, v82
	v_cndmask_b32_e32 v82, v82, v84, vcc
	v_pk_mul_f32 v[76:77], v[76:77], v[82:83] op_sel_hi:[1,0]
	v_pk_mul_f32 v[72:73], v[72:73], v[82:83] op_sel_hi:[1,0]
	v_pk_mul_f32 v[78:79], v[78:79], v[82:83] op_sel_hi:[1,0]
	v_pk_mul_f32 v[84:85], v[74:75], v[82:83] op_sel_hi:[1,0]
	v_cvt_pk_bf16_f32 v74, v76, v77
	v_cvt_pk_bf16_f32 v76, v72, v73
	v_mad_i64_i32 v[72:73], s[12:13], v83, s75, v[124:125]
	v_cvt_pk_bf16_f32 v75, v78, v79
	v_cvt_pk_bf16_f32 v77, v84, v85
	v_lshl_add_u64 v[72:73], v[72:73], 0, v[126:127]
	global_store_dwordx4 v[72:73], v[74:77], off
	s_nop 0
	s_nop 0
	v_add_u32_e32 v75, 0xb0, v146
	s_waitcnt vmcnt(7)
; __device__ __forceinline__ unsigned pk2(float lo, float hi) { f32x2_t v = {lo, hi}; bf16x2_t b = __builtin_convertvector(v, bf16x2_t); return __builtin_bit_cast(unsigned, b); }
;     __device__ __forceinline__ void operator()(const f32x4 (&acc)[2][2][4][2], const Unit& u, int wr, int wc, int fr, int fq) const {
;     ...
;         for (int bj = 0; bj < 2; ++bj) {
;             const int c = u.pn * BM + bj * HALF + wc * 32 + 8 * fq; const int dc = remap ? (c >> 7) * 192 + (c & 127) : c;
;             f32x4 cs0 = (f32x4){1.f, 1.f, 1.f, 1.f}, cs1 = cs0;
;             if (smode == 2) { const f32x4 t0 = *(const f32x4*)(ss + c), t1 = *(const f32x4*)(ss + c + 4);
; #pragma unroll
;                 for (int e = 0; e < 4; ++e) { cs0[e] = rsqrtf(t0[e] * (1.f / 2048.f) + EPS); cs1[e] = rsqrtf(t1[e] * (1.f / 2048.f) + EPS); } }
; #pragma unroll
;             for (int ai = 0; ai < 2; ++ai)
; #pragma unroll
;                 for (int m = 0; m < 4; ++m) {
;                     const int row = row0 + ai * HALF + m * 16;
;                     const float rs = (smode == 1) ? rsqrtf(ss[row] * (1.f / 2048.f) + EPS) : 1.f;
;                     const f32x4 v0 = acc[ai][bj][m][0] * cs0 * rs, v1 = acc[ai][bj][m][1] * cs1 * rs; u32x4 w;
;                     w.x = pk2(v0[0], v0[1]); w.y = pk2(v0[2], v0[3]); w.z = pk2(v1[0], v1[1]); w.w = pk2(v1[2], v1[3]);
;                     size_t off = (size_t)row * ldc + dc;
;                     if (remap == 3) {
;                         const int b_ = c >> 11, ch_ = (c >> 6) & 31, s_ = (c >> 5) & 1, fq_ = (c >> 3) & 3, h_ = row >> 8, vs_ = (row >> 5) & 7, n_ = (row >> 4) & 1, fr_ = row & 15;
;                         off = ((((size_t)((b_ * 4 + h_) * 8 + vs_) * 32 + ch_) * 4 + n_ * 2 + s_) * 64 + fq_ * 16 + fr_) * 8; }
;                     *(u32x4*)(O + off) = w;
	v_fmamk_f32 v74, v237, 0x3a000000, v163
	v_cmp_gt_f32_e32 vcc, s74, v74
	v_mul_f32_e32 v76, 0x4b800000, v74
	s_nop 0
	v_cndmask_b32_e32 v74, v74, v76, vcc
	v_rsq_f32_e32 v74, v74
	s_nop 0
	v_mul_f32_e32 v76, 0x45800000, v74
	v_cndmask_b32_e32 v74, v74, v76, vcc
	v_pk_mul_f32 v[68:69], v[68:69], v[74:75] op_sel_hi:[1,0]
	v_pk_mul_f32 v[64:65], v[64:65], v[74:75] op_sel_hi:[1,0]
	v_pk_mul_f32 v[70:71], v[70:71], v[74:75] op_sel_hi:[1,0]
	v_pk_mul_f32 v[76:77], v[66:67], v[74:75] op_sel_hi:[1,0]
	v_cvt_pk_bf16_f32 v66, v68, v69
	v_cvt_pk_bf16_f32 v68, v64, v65
	v_mad_i64_i32 v[64:65], s[12:13], v75, s75, v[124:125]
	v_cvt_pk_bf16_f32 v67, v70, v71
	v_cvt_pk_bf16_f32 v69, v76, v77
	v_lshl_add_u64 v[64:65], v[64:65], 0, v[126:127]
	global_store_dwordx4 v[64:65], v[66:69], off
	s_nop 0
	s_mov_b64 s[12:13], -1
	s_nop 0
	v_fmamk_f32 v66, v230, 0x3a000000, v163
	v_cmp_gt_f32_e32 vcc, s74, v66
	v_mul_f32_e32 v67, 0x4b800000, v66
	s_nop 0
	v_cndmask_b32_e32 v66, v66, v67, vcc
	v_rsq_f32_e32 v66, v66
	s_nop 0
	v_mul_f32_e32 v67, 0x45800000, v66
	v_cndmask_b32_e32 v66, v66, v67, vcc
	v_pk_mul_f32 v[62:63], v[62:63], v[66:67] op_sel_hi:[1,0]
	v_pk_mul_f32 v[60:61], v[60:61], v[66:67] op_sel_hi:[1,0]
	v_pk_mul_f32 v[68:69], v[58:59], v[66:67] op_sel_hi:[1,0]
	v_pk_mul_f32 v[58:59], v[56:57], v[66:67] op_sel_hi:[1,0]
	v_cvt_pk_bf16_f32 v56, v60, v61
	v_cvt_pk_bf16_f32 v57, v62, v63
	v_cvt_pk_bf16_f32 v58, v58, v59
	v_cvt_pk_bf16_f32 v59, v68, v69
	global_store_dwordx4 v[120:121], v[56:59], off offset:256
	s_nop 0
	s_nop 0
	v_fmamk_f32 v56, v231, 0x3a000000, v163
	v_cmp_gt_f32_e32 vcc, s74, v56
	v_mul_f32_e32 v57, 0x4b800000, v56
	s_nop 0
	v_cndmask_b32_e32 v56, v56, v57, vcc
	v_rsq_f32_e32 v56, v56
	s_nop 0
	v_mul_f32_e32 v57, 0x45800000, v56
	v_cndmask_b32_e32 v56, v56, v57, vcc
	v_pk_mul_f32 v[54:55], v[54:55], v[56:57] op_sel_hi:[1,0]
	v_pk_mul_f32 v[52:53], v[52:53], v[56:57] op_sel_hi:[1,0]
	v_pk_mul_f32 v[58:59], v[50:51], v[56:57] op_sel_hi:[1,0]
	v_pk_mul_f32 v[50:51], v[48:49], v[56:57] op_sel_hi:[1,0]
	v_cvt_pk_bf16_f32 v48, v52, v53
	v_cvt_pk_bf16_f32 v49, v54, v55
	v_cvt_pk_bf16_f32 v50, v50, v51
	v_cvt_pk_bf16_f32 v51, v58, v59
	global_store_dwordx4 v[112:113], v[48:51], off offset:256
	s_nop 0
	s_nop 0
	v_fmamk_f32 v48, v232, 0x3a000000, v163
	v_cmp_gt_f32_e32 vcc, s74, v48
	v_mul_f32_e32 v49, 0x4b800000, v48
	s_nop 0
	v_cndmask_b32_e32 v48, v48, v49, vcc
	v_rsq_f32_e32 v48, v48
	s_nop 0
	v_mul_f32_e32 v49, 0x45800000, v48
	v_cndmask_b32_e32 v48, v48, v49, vcc
	v_pk_mul_f32 v[46:47], v[46:47], v[48:49] op_sel_hi:[1,0]
	v_pk_mul_f32 v[44:45], v[44:45], v[48:49] op_sel_hi:[1,0]
	v_pk_mul_f32 v[50:51], v[42:43], v[48:49] op_sel_hi:[1,0]
	v_pk_mul_f32 v[42:43], v[40:41], v[48:49] op_sel_hi:[1,0]
	v_cvt_pk_bf16_f32 v40, v44, v45
	v_cvt_pk_bf16_f32 v41, v46, v47
	v_cvt_pk_bf16_f32 v42, v42, v43
	v_cvt_pk_bf16_f32 v43, v50, v51
	global_store_dwordx4 v[104:105], v[40:43], off offset:256
	s_nop 0
	s_nop 0
	v_fmamk_f32 v40, v233, 0x3a000000, v163
	v_cmp_gt_f32_e32 vcc, s74, v40
	v_mul_f32_e32 v41, 0x4b800000, v40
	s_nop 0
	v_cndmask_b32_e32 v40, v40, v41, vcc
	v_rsq_f32_e32 v40, v40
	s_nop 0
	v_mul_f32_e32 v41, 0x45800000, v40
	v_cndmask_b32_e32 v40, v40, v41, vcc
	v_pk_mul_f32 v[38:39], v[38:39], v[40:41] op_sel_hi:[1,0]
	v_pk_mul_f32 v[36:37], v[36:37], v[40:41] op_sel_hi:[1,0]
	v_pk_mul_f32 v[42:43], v[34:35], v[40:41] op_sel_hi:[1,0]
	v_pk_mul_f32 v[34:35], v[32:33], v[40:41] op_sel_hi:[1,0]
	v_cvt_pk_bf16_f32 v32, v36, v37
	v_cvt_pk_bf16_f32 v33, v38, v39
	v_cvt_pk_bf16_f32 v34, v34, v35
	v_cvt_pk_bf16_f32 v35, v42, v43
	global_store_dwordx4 v[96:97], v[32:35], off offset:256
	s_nop 0
	s_nop 0
	v_fmamk_f32 v32, v234, 0x3a000000, v163
	v_cmp_gt_f32_e32 vcc, s74, v32
	v_mul_f32_e32 v33, 0x4b800000, v32
	s_nop 0
	v_cndmask_b32_e32 v32, v32, v33, vcc
	v_rsq_f32_e32 v32, v32
	s_nop 0
	v_mul_f32_e32 v33, 0x45800000, v32
	v_cndmask_b32_e32 v32, v32, v33, vcc
	v_pk_mul_f32 v[30:31], v[30:31], v[32:33] op_sel_hi:[1,0]
	v_pk_mul_f32 v[28:29], v[28:29], v[32:33] op_sel_hi:[1,0]
	v_pk_mul_f32 v[34:35], v[26:27], v[32:33] op_sel_hi:[1,0]
	v_pk_mul_f32 v[26:27], v[24:25], v[32:33] op_sel_hi:[1,0]
	v_cvt_pk_bf16_f32 v24, v28, v29
	v_cvt_pk_bf16_f32 v25, v30, v31
	v_cvt_pk_bf16_f32 v26, v26, v27
	v_cvt_pk_bf16_f32 v27, v34, v35
	global_store_dwordx4 v[88:89], v[24:27], off offset:256
	s_nop 0
	s_nop 0
	v_fmamk_f32 v24, v235, 0x3a000000, v163
	v_cmp_gt_f32_e32 vcc, s74, v24
	v_mul_f32_e32 v25, 0x4b800000, v24
	s_nop 0
	v_cndmask_b32_e32 v24, v24, v25, vcc
	v_rsq_f32_e32 v24, v24
	s_nop 0
	v_mul_f32_e32 v25, 0x45800000, v24
	v_cndmask_b32_e32 v24, v24, v25, vcc
	v_pk_mul_f32 v[22:23], v[22:23], v[24:25] op_sel_hi:[1,0]
	v_pk_mul_f32 v[20:21], v[20:21], v[24:25] op_sel_hi:[1,0]
	v_pk_mul_f32 v[26:27], v[18:19], v[24:25] op_sel_hi:[1,0]
	v_pk_mul_f32 v[18:19], v[16:17], v[24:25] op_sel_hi:[1,0]
	v_cvt_pk_bf16_f32 v16, v20, v21
	v_cvt_pk_bf16_f32 v17, v22, v23
	v_cvt_pk_bf16_f32 v18, v18, v19
	v_cvt_pk_bf16_f32 v19, v26, v27
	global_store_dwordx4 v[80:81], v[16:19], off offset:256
	s_nop 0
	s_nop 0
	v_fmamk_f32 v16, v236, 0x3a000000, v163
	v_cmp_gt_f32_e32 vcc, s74, v16
	v_mul_f32_e32 v17, 0x4b800000, v16
	s_nop 0
	v_cndmask_b32_e32 v16, v16, v17, vcc
	v_rsq_f32_e32 v16, v16
	s_nop 0
	v_mul_f32_e32 v17, 0x45800000, v16
	v_cndmask_b32_e32 v16, v16, v17, vcc
	v_pk_mul_f32 v[14:15], v[14:15], v[16:17] op_sel_hi:[1,0]
	v_pk_mul_f32 v[12:13], v[12:13], v[16:17] op_sel_hi:[1,0]
	v_pk_mul_f32 v[18:19], v[10:11], v[16:17] op_sel_hi:[1,0]
	v_pk_mul_f32 v[10:11], v[8:9], v[16:17] op_sel_hi:[1,0]
	v_cvt_pk_bf16_f32 v8, v12, v13
	v_cvt_pk_bf16_f32 v9, v14, v15
	v_cvt_pk_bf16_f32 v10, v10, v11
	v_cvt_pk_bf16_f32 v11, v18, v19
	global_store_dwordx4 v[72:73], v[8:11], off offset:256
	s_nop 0
	s_nop 0
	v_fmamk_f32 v8, v237, 0x3a000000, v163
	v_cmp_gt_f32_e32 vcc, s74, v8
	v_mul_f32_e32 v9, 0x4b800000, v8
	s_nop 0
	v_cndmask_b32_e32 v8, v8, v9, vcc
	v_rsq_f32_e32 v8, v8
	s_nop 0
	v_mul_f32_e32 v9, 0x45800000, v8
	v_cndmask_b32_e32 v8, v8, v9, vcc
	v_pk_mul_f32 v[6:7], v[6:7], v[8:9] op_sel_hi:[1,0]
	v_pk_mul_f32 v[4:5], v[4:5], v[8:9] op_sel_hi:[1,0]
	v_pk_mul_f32 v[2:3], v[2:3], v[8:9] op_sel_hi:[1,0]
	v_pk_mul_f32 v[0:1], v[0:1], v[8:9] op_sel_hi:[1,0]
	v_cvt_pk_bf16_f32 v4, v4, v5
	v_cvt_pk_bf16_f32 v5, v6, v7
	v_cvt_pk_bf16_f32 v6, v0, v1
	v_cvt_pk_bf16_f32 v7, v2, v3
	s_andn2_b64 vcc, exec, s[2:3]
	global_store_dwordx4 v[64:65], v[4:7], off offset:256
	s_cbranch_vccnz .LBB0_503
	s_andn2_b64 vcc, exec, s[0:1]
	s_cbranch_vccnz .LBB0_502
	s_barrier
	s_branch .LBB0_502

; __device__ __forceinline__ unsigned pk2(float lo, float hi) { f32x2_t v = {lo, hi}; bf16x2_t b = __builtin_convertvector(v, bf16x2_t); return __builtin_bit_cast(unsigned, b); }
; __device__ __forceinline__ float xor16_sum(float v) { float a = v, b = v; swap16(a, b); return a + b; }
; __device__ __forceinline__ float xor32_sum(float v) { float a = v, b = v; swap32(a, b); return a + b; }
;     __device__ __forceinline__ void operator()(const f32x4 (&acc)[2][2][4][2], const Unit& u, int wr, int wc, int fr, int fq) const {
;     ...
;         for (int ai = 0; ai < 2; ++ai)
; #pragma unroll
;             for (int m = 0; m < 4; ++m) {
;                 const int row = row0 + ai * HALF + m * 16; float sq = 0.f;
; #pragma unroll
;                 for (int bj = 0; bj < 2; ++bj)
; #pragma unroll
;                     for (int n = 0; n < 2; ++n) {
;                         const size_t idx = (size_t)row * ldc + u.pn * BM + bj * HALF + wc * 32 + 8 * fq + 4 * n;
;                         const f32x4 b = *(const f32x4*)(base + idx);
;                         const f32x4 v = b + acc[ai][bj][m][n] * alpha;
;                         *(f32x4*)(out + idx) = v;
;                         if (NORM) { u32x2 w; w.x = pk2(v[0], v[1]); w.y = pk2(v[2], v[3]); *(u32x2*)(xb + idx) = w; sq += (v[0] * v[0] + v[1] * v[1]) + (v[2] * v[2] + v[3] * v[3]); }
;                     }
;                 if (NORM) { sq = xor16_sum(sq); sq = xor32_sum(sq); if (fq == 0) __hip_atomic_fetch_add(ss + row, sq, __ATOMIC_RELAXED, __HIP_MEMORY_SCOPE_AGENT); }
.LBB0_1208:
	v_lshl_add_u32 v148, s12, 8, v137
	s_lshl_b32 s12, s44, 8
	s_ashr_i32 s13, s12, 31
	v_ashrrev_i32_e32 v149, 31, v148
	v_mov_b32_e32 v147, s13
	v_or_b32_e32 v146, s12, v136
	v_lshlrev_b64 v[154:155], 11, v[148:149]
	v_lshl_add_u64 v[158:159], v[154:155], 0, v[146:147]
	v_lshl_add_u64 v[160:161], v[158:159], 2, s[30:31]
	v_mov_b32_e32 v232, v160
	v_mov_b32_e32 v233, v161
	v_mov_b32_e32 v231, 0
	v_mov_b32_e32 v230, 0x0
	v_lshl_add_u64 v[228:229], v[232:233], 0, v[230:231]
	global_load_dwordx4 v[164:167], v[228:229], off
	global_load_dwordx4 v[168:171], v[228:229], off offset:16
	global_load_dwordx4 v[172:175], v[228:229], off offset:512
	global_load_dwordx4 v[176:179], v[228:229], off offset:528
	v_mov_b32_e32 v230, 0x20000
	v_lshl_add_u64 v[228:229], v[232:233], 0, v[230:231]
	global_load_dwordx4 v[180:183], v[228:229], off
	global_load_dwordx4 v[188:191], v[228:229], off offset:16
	global_load_dwordx4 v[192:195], v[228:229], off offset:512
	global_load_dwordx4 v[196:199], v[228:229], off offset:528
	v_mov_b32_e32 v230, 0x40000
	v_lshl_add_u64 v[228:229], v[232:233], 0, v[230:231]
	global_load_dwordx4 v[200:203], v[228:229], off
	global_load_dwordx4 v[204:207], v[228:229], off offset:16
	global_load_dwordx4 v[208:211], v[228:229], off offset:512
	global_load_dwordx4 v[212:215], v[228:229], off offset:528
	v_mov_b32_e32 v230, 0x60000
	v_lshl_add_u64 v[228:229], v[232:233], 0, v[230:231]
	global_load_dwordx4 v[216:219], v[228:229], off
	global_load_dwordx4 v[220:223], v[228:229], off offset:16
	global_load_dwordx4 v[224:227], v[228:229], off offset:512
	global_load_dwordx4 v[234:237], v[228:229], off offset:528
	s_nop 0
	v_lshlrev_b64 v[158:159], 1, v[158:159]
	v_lshl_add_u64 v[162:163], s[6:7], 0, v[158:159]
	s_nop 0
	s_waitcnt vmcnt(12)
	v_pk_add_f32 v[126:127], v[126:127], v[166:167]
	v_pk_add_f32 v[124:125], v[124:125], v[164:165]
	v_cvt_pk_bf16_f32 v155, v126, v127
	v_cvt_pk_bf16_f32 v154, v124, v125
	global_store_dwordx4 v[160:161], v[124:127], off
	global_store_dwordx2 v[162:163], v[154:155], off
	s_nop 0
	v_or_b32_e32 v162, 8, v158
	v_mov_b32_e32 v163, v159
	v_lshl_add_u64 v[162:163], s[6:7], 0, v[162:163]
	v_mul_f32_e32 v125, v125, v125
	v_mul_f32_e32 v127, v127, v127
	v_fmac_f32_e32 v125, v124, v124
	v_fmac_f32_e32 v127, v126, v126
	v_add_f32_e32 v124, v125, v127
	s_nop 0
	v_pk_add_f32 v[122:123], v[122:123], v[170:171]
	v_pk_add_f32 v[120:121], v[120:121], v[168:169]
	v_cvt_pk_bf16_f32 v155, v122, v123
	v_cvt_pk_bf16_f32 v154, v120, v121
	global_store_dwordx4 v[160:161], v[120:123], off offset:16
	global_store_dwordx2 v[162:163], v[154:155], off
	s_nop 0
	v_or_b32_e32 v162, 0x100, v158
	v_mov_b32_e32 v163, v159
	v_lshl_add_u64 v[162:163], s[6:7], 0, v[162:163]
	v_mul_f32_e32 v121, v121, v121
	v_mul_f32_e32 v123, v123, v123
	v_fmac_f32_e32 v121, v120, v120
	v_fmac_f32_e32 v123, v122, v122
	v_add_f32_e32 v120, v121, v123
	v_add_f32_e32 v120, v124, v120
	v_or_b32_e32 v158, 0x108, v158
	v_lshl_add_u64 v[158:159], s[6:7], 0, v[158:159]
	s_nop 0
	v_pk_add_f32 v[118:119], v[118:119], v[174:175]
	v_pk_add_f32 v[116:117], v[116:117], v[172:173]
	v_cvt_pk_bf16_f32 v155, v118, v119
	v_cvt_pk_bf16_f32 v154, v116, v117
	global_store_dwordx4 v[160:161], v[116:119], off offset:512
	global_store_dwordx2 v[162:163], v[154:155], off
	s_nop 0
	v_mul_f32_e32 v117, v117, v117
	v_mul_f32_e32 v119, v119, v119
	v_fmac_f32_e32 v117, v116, v116
	v_fmac_f32_e32 v119, v118, v118
	v_add_f32_e32 v116, v117, v119
	v_add_f32_e32 v118, v120, v116
	s_nop 0
	v_pk_add_f32 v[114:115], v[114:115], v[178:179]
	v_pk_add_f32 v[112:113], v[112:113], v[176:177]
	v_mov_b32_e32 v230, 0x100000
	v_lshl_add_u64 v[228:229], v[232:233], 0, v[230:231]
	global_load_dwordx4 v[164:167], v[228:229], off
	global_load_dwordx4 v[168:171], v[228:229], off offset:16
	global_load_dwordx4 v[172:175], v[228:229], off offset:512
	global_load_dwordx4 v[176:179], v[228:229], off offset:528
	global_store_dwordx4 v[160:161], v[112:115], off offset:528
	v_cvt_pk_bf16_f32 v116, v112, v113
	v_cvt_pk_bf16_f32 v117, v114, v115
	v_mul_f32_e32 v113, v113, v113
	v_mul_f32_e32 v115, v115, v115
	v_fmac_f32_e32 v113, v112, v112
	v_fmac_f32_e32 v115, v114, v114
	v_add_f32_e32 v112, v113, v115
	v_add_f32_e32 v112, v118, v112
	v_mov_b32_e32 v113, v112
	s_nop 1
	v_permlane16_swap_b32 v113, v112
	global_store_dwordx2 v[158:159], v[116:117], off
	v_add_f32_e32 v112, v113, v112
	v_mov_b32_e32 v113, v112
	s_nop 1
	v_permlane32_swap_b32 v113, v112
	s_and_saveexec_b64 s[12:13], s[2:3]
	s_cbranch_execz .LBB0_1210
	v_lshl_add_u64 v[114:115], v[148:149], 2, s[8:9]
	v_add_f32_e32 v112, v113, v112
	global_atomic_add_f32 v[114:115], v112, off
; __device__ __forceinline__ unsigned pk2(float lo, float hi) { f32x2_t v = {lo, hi}; bf16x2_t b = __builtin_convertvector(v, bf16x2_t); return __builtin_bit_cast(unsigned, b); }
; __device__ __forceinline__ float xor16_sum(float v) { float a = v, b = v; swap16(a, b); return a + b; }
; __device__ __forceinline__ float xor32_sum(float v) { float a = v, b = v; swap32(a, b); return a + b; }
;     __device__ __forceinline__ void operator()(const f32x4 (&acc)[2][2][4][2], const Unit& u, int wr, int wc, int fr, int fq) const {
;     ...
;         for (int ai = 0; ai < 2; ++ai)
; #pragma unroll
;             for (int m = 0; m < 4; ++m) {
;                 const int row = row0 + ai * HALF + m * 16; float sq = 0.f;
; #pragma unroll
;                 for (int bj = 0; bj < 2; ++bj)
; #pragma unroll
;                     for (int n = 0; n < 2; ++n) {
;                         const size_t idx = (size_t)row * ldc + u.pn * BM + bj * HALF + wc * 32 + 8 * fq + 4 * n;
;                         const f32x4 b = *(const f32x4*)(base + idx);
;                         const f32x4 v = b + acc[ai][bj][m][n] * alpha;
;                         *(f32x4*)(out + idx) = v;
;                         if (NORM) { u32x2 w; w.x = pk2(v[0], v[1]); w.y = pk2(v[2], v[3]); *(u32x2*)(xb + idx) = w; sq += (v[0] * v[0] + v[1] * v[1]) + (v[2] * v[2] + v[3] * v[3]); }
;                     }
;                 if (NORM) { sq = xor16_sum(sq); sq = xor32_sum(sq); if (fq == 0) __hip_atomic_fetch_add(ss + row, sq, __ATOMIC_RELAXED, __HIP_MEMORY_SCOPE_AGENT); }
.LBB0_1210:
	s_or_b64 exec, exec, s[12:13]
	v_or_b32_e32 v112, 16, v148
	v_ashrrev_i32_e32 v113, 31, v112
	v_lshlrev_b64 v[114:115], 11, v[112:113]
	v_lshl_add_u64 v[118:119], v[114:115], 0, v[146:147]
	v_lshl_add_u64 v[120:121], v[118:119], 2, s[30:31]
	s_nop 0
	v_lshlrev_b64 v[118:119], 1, v[118:119]
	v_lshl_add_u64 v[122:123], s[6:7], 0, v[118:119]
	s_nop 0
	s_waitcnt vmcnt(20)
	v_pk_add_f32 v[110:111], v[110:111], v[182:183]
	v_pk_add_f32 v[108:109], v[108:109], v[180:181]
	v_cvt_pk_bf16_f32 v115, v110, v111
	v_cvt_pk_bf16_f32 v114, v108, v109
	global_store_dwordx4 v[120:121], v[108:111], off
	global_store_dwordx2 v[122:123], v[114:115], off
	s_nop 0
	v_or_b32_e32 v122, 8, v118
	v_mov_b32_e32 v123, v119
	v_lshl_add_u64 v[122:123], s[6:7], 0, v[122:123]
	v_mul_f32_e32 v109, v109, v109
	v_mul_f32_e32 v111, v111, v111
	v_fmac_f32_e32 v109, v108, v108
	v_fmac_f32_e32 v111, v110, v110
	v_add_f32_e32 v108, v109, v111
	s_nop 0
	v_pk_add_f32 v[106:107], v[106:107], v[190:191]
	v_pk_add_f32 v[104:105], v[104:105], v[188:189]
	v_cvt_pk_bf16_f32 v115, v106, v107
	v_cvt_pk_bf16_f32 v114, v104, v105
	global_store_dwordx4 v[120:121], v[104:107], off offset:16
	global_store_dwordx2 v[122:123], v[114:115], off
	s_nop 0
	v_or_b32_e32 v122, 0x100, v118
	v_mov_b32_e32 v123, v119
	v_lshl_add_u64 v[122:123], s[6:7], 0, v[122:123]
	v_mul_f32_e32 v105, v105, v105
	v_mul_f32_e32 v107, v107, v107
	v_fmac_f32_e32 v105, v104, v104
	v_fmac_f32_e32 v107, v106, v106
	v_add_f32_e32 v104, v105, v107
	v_add_f32_e32 v104, v108, v104
	v_or_b32_e32 v118, 0x108, v118
	v_lshl_add_u64 v[118:119], s[6:7], 0, v[118:119]
	s_nop 0
	v_pk_add_f32 v[102:103], v[102:103], v[194:195]
	v_pk_add_f32 v[100:101], v[100:101], v[192:193]
	v_cvt_pk_bf16_f32 v115, v102, v103
	v_cvt_pk_bf16_f32 v114, v100, v101
	global_store_dwordx4 v[120:121], v[100:103], off offset:512
	global_store_dwordx2 v[122:123], v[114:115], off
	s_nop 0
	v_mul_f32_e32 v101, v101, v101
	v_mul_f32_e32 v103, v103, v103
	v_fmac_f32_e32 v101, v100, v100
	v_fmac_f32_e32 v103, v102, v102
	v_add_f32_e32 v100, v101, v103
	v_add_f32_e32 v102, v104, v100
	s_nop 0
	v_pk_add_f32 v[98:99], v[98:99], v[198:199]
	v_pk_add_f32 v[96:97], v[96:97], v[196:197]
	v_mov_b32_e32 v230, 0x120000
	v_lshl_add_u64 v[228:229], v[232:233], 0, v[230:231]
	global_load_dwordx4 v[180:183], v[228:229], off
	global_load_dwordx4 v[188:191], v[228:229], off offset:16
	global_load_dwordx4 v[192:195], v[228:229], off offset:512
	global_load_dwordx4 v[196:199], v[228:229], off offset:528
	global_store_dwordx4 v[120:121], v[96:99], off offset:528
	v_cvt_pk_bf16_f32 v100, v96, v97
	v_cvt_pk_bf16_f32 v101, v98, v99
	v_mul_f32_e32 v97, v97, v97
	v_mul_f32_e32 v99, v99, v99
	v_fmac_f32_e32 v97, v96, v96
	v_fmac_f32_e32 v99, v98, v98
	v_add_f32_e32 v96, v97, v99
	v_add_f32_e32 v96, v102, v96
	v_mov_b32_e32 v97, v96
	s_nop 1
	v_permlane16_swap_b32 v96, v97
	global_store_dwordx2 v[118:119], v[100:101], off
	v_add_f32_e32 v96, v96, v97
	v_mov_b32_e32 v97, v96
	s_nop 1
	v_permlane32_swap_b32 v96, v97
	s_and_saveexec_b64 s[12:13], s[2:3]
	s_cbranch_execz .LBB0_1212
	v_lshl_add_u64 v[98:99], v[112:113], 2, s[8:9]
	v_add_f32_e32 v96, v96, v97
	global_atomic_add_f32 v[98:99], v96, off
.LBB0_1212:
	s_or_b64 exec, exec, s[12:13]
	v_or_b32_e32 v96, 32, v148
	v_ashrrev_i32_e32 v97, 31, v96
	v_lshlrev_b64 v[98:99], 11, v[96:97]
	v_lshl_add_u64 v[102:103], v[98:99], 0, v[146:147]
	v_lshl_add_u64 v[104:105], v[102:103], 2, s[30:31]
	s_nop 0
	v_lshlrev_b64 v[102:103], 1, v[102:103]
	v_lshl_add_u64 v[106:107], s[6:7], 0, v[102:103]
	s_nop 0
	s_waitcnt vmcnt(28)
	v_pk_add_f32 v[94:95], v[94:95], v[202:203]
	v_pk_add_f32 v[92:93], v[92:93], v[200:201]
	v_cvt_pk_bf16_f32 v99, v94, v95
	v_cvt_pk_bf16_f32 v98, v92, v93
	global_store_dwordx4 v[104:105], v[92:95], off
	global_store_dwordx2 v[106:107], v[98:99], off
	s_nop 0
	v_or_b32_e32 v106, 8, v102
	v_mov_b32_e32 v107, v103
	v_lshl_add_u64 v[106:107], s[6:7], 0, v[106:107]
	v_mul_f32_e32 v93, v93, v93
	v_mul_f32_e32 v95, v95, v95
	v_fmac_f32_e32 v93, v92, v92
	v_fmac_f32_e32 v95, v94, v94
	v_add_f32_e32 v92, v93, v95
	s_nop 0
	v_pk_add_f32 v[90:91], v[90:91], v[206:207]
	v_pk_add_f32 v[88:89], v[88:89], v[204:205]
	v_cvt_pk_bf16_f32 v99, v90, v91
	v_cvt_pk_bf16_f32 v98, v88, v89
	global_store_dwordx4 v[104:105], v[88:91], off offset:16
	global_store_dwordx2 v[106:107], v[98:99], off
	s_nop 0
	v_or_b32_e32 v106, 0x100, v102
	v_mov_b32_e32 v107, v103
	v_lshl_add_u64 v[106:107], s[6:7], 0, v[106:107]
	v_mul_f32_e32 v89, v89, v89
	v_mul_f32_e32 v91, v91, v91
	v_fmac_f32_e32 v89, v88, v88
	v_fmac_f32_e32 v91, v90, v90
	v_add_f32_e32 v88, v89, v91
	v_add_f32_e32 v88, v92, v88
	v_or_b32_e32 v102, 0x108, v102
	v_lshl_add_u64 v[102:103], s[6:7], 0, v[102:103]
	s_nop 0
	v_pk_add_f32 v[86:87], v[86:87], v[210:211]
	v_pk_add_f32 v[84:85], v[84:85], v[208:209]
	v_cvt_pk_bf16_f32 v99, v86, v87
	v_cvt_pk_bf16_f32 v98, v84, v85
	global_store_dwordx4 v[104:105], v[84:87], off offset:512
	global_store_dwordx2 v[106:107], v[98:99], off
	s_nop 0
	v_mul_f32_e32 v85, v85, v85
	v_mul_f32_e32 v87, v87, v87
	v_fmac_f32_e32 v85, v84, v84
	v_fmac_f32_e32 v87, v86, v86
	v_add_f32_e32 v84, v85, v87
	v_add_f32_e32 v86, v88, v84
	s_nop 0
	v_pk_add_f32 v[82:83], v[82:83], v[214:215]
	v_pk_add_f32 v[80:81], v[80:81], v[212:213]
	v_mov_b32_e32 v230, 0x140000
	v_lshl_add_u64 v[228:229], v[232:233], 0, v[230:231]
	global_load_dwordx4 v[200:203], v[228:229], off
	global_load_dwordx4 v[204:207], v[228:229], off offset:16
	global_load_dwordx4 v[208:211], v[228:229], off offset:512
	global_load_dwordx4 v[212:215], v[228:229], off offset:528
	global_store_dwordx4 v[104:105], v[80:83], off offset:528
	v_cvt_pk_bf16_f32 v84, v80, v81
	v_cvt_pk_bf16_f32 v85, v82, v83
	v_mul_f32_e32 v81, v81, v81
	v_mul_f32_e32 v83, v83, v83
	v_fmac_f32_e32 v81, v80, v80
	v_fmac_f32_e32 v83, v82, v82
	v_add_f32_e32 v80, v81, v83
	v_add_f32_e32 v80, v86, v80
	v_mov_b32_e32 v81, v80
	s_nop 1
	v_permlane16_swap_b32 v80, v81
	global_store_dwordx2 v[102:103], v[84:85], off
	v_add_f32_e32 v80, v80, v81
	v_mov_b32_e32 v81, v80
	s_nop 1
	v_permlane32_swap_b32 v80, v81
	s_and_saveexec_b64 s[12:13], s[2:3]
	s_cbranch_execz .LBB0_1214
	v_lshl_add_u64 v[82:83], v[96:97], 2, s[8:9]
	v_add_f32_e32 v80, v80, v81
	global_atomic_add_f32 v[82:83], v80, off
; __device__ __forceinline__ unsigned pk2(float lo, float hi) { f32x2_t v = {lo, hi}; bf16x2_t b = __builtin_convertvector(v, bf16x2_t); return __builtin_bit_cast(unsigned, b); }
; __device__ __forceinline__ float xor16_sum(float v) { float a = v, b = v; swap16(a, b); return a + b; }
; __device__ __forceinline__ float xor32_sum(float v) { float a = v, b = v; swap32(a, b); return a + b; }
;     __device__ __forceinline__ void operator()(const f32x4 (&acc)[2][2][4][2], const Unit& u, int wr, int wc, int fr, int fq) const {
;     ...
;         for (int ai = 0; ai < 2; ++ai)
; #pragma unroll
;             for (int m = 0; m < 4; ++m) {
;                 const int row = row0 + ai * HALF + m * 16; float sq = 0.f;
; #pragma unroll
;                 for (int bj = 0; bj < 2; ++bj)
; #pragma unroll
;                     for (int n = 0; n < 2; ++n) {
;                         const size_t idx = (size_t)row * ldc + u.pn * BM + bj * HALF + wc * 32 + 8 * fq + 4 * n;
;                         const f32x4 b = *(const f32x4*)(base + idx);
;                         const f32x4 v = b + acc[ai][bj][m][n] * alpha;
;                         *(f32x4*)(out + idx) = v;
;                         if (NORM) { u32x2 w; w.x = pk2(v[0], v[1]); w.y = pk2(v[2], v[3]); *(u32x2*)(xb + idx) = w; sq += (v[0] * v[0] + v[1] * v[1]) + (v[2] * v[2] + v[3] * v[3]); }
;                     }
;                 if (NORM) { sq = xor16_sum(sq); sq = xor32_sum(sq); if (fq == 0) __hip_atomic_fetch_add(ss + row, sq, __ATOMIC_RELAXED, __HIP_MEMORY_SCOPE_AGENT); }
.LBB0_1214:
	s_or_b64 exec, exec, s[12:13]
	v_or_b32_e32 v80, 48, v148
	v_ashrrev_i32_e32 v81, 31, v80
	v_lshlrev_b64 v[82:83], 11, v[80:81]
	v_lshl_add_u64 v[86:87], v[82:83], 0, v[146:147]
	v_lshl_add_u64 v[88:89], v[86:87], 2, s[30:31]
	s_nop 0
	v_lshlrev_b64 v[86:87], 1, v[86:87]
	v_lshl_add_u64 v[90:91], s[6:7], 0, v[86:87]
	s_nop 0
	s_waitcnt vmcnt(36)
	v_pk_add_f32 v[78:79], v[78:79], v[218:219]
	v_pk_add_f32 v[76:77], v[76:77], v[216:217]
	v_cvt_pk_bf16_f32 v83, v78, v79
	v_cvt_pk_bf16_f32 v82, v76, v77
	global_store_dwordx4 v[88:89], v[76:79], off
	global_store_dwordx2 v[90:91], v[82:83], off
	s_nop 0
	v_or_b32_e32 v90, 8, v86
	v_mov_b32_e32 v91, v87
	v_lshl_add_u64 v[90:91], s[6:7], 0, v[90:91]
	v_mul_f32_e32 v77, v77, v77
	v_mul_f32_e32 v79, v79, v79
	v_fmac_f32_e32 v77, v76, v76
	v_fmac_f32_e32 v79, v78, v78
	v_add_f32_e32 v76, v77, v79
	s_nop 0
	v_pk_add_f32 v[74:75], v[74:75], v[222:223]
	v_pk_add_f32 v[72:73], v[72:73], v[220:221]
	v_cvt_pk_bf16_f32 v83, v74, v75
	v_cvt_pk_bf16_f32 v82, v72, v73
	global_store_dwordx4 v[88:89], v[72:75], off offset:16
	global_store_dwordx2 v[90:91], v[82:83], off
	s_nop 0
	v_or_b32_e32 v90, 0x100, v86
	v_mov_b32_e32 v91, v87
	v_lshl_add_u64 v[90:91], s[6:7], 0, v[90:91]
	v_mul_f32_e32 v73, v73, v73
	v_mul_f32_e32 v75, v75, v75
	v_fmac_f32_e32 v73, v72, v72
	v_fmac_f32_e32 v75, v74, v74
	v_add_f32_e32 v72, v73, v75
	v_add_f32_e32 v72, v76, v72
	v_or_b32_e32 v86, 0x108, v86
	v_lshl_add_u64 v[86:87], s[6:7], 0, v[86:87]
	s_nop 0
	v_pk_add_f32 v[70:71], v[70:71], v[226:227]
	v_pk_add_f32 v[68:69], v[68:69], v[224:225]
	v_cvt_pk_bf16_f32 v83, v70, v71
	v_cvt_pk_bf16_f32 v82, v68, v69
	global_store_dwordx4 v[88:89], v[68:71], off offset:512
	global_store_dwordx2 v[90:91], v[82:83], off
	s_nop 0
	v_mul_f32_e32 v69, v69, v69
	v_mul_f32_e32 v71, v71, v71
	v_fmac_f32_e32 v69, v68, v68
	v_fmac_f32_e32 v71, v70, v70
	v_add_f32_e32 v68, v69, v71
	v_add_f32_e32 v70, v72, v68
	s_nop 0
	v_pk_add_f32 v[66:67], v[66:67], v[236:237]
	v_pk_add_f32 v[64:65], v[64:65], v[234:235]
	v_mov_b32_e32 v230, 0x160000
	v_lshl_add_u64 v[228:229], v[232:233], 0, v[230:231]
	global_load_dwordx4 v[216:219], v[228:229], off
	global_load_dwordx4 v[220:223], v[228:229], off offset:16
	global_load_dwordx4 v[224:227], v[228:229], off offset:512
	global_load_dwordx4 v[234:237], v[228:229], off offset:528
	global_store_dwordx4 v[88:89], v[64:67], off offset:528
	v_cvt_pk_bf16_f32 v68, v64, v65
	v_cvt_pk_bf16_f32 v69, v66, v67
	v_mul_f32_e32 v65, v65, v65
	v_mul_f32_e32 v67, v67, v67
	v_fmac_f32_e32 v65, v64, v64
	v_fmac_f32_e32 v67, v66, v66
	v_add_f32_e32 v64, v65, v67
	v_add_f32_e32 v64, v70, v64
	v_mov_b32_e32 v65, v64
	s_nop 1
	v_permlane16_swap_b32 v64, v65
	global_store_dwordx2 v[86:87], v[68:69], off
	v_add_f32_e32 v64, v64, v65
	v_mov_b32_e32 v65, v64
	s_nop 1
	v_permlane32_swap_b32 v64, v65
	s_and_saveexec_b64 s[12:13], s[2:3]
	s_cbranch_execz .LBB0_1216
	v_lshl_add_u64 v[66:67], v[80:81], 2, s[8:9]
	v_add_f32_e32 v64, v64, v65
	global_atomic_add_f32 v[66:67], v64, off
.LBB0_1216:
	s_or_b64 exec, exec, s[12:13]
	v_add_u32_e32 v64, 0x80, v148
	v_ashrrev_i32_e32 v65, 31, v64
	v_lshlrev_b64 v[66:67], 11, v[64:65]
	v_lshl_add_u64 v[70:71], v[66:67], 0, v[146:147]
	v_lshl_add_u64 v[72:73], v[70:71], 2, s[30:31]
	s_nop 0
	v_lshlrev_b64 v[70:71], 1, v[70:71]
	v_lshl_add_u64 v[74:75], s[6:7], 0, v[70:71]
	s_nop 0
	s_waitcnt vmcnt(38)
	v_pk_add_f32 v[62:63], v[62:63], v[166:167]
	v_pk_add_f32 v[60:61], v[60:61], v[164:165]
	v_cvt_pk_bf16_f32 v67, v62, v63
	v_cvt_pk_bf16_f32 v66, v60, v61
	global_store_dwordx4 v[72:73], v[60:63], off
	global_store_dwordx2 v[74:75], v[66:67], off
	s_nop 0
	v_or_b32_e32 v74, 8, v70
	v_mov_b32_e32 v75, v71
	v_lshl_add_u64 v[74:75], s[6:7], 0, v[74:75]
	v_mul_f32_e32 v61, v61, v61
	v_mul_f32_e32 v63, v63, v63
	v_fmac_f32_e32 v61, v60, v60
	v_fmac_f32_e32 v63, v62, v62
	v_add_f32_e32 v60, v61, v63
	s_nop 0
	v_pk_add_f32 v[58:59], v[58:59], v[170:171]
	v_pk_add_f32 v[56:57], v[56:57], v[168:169]
	v_cvt_pk_bf16_f32 v67, v58, v59
	v_cvt_pk_bf16_f32 v66, v56, v57
	global_store_dwordx4 v[72:73], v[56:59], off offset:16
	global_store_dwordx2 v[74:75], v[66:67], off
	s_nop 0
	v_or_b32_e32 v74, 0x100, v70
	v_mov_b32_e32 v75, v71
	v_lshl_add_u64 v[74:75], s[6:7], 0, v[74:75]
	v_mul_f32_e32 v57, v57, v57
	v_mul_f32_e32 v59, v59, v59
	v_fmac_f32_e32 v57, v56, v56
	v_fmac_f32_e32 v59, v58, v58
	v_add_f32_e32 v56, v57, v59
	v_add_f32_e32 v56, v60, v56
	v_or_b32_e32 v70, 0x108, v70
	v_lshl_add_u64 v[70:71], s[6:7], 0, v[70:71]
	s_nop 0
	v_pk_add_f32 v[54:55], v[54:55], v[174:175]
	v_pk_add_f32 v[52:53], v[52:53], v[172:173]
	v_cvt_pk_bf16_f32 v67, v54, v55
	v_cvt_pk_bf16_f32 v66, v52, v53
	global_store_dwordx4 v[72:73], v[52:55], off offset:512
	global_store_dwordx2 v[74:75], v[66:67], off
	s_nop 0
	v_mul_f32_e32 v53, v53, v53
	v_mul_f32_e32 v55, v55, v55
	v_fmac_f32_e32 v53, v52, v52
	v_fmac_f32_e32 v55, v54, v54
	v_add_f32_e32 v52, v53, v55
	v_add_f32_e32 v54, v56, v52
	s_nop 0
	v_pk_add_f32 v[50:51], v[50:51], v[178:179]
	v_pk_add_f32 v[48:49], v[48:49], v[176:177]
	global_store_dwordx4 v[72:73], v[48:51], off offset:528
	v_cvt_pk_bf16_f32 v52, v48, v49
	v_cvt_pk_bf16_f32 v53, v50, v51
	v_mul_f32_e32 v49, v49, v49
	v_mul_f32_e32 v51, v51, v51
	v_fmac_f32_e32 v49, v48, v48
	v_fmac_f32_e32 v51, v50, v50
	v_add_f32_e32 v48, v49, v51
	v_add_f32_e32 v48, v54, v48
	v_mov_b32_e32 v49, v48
	s_nop 1
	v_permlane16_swap_b32 v48, v49
	global_store_dwordx2 v[70:71], v[52:53], off
	v_add_f32_e32 v48, v48, v49
	v_mov_b32_e32 v49, v48
	s_nop 1
	v_permlane32_swap_b32 v48, v49
	s_and_saveexec_b64 s[12:13], s[2:3]
	s_cbranch_execz .LBB0_1218
	v_lshl_add_u64 v[50:51], v[64:65], 2, s[8:9]
	v_add_f32_e32 v48, v48, v49
	global_atomic_add_f32 v[50:51], v48, off
; __device__ __forceinline__ unsigned pk2(float lo, float hi) { f32x2_t v = {lo, hi}; bf16x2_t b = __builtin_convertvector(v, bf16x2_t); return __builtin_bit_cast(unsigned, b); }
; __device__ __forceinline__ float xor16_sum(float v) { float a = v, b = v; swap16(a, b); return a + b; }
; __device__ __forceinline__ float xor32_sum(float v) { float a = v, b = v; swap32(a, b); return a + b; }
;     __device__ __forceinline__ void operator()(const f32x4 (&acc)[2][2][4][2], const Unit& u, int wr, int wc, int fr, int fq) const {
;     ...
;         for (int ai = 0; ai < 2; ++ai)
; #pragma unroll
;             for (int m = 0; m < 4; ++m) {
;                 const int row = row0 + ai * HALF + m * 16; float sq = 0.f;
; #pragma unroll
;                 for (int bj = 0; bj < 2; ++bj)
; #pragma unroll
;                     for (int n = 0; n < 2; ++n) {
;                         const size_t idx = (size_t)row * ldc + u.pn * BM + bj * HALF + wc * 32 + 8 * fq + 4 * n;
;                         const f32x4 b = *(const f32x4*)(base + idx);
;                         const f32x4 v = b + acc[ai][bj][m][n] * alpha;
;                         *(f32x4*)(out + idx) = v;
;                         if (NORM) { u32x2 w; w.x = pk2(v[0], v[1]); w.y = pk2(v[2], v[3]); *(u32x2*)(xb + idx) = w; sq += (v[0] * v[0] + v[1] * v[1]) + (v[2] * v[2] + v[3] * v[3]); }
;                     }
;                 if (NORM) { sq = xor16_sum(sq); sq = xor32_sum(sq); if (fq == 0) __hip_atomic_fetch_add(ss + row, sq, __ATOMIC_RELAXED, __HIP_MEMORY_SCOPE_AGENT); }
.LBB0_1218:
	s_or_b64 exec, exec, s[12:13]
	v_add_u32_e32 v48, 0x90, v148
	v_ashrrev_i32_e32 v49, 31, v48
	v_lshlrev_b64 v[50:51], 11, v[48:49]
	v_lshl_add_u64 v[54:55], v[50:51], 0, v[146:147]
	v_lshl_add_u64 v[56:57], v[54:55], 2, s[30:31]
	s_nop 0
	v_lshlrev_b64 v[54:55], 1, v[54:55]
	v_lshl_add_u64 v[58:59], s[6:7], 0, v[54:55]
	s_nop 0
	s_waitcnt vmcnt(34)
	v_pk_add_f32 v[46:47], v[46:47], v[182:183]
	v_pk_add_f32 v[44:45], v[44:45], v[180:181]
	v_cvt_pk_bf16_f32 v51, v46, v47
	v_cvt_pk_bf16_f32 v50, v44, v45
	global_store_dwordx4 v[56:57], v[44:47], off
	global_store_dwordx2 v[58:59], v[50:51], off
	s_nop 0
	v_or_b32_e32 v58, 8, v54
	v_mov_b32_e32 v59, v55
	v_lshl_add_u64 v[58:59], s[6:7], 0, v[58:59]
	v_mul_f32_e32 v45, v45, v45
	v_mul_f32_e32 v47, v47, v47
	v_fmac_f32_e32 v45, v44, v44
	v_fmac_f32_e32 v47, v46, v46
	v_add_f32_e32 v44, v45, v47
	s_nop 0
	v_pk_add_f32 v[42:43], v[42:43], v[190:191]
	v_pk_add_f32 v[40:41], v[40:41], v[188:189]
	v_cvt_pk_bf16_f32 v51, v42, v43
	v_cvt_pk_bf16_f32 v50, v40, v41
	global_store_dwordx4 v[56:57], v[40:43], off offset:16
	global_store_dwordx2 v[58:59], v[50:51], off
	s_nop 0
	v_or_b32_e32 v58, 0x100, v54
	v_mov_b32_e32 v59, v55
	v_lshl_add_u64 v[58:59], s[6:7], 0, v[58:59]
	v_mul_f32_e32 v41, v41, v41
	v_mul_f32_e32 v43, v43, v43
	v_fmac_f32_e32 v41, v40, v40
	v_fmac_f32_e32 v43, v42, v42
	v_add_f32_e32 v40, v41, v43
	v_add_f32_e32 v40, v44, v40
	v_or_b32_e32 v54, 0x108, v54
	v_lshl_add_u64 v[54:55], s[6:7], 0, v[54:55]
	s_nop 0
	v_pk_add_f32 v[38:39], v[38:39], v[194:195]
	v_pk_add_f32 v[36:37], v[36:37], v[192:193]
	v_cvt_pk_bf16_f32 v51, v38, v39
	v_cvt_pk_bf16_f32 v50, v36, v37
	global_store_dwordx4 v[56:57], v[36:39], off offset:512
	global_store_dwordx2 v[58:59], v[50:51], off
	s_nop 0
	v_mul_f32_e32 v37, v37, v37
	v_mul_f32_e32 v39, v39, v39
	v_fmac_f32_e32 v37, v36, v36
	v_fmac_f32_e32 v39, v38, v38
	v_add_f32_e32 v36, v37, v39
	v_add_f32_e32 v38, v40, v36
	s_nop 0
	v_pk_add_f32 v[34:35], v[34:35], v[198:199]
	v_pk_add_f32 v[32:33], v[32:33], v[196:197]
	global_store_dwordx4 v[56:57], v[32:35], off offset:528
	v_cvt_pk_bf16_f32 v36, v32, v33
	v_cvt_pk_bf16_f32 v37, v34, v35
	v_mul_f32_e32 v33, v33, v33
	v_mul_f32_e32 v35, v35, v35
	v_fmac_f32_e32 v33, v32, v32
	v_fmac_f32_e32 v35, v34, v34
	v_add_f32_e32 v32, v33, v35
	v_add_f32_e32 v32, v38, v32
	v_mov_b32_e32 v33, v32
	s_nop 1
	v_permlane16_swap_b32 v32, v33
	global_store_dwordx2 v[54:55], v[36:37], off
	v_add_f32_e32 v32, v32, v33
	v_mov_b32_e32 v33, v32
	s_nop 1
	v_permlane32_swap_b32 v32, v33
	s_and_saveexec_b64 s[12:13], s[2:3]
	s_cbranch_execz .LBB0_1220
	v_lshl_add_u64 v[34:35], v[48:49], 2, s[8:9]
	v_add_f32_e32 v32, v32, v33
	global_atomic_add_f32 v[34:35], v32, off
; __device__ __forceinline__ unsigned pk2(float lo, float hi) { f32x2_t v = {lo, hi}; bf16x2_t b = __builtin_convertvector(v, bf16x2_t); return __builtin_bit_cast(unsigned, b); }
; __device__ __forceinline__ float xor16_sum(float v) { float a = v, b = v; swap16(a, b); return a + b; }
; __device__ __forceinline__ float xor32_sum(float v) { float a = v, b = v; swap32(a, b); return a + b; }
;     __device__ __forceinline__ void operator()(const f32x4 (&acc)[2][2][4][2], const Unit& u, int wr, int wc, int fr, int fq) const {
;     ...
;         for (int ai = 0; ai < 2; ++ai)
; #pragma unroll
;             for (int m = 0; m < 4; ++m) {
;                 const int row = row0 + ai * HALF + m * 16; float sq = 0.f;
; #pragma unroll
;                 for (int bj = 0; bj < 2; ++bj)
; #pragma unroll
;                     for (int n = 0; n < 2; ++n) {
;                         const size_t idx = (size_t)row * ldc + u.pn * BM + bj * HALF + wc * 32 + 8 * fq + 4 * n;
;                         const f32x4 b = *(const f32x4*)(base + idx);
;                         const f32x4 v = b + acc[ai][bj][m][n] * alpha;
;                         *(f32x4*)(out + idx) = v;
;                         if (NORM) { u32x2 w; w.x = pk2(v[0], v[1]); w.y = pk2(v[2], v[3]); *(u32x2*)(xb + idx) = w; sq += (v[0] * v[0] + v[1] * v[1]) + (v[2] * v[2] + v[3] * v[3]); }
;                     }
;                 if (NORM) { sq = xor16_sum(sq); sq = xor32_sum(sq); if (fq == 0) __hip_atomic_fetch_add(ss + row, sq, __ATOMIC_RELAXED, __HIP_MEMORY_SCOPE_AGENT); }
.LBB0_1220:
	s_or_b64 exec, exec, s[12:13]
	v_add_u32_e32 v32, 0xa0, v148
	v_ashrrev_i32_e32 v33, 31, v32
	v_lshlrev_b64 v[34:35], 11, v[32:33]
	v_lshl_add_u64 v[38:39], v[34:35], 0, v[146:147]
	v_lshl_add_u64 v[40:41], v[38:39], 2, s[30:31]
	s_nop 0
	v_lshlrev_b64 v[38:39], 1, v[38:39]
	v_lshl_add_u64 v[42:43], s[6:7], 0, v[38:39]
	s_nop 0
	s_waitcnt vmcnt(30)
	v_pk_add_f32 v[30:31], v[30:31], v[202:203]
	v_pk_add_f32 v[28:29], v[28:29], v[200:201]
	v_cvt_pk_bf16_f32 v35, v30, v31
	v_cvt_pk_bf16_f32 v34, v28, v29
	global_store_dwordx4 v[40:41], v[28:31], off
	global_store_dwordx2 v[42:43], v[34:35], off
	s_nop 0
	v_or_b32_e32 v42, 8, v38
	v_mov_b32_e32 v43, v39
	v_lshl_add_u64 v[42:43], s[6:7], 0, v[42:43]
	v_mul_f32_e32 v29, v29, v29
	v_mul_f32_e32 v31, v31, v31
	v_fmac_f32_e32 v29, v28, v28
	v_fmac_f32_e32 v31, v30, v30
	v_add_f32_e32 v28, v29, v31
	s_nop 0
	v_pk_add_f32 v[26:27], v[26:27], v[206:207]
	v_pk_add_f32 v[24:25], v[24:25], v[204:205]
	v_cvt_pk_bf16_f32 v35, v26, v27
	v_cvt_pk_bf16_f32 v34, v24, v25
	global_store_dwordx4 v[40:41], v[24:27], off offset:16
	global_store_dwordx2 v[42:43], v[34:35], off
	s_nop 0
	v_or_b32_e32 v42, 0x100, v38
	v_mov_b32_e32 v43, v39
	v_lshl_add_u64 v[42:43], s[6:7], 0, v[42:43]
	v_mul_f32_e32 v25, v25, v25
	v_mul_f32_e32 v27, v27, v27
	v_fmac_f32_e32 v25, v24, v24
	v_fmac_f32_e32 v27, v26, v26
	v_add_f32_e32 v24, v25, v27
	v_add_f32_e32 v24, v28, v24
	v_or_b32_e32 v38, 0x108, v38
	v_lshl_add_u64 v[38:39], s[6:7], 0, v[38:39]
	s_nop 0
	v_pk_add_f32 v[22:23], v[22:23], v[210:211]
	v_pk_add_f32 v[20:21], v[20:21], v[208:209]
	v_cvt_pk_bf16_f32 v35, v22, v23
	v_cvt_pk_bf16_f32 v34, v20, v21
	global_store_dwordx4 v[40:41], v[20:23], off offset:512
	global_store_dwordx2 v[42:43], v[34:35], off
	s_nop 0
	v_mul_f32_e32 v21, v21, v21
	v_mul_f32_e32 v23, v23, v23
	v_fmac_f32_e32 v21, v20, v20
	v_fmac_f32_e32 v23, v22, v22
	v_add_f32_e32 v20, v21, v23
	v_add_f32_e32 v22, v24, v20
	s_nop 0
	v_pk_add_f32 v[18:19], v[18:19], v[214:215]
	v_pk_add_f32 v[16:17], v[16:17], v[212:213]
	global_store_dwordx4 v[40:41], v[16:19], off offset:528
	v_cvt_pk_bf16_f32 v20, v16, v17
	v_cvt_pk_bf16_f32 v21, v18, v19
	v_mul_f32_e32 v17, v17, v17
	v_mul_f32_e32 v19, v19, v19
	v_fmac_f32_e32 v17, v16, v16
	v_fmac_f32_e32 v19, v18, v18
	v_add_f32_e32 v16, v17, v19
	v_add_f32_e32 v16, v22, v16
	v_mov_b32_e32 v17, v16
	s_nop 1
	v_permlane16_swap_b32 v16, v17
	global_store_dwordx2 v[38:39], v[20:21], off
	v_add_f32_e32 v16, v16, v17
	v_mov_b32_e32 v17, v16
	s_nop 1
	v_permlane32_swap_b32 v16, v17
	s_and_saveexec_b64 s[12:13], s[2:3]
	s_cbranch_execz .LBB0_1222
	v_lshl_add_u64 v[18:19], v[32:33], 2, s[8:9]
	v_add_f32_e32 v16, v16, v17
	global_atomic_add_f32 v[18:19], v16, off
.LBB0_1222:
	s_or_b64 exec, exec, s[12:13]
	v_add_u32_e32 v16, 0xb0, v148
	v_ashrrev_i32_e32 v17, 31, v16
	v_lshlrev_b64 v[18:19], 11, v[16:17]
	v_lshl_add_u64 v[22:23], v[18:19], 0, v[146:147]
	v_lshl_add_u64 v[24:25], v[22:23], 2, s[30:31]
	s_nop 0
	v_lshlrev_b64 v[22:23], 1, v[22:23]
	v_lshl_add_u64 v[26:27], s[6:7], 0, v[22:23]
	s_nop 0
	s_waitcnt vmcnt(26)
	v_pk_add_f32 v[14:15], v[14:15], v[218:219]
	v_pk_add_f32 v[12:13], v[12:13], v[216:217]
	v_cvt_pk_bf16_f32 v19, v14, v15
	v_cvt_pk_bf16_f32 v18, v12, v13
	global_store_dwordx4 v[24:25], v[12:15], off
	global_store_dwordx2 v[26:27], v[18:19], off
	s_nop 0
	v_or_b32_e32 v26, 8, v22
	v_mov_b32_e32 v27, v23
	v_lshl_add_u64 v[26:27], s[6:7], 0, v[26:27]
	v_mul_f32_e32 v13, v13, v13
	v_mul_f32_e32 v15, v15, v15
	v_fmac_f32_e32 v13, v12, v12
	v_fmac_f32_e32 v15, v14, v14
	v_add_f32_e32 v12, v13, v15
	s_nop 0
	v_pk_add_f32 v[10:11], v[10:11], v[222:223]
	v_pk_add_f32 v[8:9], v[8:9], v[220:221]
	v_cvt_pk_bf16_f32 v19, v10, v11
	v_cvt_pk_bf16_f32 v18, v8, v9
	global_store_dwordx4 v[24:25], v[8:11], off offset:16
	global_store_dwordx2 v[26:27], v[18:19], off
	s_nop 0
	v_or_b32_e32 v26, 0x100, v22
	v_mov_b32_e32 v27, v23
	v_lshl_add_u64 v[26:27], s[6:7], 0, v[26:27]
	v_mul_f32_e32 v9, v9, v9
	v_mul_f32_e32 v11, v11, v11
	v_fmac_f32_e32 v9, v8, v8
	v_fmac_f32_e32 v11, v10, v10
	v_add_f32_e32 v8, v9, v11
	v_add_f32_e32 v8, v12, v8
	v_or_b32_e32 v22, 0x108, v22
	v_lshl_add_u64 v[22:23], s[6:7], 0, v[22:23]
	s_nop 0
	v_pk_add_f32 v[6:7], v[6:7], v[226:227]
	v_pk_add_f32 v[4:5], v[4:5], v[224:225]
	v_cvt_pk_bf16_f32 v19, v6, v7
	v_cvt_pk_bf16_f32 v18, v4, v5
	global_store_dwordx4 v[24:25], v[4:7], off offset:512
	global_store_dwordx2 v[26:27], v[18:19], off
	s_nop 0
	v_mul_f32_e32 v5, v5, v5
	v_mul_f32_e32 v7, v7, v7
	v_fmac_f32_e32 v5, v4, v4
	v_fmac_f32_e32 v7, v6, v6
	v_add_f32_e32 v4, v5, v7
	v_add_f32_e32 v6, v8, v4
	s_nop 0
	v_pk_add_f32 v[2:3], v[2:3], v[236:237]
	v_pk_add_f32 v[0:1], v[0:1], v[234:235]
	global_store_dwordx4 v[24:25], v[0:3], off offset:528
	v_cvt_pk_bf16_f32 v4, v0, v1
	v_cvt_pk_bf16_f32 v5, v2, v3
	v_mul_f32_e32 v1, v1, v1
	v_mul_f32_e32 v3, v3, v3
	v_fmac_f32_e32 v1, v0, v0
	v_fmac_f32_e32 v3, v2, v2
	v_add_f32_e32 v0, v1, v3
	v_add_f32_e32 v0, v6, v0
	v_mov_b32_e32 v1, v0
	s_nop 1
	v_permlane16_swap_b32 v0, v1
	global_store_dwordx2 v[22:23], v[4:5], off
	v_add_f32_e32 v0, v0, v1
	v_mov_b32_e32 v1, v0
	s_nop 1
	v_permlane32_swap_b32 v0, v1
	s_and_saveexec_b64 s[12:13], s[2:3]
	s_cbranch_execz .LBB0_1224
	v_lshl_add_u64 v[2:3], v[16:17], 2, s[8:9]
	v_add_f32_e32 v0, v0, v1
	global_atomic_add_f32 v[2:3], v0, off

; __device__ __forceinline__ unsigned pk2(float lo, float hi) { f32x2_t v = {lo, hi}; bf16x2_t b = __builtin_convertvector(v, bf16x2_t); return __builtin_bit_cast(unsigned, b); }
;     __device__ __forceinline__ void operator()(const f32x4 (&acc)[2][2][4][2], const Unit& u, int wr, int wc, int fr, int fq) const {
;     ...
;         for (int bj = 0; bj < 2; ++bj) {
;             const int c = u.pn * BM + bj * HALF + wc * 32 + 8 * fq; const int dc = remap ? (c >> 7) * 192 + (c & 127) : c;
;             f32x4 cs0 = (f32x4){1.f, 1.f, 1.f, 1.f}, cs1 = cs0;
;             if (smode == 2) { const f32x4 t0 = *(const f32x4*)(ss + c), t1 = *(const f32x4*)(ss + c + 4);
; #pragma unroll
;                 for (int e = 0; e < 4; ++e) { cs0[e] = rsqrtf(t0[e] * (1.f / 2048.f) + EPS); cs1[e] = rsqrtf(t1[e] * (1.f / 2048.f) + EPS); } }
; #pragma unroll
;             for (int ai = 0; ai < 2; ++ai)
; #pragma unroll
;                 for (int m = 0; m < 4; ++m) {
;                     const int row = row0 + ai * HALF + m * 16;
;                     const float rs = (smode == 1) ? rsqrtf(ss[row] * (1.f / 2048.f) + EPS) : 1.f;
;                     const f32x4 v0 = acc[ai][bj][m][0] * cs0 * rs, v1 = acc[ai][bj][m][1] * cs1 * rs; u32x4 w;
;                     w.x = pk2(v0[0], v0[1]); w.y = pk2(v0[2], v0[3]); w.z = pk2(v1[0], v1[1]); w.w = pk2(v1[2], v1[3]);
;                     size_t off = (size_t)row * ldc + dc;
;                     if (remap == 3) {
;                         const int b_ = c >> 11, ch_ = (c >> 6) & 31, s_ = (c >> 5) & 1, fq_ = (c >> 3) & 3, h_ = row >> 8, vs_ = (row >> 5) & 7, n_ = (row >> 4) & 1, fr_ = row & 15;
;                         off = ((((size_t)((b_ * 4 + h_) * 8 + vs_) * 32 + ch_) * 4 + n_ * 2 + s_) * 64 + fq_ * 16 + fr_) * 8; }
;                     *(u32x4*)(O + off) = w;
.LBB0_1303:
	v_lshl_add_u32 v166, s0, 8, v158
	v_ashrrev_i32_e32 v167, 31, v166
	v_lshl_add_u64 v[144:145], v[166:167], 2, s[8:9]
	global_load_dword v230, v[144:145], off
	global_load_dword v231, v[144:145], off offset:64
	global_load_dword v232, v[144:145], off offset:128
	global_load_dword v233, v[144:145], off offset:192
	global_load_dword v234, v[144:145], off offset:512
	global_load_dword v235, v[144:145], off offset:576
	global_load_dword v236, v[144:145], off offset:640
	global_load_dword v237, v[144:145], off offset:704
	s_nop 0
	v_lshl_or_b32 v146, s1, 8, v160
	v_ashrrev_i32_e32 v147, 31, v146
	v_lshlrev_b64 v[170:171], 1, v[146:147]
	v_lshlrev_b64 v[148:149], 10, v[166:167]
	v_or_b32_e32 v168, 16, v166
	v_ashrrev_i32_e32 v169, 31, v168
	s_waitcnt vmcnt(7)
	v_fmamk_f32 v146, v230, 0x3a000000, v164
	v_mul_f32_e32 v147, 0x4b800000, v146
	v_cmp_gt_f32_e32 vcc, s64, v146
	s_nop 1
	v_cndmask_b32_e32 v146, v146, v147, vcc
	v_rsq_f32_e32 v165, v146
	v_lshl_add_u64 v[146:147], s[10:11], 0, v[148:149]
	v_lshl_add_u64 v[146:147], v[146:147], 0, v[170:171]
	v_lshl_add_u64 v[148:149], v[168:169], 2, s[8:9]
	v_mul_f32_e32 v167, 0x45800000, v165
	v_cndmask_b32_e32 v172, v165, v167, vcc
	v_pk_mul_f32 v[126:127], v[126:127], v[172:173] op_sel_hi:[1,0]
	v_pk_mul_f32 v[124:125], v[124:125], v[172:173] op_sel_hi:[1,0]
	v_pk_mul_f32 v[174:175], v[122:123], v[172:173] op_sel_hi:[1,0]
	v_pk_mul_f32 v[122:123], v[120:121], v[172:173] op_sel_hi:[1,0]
	v_cvt_pk_bf16_f32 v120, v124, v125
	v_cvt_pk_bf16_f32 v121, v126, v127
	v_cvt_pk_bf16_f32 v122, v122, v123
	v_cvt_pk_bf16_f32 v123, v174, v175
	global_store_dwordx4 v[146:147], v[120:123], off
	s_nop 0
	v_or_b32_e32 v124, 32, v166
	v_lshlrev_b64 v[122:123], 10, v[168:169]
	v_lshl_add_u64 v[122:123], s[10:11], 0, v[122:123]
	v_ashrrev_i32_e32 v125, 31, v124
	v_lshl_add_u64 v[122:123], v[122:123], 0, v[170:171]
	s_waitcnt vmcnt(7)
	v_fmamk_f32 v120, v231, 0x3a000000, v164
	v_mul_f32_e32 v121, 0x4b800000, v120
	v_cmp_gt_f32_e32 vcc, s64, v120
	s_nop 1
	v_cndmask_b32_e32 v120, v120, v121, vcc
	v_rsq_f32_e32 v126, v120
	v_lshl_add_u64 v[120:121], v[124:125], 2, s[8:9]
	v_mul_f32_e32 v127, 0x45800000, v126
	v_cndmask_b32_e32 v126, v126, v127, vcc
	v_pk_mul_f32 v[118:119], v[118:119], v[126:127] op_sel_hi:[1,0]
	v_pk_mul_f32 v[116:117], v[116:117], v[126:127] op_sel_hi:[1,0]
	v_pk_mul_f32 v[168:169], v[114:115], v[126:127] op_sel_hi:[1,0]
	v_pk_mul_f32 v[114:115], v[112:113], v[126:127] op_sel_hi:[1,0]
	v_cvt_pk_bf16_f32 v112, v116, v117
	v_cvt_pk_bf16_f32 v113, v118, v119
	v_cvt_pk_bf16_f32 v114, v114, v115
	v_cvt_pk_bf16_f32 v115, v168, v169
	global_store_dwordx4 v[122:123], v[112:115], off
	s_nop 0
	v_or_b32_e32 v116, 48, v166
	v_lshlrev_b64 v[114:115], 10, v[124:125]
	v_lshl_add_u64 v[114:115], s[10:11], 0, v[114:115]
	v_ashrrev_i32_e32 v117, 31, v116
	v_lshl_add_u64 v[114:115], v[114:115], 0, v[170:171]
	s_waitcnt vmcnt(7)
	v_fmamk_f32 v112, v232, 0x3a000000, v164
	v_mul_f32_e32 v113, 0x4b800000, v112
	v_cmp_gt_f32_e32 vcc, s64, v112
	s_nop 1
	v_cndmask_b32_e32 v112, v112, v113, vcc
	v_rsq_f32_e32 v118, v112
	v_lshl_add_u64 v[112:113], v[116:117], 2, s[8:9]
	v_mul_f32_e32 v119, 0x45800000, v118
	v_cndmask_b32_e32 v118, v118, v119, vcc
	v_pk_mul_f32 v[110:111], v[110:111], v[118:119] op_sel_hi:[1,0]
	v_pk_mul_f32 v[108:109], v[108:109], v[118:119] op_sel_hi:[1,0]
	v_pk_mul_f32 v[124:125], v[106:107], v[118:119] op_sel_hi:[1,0]
	v_pk_mul_f32 v[106:107], v[104:105], v[118:119] op_sel_hi:[1,0]
	v_cvt_pk_bf16_f32 v104, v108, v109
	v_cvt_pk_bf16_f32 v105, v110, v111
	v_cvt_pk_bf16_f32 v106, v106, v107
	v_cvt_pk_bf16_f32 v107, v124, v125
	global_store_dwordx4 v[114:115], v[104:107], off
	s_nop 0
	s_waitcnt vmcnt(7)
	v_fmamk_f32 v104, v233, 0x3a000000, v164
	v_mul_f32_e32 v105, 0x4b800000, v104
	v_cmp_gt_f32_e32 vcc, s64, v104
	s_nop 1
	v_cndmask_b32_e32 v104, v104, v105, vcc
	v_rsq_f32_e32 v106, v104
	v_lshlrev_b64 v[104:105], 10, v[116:117]
	v_lshl_add_u64 v[104:105], s[10:11], 0, v[104:105]
	v_lshl_add_u64 v[104:105], v[104:105], 0, v[170:171]
	v_mul_f32_e32 v107, 0x45800000, v106
	v_cndmask_b32_e32 v106, v106, v107, vcc
	v_pk_mul_f32 v[102:103], v[102:103], v[106:107] op_sel_hi:[1,0]
	v_pk_mul_f32 v[100:101], v[100:101], v[106:107] op_sel_hi:[1,0]
	v_pk_mul_f32 v[108:109], v[98:99], v[106:107] op_sel_hi:[1,0]
	v_pk_mul_f32 v[98:99], v[96:97], v[106:107] op_sel_hi:[1,0]
	v_cvt_pk_bf16_f32 v96, v100, v101
	v_cvt_pk_bf16_f32 v97, v102, v103
	v_cvt_pk_bf16_f32 v98, v98, v99
	v_cvt_pk_bf16_f32 v99, v108, v109
	global_store_dwordx4 v[104:105], v[96:99], off
	s_nop 0
	s_waitcnt vmcnt(7)
	v_fmamk_f32 v96, v234, 0x3a000000, v164
	v_mul_f32_e32 v97, 0x4b800000, v96
	v_cmp_gt_f32_e32 vcc, s64, v96
	s_nop 1
	v_cndmask_b32_e32 v96, v96, v97, vcc
	v_rsq_f32_e32 v98, v96
	v_add_co_u32_e64 v96, s[0:1], s65, v146
	v_mul_f32_e32 v99, 0x45800000, v98
	v_cndmask_b32_e32 v98, v98, v99, vcc
	v_pk_mul_f32 v[94:95], v[94:95], v[98:99] op_sel_hi:[1,0]
	v_pk_mul_f32 v[92:93], v[92:93], v[98:99] op_sel_hi:[1,0]
	v_pk_mul_f32 v[100:101], v[90:91], v[98:99] op_sel_hi:[1,0]
	v_pk_mul_f32 v[90:91], v[88:89], v[98:99] op_sel_hi:[1,0]
	v_addc_co_u32_e64 v97, s[0:1], 0, v147, s[0:1]
	v_cvt_pk_bf16_f32 v88, v92, v93
	v_cvt_pk_bf16_f32 v89, v94, v95
	v_cvt_pk_bf16_f32 v90, v90, v91
	v_cvt_pk_bf16_f32 v91, v100, v101
	global_store_dwordx4 v[96:97], v[88:91], off
	s_nop 0
	s_waitcnt vmcnt(7)
; __device__ __forceinline__ unsigned pk2(float lo, float hi) { f32x2_t v = {lo, hi}; bf16x2_t b = __builtin_convertvector(v, bf16x2_t); return __builtin_bit_cast(unsigned, b); }
;     __device__ __forceinline__ void operator()(const f32x4 (&acc)[2][2][4][2], const Unit& u, int wr, int wc, int fr, int fq) const {
;     ...
;         for (int bj = 0; bj < 2; ++bj) {
;             const int c = u.pn * BM + bj * HALF + wc * 32 + 8 * fq; const int dc = remap ? (c >> 7) * 192 + (c & 127) : c;
;             f32x4 cs0 = (f32x4){1.f, 1.f, 1.f, 1.f}, cs1 = cs0;
;             if (smode == 2) { const f32x4 t0 = *(const f32x4*)(ss + c), t1 = *(const f32x4*)(ss + c + 4);
; #pragma unroll
;                 for (int e = 0; e < 4; ++e) { cs0[e] = rsqrtf(t0[e] * (1.f / 2048.f) + EPS); cs1[e] = rsqrtf(t1[e] * (1.f / 2048.f) + EPS); } }
; #pragma unroll
;             for (int ai = 0; ai < 2; ++ai)
; #pragma unroll
;                 for (int m = 0; m < 4; ++m) {
;                     const int row = row0 + ai * HALF + m * 16;
;                     const float rs = (smode == 1) ? rsqrtf(ss[row] * (1.f / 2048.f) + EPS) : 1.f;
;                     const f32x4 v0 = acc[ai][bj][m][0] * cs0 * rs, v1 = acc[ai][bj][m][1] * cs1 * rs; u32x4 w;
;                     w.x = pk2(v0[0], v0[1]); w.y = pk2(v0[2], v0[3]); w.z = pk2(v1[0], v1[1]); w.w = pk2(v1[2], v1[3]);
;                     size_t off = (size_t)row * ldc + dc;
;                     if (remap == 3) {
;                         const int b_ = c >> 11, ch_ = (c >> 6) & 31, s_ = (c >> 5) & 1, fq_ = (c >> 3) & 3, h_ = row >> 8, vs_ = (row >> 5) & 7, n_ = (row >> 4) & 1, fr_ = row & 15;
;                         off = ((((size_t)((b_ * 4 + h_) * 8 + vs_) * 32 + ch_) * 4 + n_ * 2 + s_) * 64 + fq_ * 16 + fr_) * 8; }
;                     *(u32x4*)(O + off) = w;
	v_fmamk_f32 v88, v235, 0x3a000000, v164
	v_mul_f32_e32 v89, 0x4b800000, v88
	v_cmp_gt_f32_e32 vcc, s64, v88
	s_nop 1
	v_cndmask_b32_e32 v88, v88, v89, vcc
	v_rsq_f32_e32 v90, v88
	v_add_co_u32_e64 v88, s[0:1], s66, v146
	v_mul_f32_e32 v91, 0x45800000, v90
	v_cndmask_b32_e32 v90, v90, v91, vcc
	v_pk_mul_f32 v[86:87], v[86:87], v[90:91] op_sel_hi:[1,0]
	v_pk_mul_f32 v[84:85], v[84:85], v[90:91] op_sel_hi:[1,0]
	v_pk_mul_f32 v[92:93], v[82:83], v[90:91] op_sel_hi:[1,0]
	v_pk_mul_f32 v[82:83], v[80:81], v[90:91] op_sel_hi:[1,0]
	v_addc_co_u32_e64 v89, s[0:1], 0, v147, s[0:1]
	v_cvt_pk_bf16_f32 v80, v84, v85
	v_cvt_pk_bf16_f32 v81, v86, v87
	v_cvt_pk_bf16_f32 v82, v82, v83
	v_cvt_pk_bf16_f32 v83, v92, v93
	global_store_dwordx4 v[88:89], v[80:83], off
	s_nop 0
	s_waitcnt vmcnt(7)
	v_fmamk_f32 v80, v236, 0x3a000000, v164
	v_mul_f32_e32 v81, 0x4b800000, v80
	v_cmp_gt_f32_e32 vcc, s64, v80
	s_nop 1
	v_cndmask_b32_e32 v80, v80, v81, vcc
	v_rsq_f32_e32 v82, v80
	v_add_co_u32_e64 v80, s[0:1], s67, v146
	v_mul_f32_e32 v83, 0x45800000, v82
	v_cndmask_b32_e32 v82, v82, v83, vcc
	v_pk_mul_f32 v[78:79], v[78:79], v[82:83] op_sel_hi:[1,0]
	v_pk_mul_f32 v[76:77], v[76:77], v[82:83] op_sel_hi:[1,0]
	v_pk_mul_f32 v[84:85], v[74:75], v[82:83] op_sel_hi:[1,0]
	v_pk_mul_f32 v[74:75], v[72:73], v[82:83] op_sel_hi:[1,0]
	v_addc_co_u32_e64 v81, s[0:1], 0, v147, s[0:1]
	v_cvt_pk_bf16_f32 v72, v76, v77
	v_cvt_pk_bf16_f32 v73, v78, v79
	v_cvt_pk_bf16_f32 v74, v74, v75
	v_cvt_pk_bf16_f32 v75, v84, v85
	global_store_dwordx4 v[80:81], v[72:75], off
	s_nop 0
	s_waitcnt vmcnt(7)
; __device__ __forceinline__ unsigned pk2(float lo, float hi) { f32x2_t v = {lo, hi}; bf16x2_t b = __builtin_convertvector(v, bf16x2_t); return __builtin_bit_cast(unsigned, b); }
;     __device__ __forceinline__ void operator()(const f32x4 (&acc)[2][2][4][2], const Unit& u, int wr, int wc, int fr, int fq) const {
;     ...
;         for (int bj = 0; bj < 2; ++bj) {
;             const int c = u.pn * BM + bj * HALF + wc * 32 + 8 * fq; const int dc = remap ? (c >> 7) * 192 + (c & 127) : c;
;             f32x4 cs0 = (f32x4){1.f, 1.f, 1.f, 1.f}, cs1 = cs0;
;             if (smode == 2) { const f32x4 t0 = *(const f32x4*)(ss + c), t1 = *(const f32x4*)(ss + c + 4);
; #pragma unroll
;                 for (int e = 0; e < 4; ++e) { cs0[e] = rsqrtf(t0[e] * (1.f / 2048.f) + EPS); cs1[e] = rsqrtf(t1[e] * (1.f / 2048.f) + EPS); } }
; #pragma unroll
;             for (int ai = 0; ai < 2; ++ai)
; #pragma unroll
;                 for (int m = 0; m < 4; ++m) {
;                     const int row = row0 + ai * HALF + m * 16;
;                     const float rs = (smode == 1) ? rsqrtf(ss[row] * (1.f / 2048.f) + EPS) : 1.f;
;                     const f32x4 v0 = acc[ai][bj][m][0] * cs0 * rs, v1 = acc[ai][bj][m][1] * cs1 * rs; u32x4 w;
;                     w.x = pk2(v0[0], v0[1]); w.y = pk2(v0[2], v0[3]); w.z = pk2(v1[0], v1[1]); w.w = pk2(v1[2], v1[3]);
;                     size_t off = (size_t)row * ldc + dc;
;                     if (remap == 3) {
;                         const int b_ = c >> 11, ch_ = (c >> 6) & 31, s_ = (c >> 5) & 1, fq_ = (c >> 3) & 3, h_ = row >> 8, vs_ = (row >> 5) & 7, n_ = (row >> 4) & 1, fr_ = row & 15;
;                         off = ((((size_t)((b_ * 4 + h_) * 8 + vs_) * 32 + ch_) * 4 + n_ * 2 + s_) * 64 + fq_ * 16 + fr_) * 8; }
;                     *(u32x4*)(O + off) = w;
	v_fmamk_f32 v72, v237, 0x3a000000, v164
	v_mul_f32_e32 v73, 0x4b800000, v72
	v_cmp_gt_f32_e32 vcc, s64, v72
	s_nop 1
	v_cndmask_b32_e32 v72, v72, v73, vcc
	v_rsq_f32_e32 v74, v72
	v_add_co_u32_e64 v72, s[0:1], s68, v146
	v_mul_f32_e32 v75, 0x45800000, v74
	v_cndmask_b32_e32 v74, v74, v75, vcc
	v_pk_mul_f32 v[62:63], v[62:63], v[74:75] op_sel_hi:[1,0]
	v_pk_mul_f32 v[60:61], v[60:61], v[74:75] op_sel_hi:[1,0]
	v_pk_mul_f32 v[76:77], v[54:55], v[74:75] op_sel_hi:[1,0]
	v_pk_mul_f32 v[54:55], v[52:53], v[74:75] op_sel_hi:[1,0]
	v_addc_co_u32_e64 v73, s[0:1], 0, v147, s[0:1]
	v_cvt_pk_bf16_f32 v52, v60, v61
	v_cvt_pk_bf16_f32 v53, v62, v63
	v_cvt_pk_bf16_f32 v54, v54, v55
	v_cvt_pk_bf16_f32 v55, v76, v77
	global_store_dwordx4 v[72:73], v[52:55], off
	s_nop 0
	s_mov_b64 s[0:1], 0x20000
	s_nop 0
	v_fmamk_f32 v52, v230, 0x3a000000, v164
	v_mul_f32_e32 v53, 0x4b800000, v52
	v_cmp_gt_f32_e32 vcc, s64, v52
	s_nop 1
	v_cndmask_b32_e32 v52, v52, v53, vcc
	v_rsq_f32_e32 v52, v52
	s_nop 0
	v_mul_f32_e32 v53, 0x45800000, v52
	v_cndmask_b32_e32 v52, v52, v53, vcc
	v_pk_mul_f32 v[54:55], v[70:71], v[52:53] op_sel_hi:[1,0]
	v_pk_mul_f32 v[60:61], v[68:69], v[52:53] op_sel_hi:[1,0]
	v_pk_mul_f32 v[62:63], v[66:67], v[52:53] op_sel_hi:[1,0]
	v_pk_mul_f32 v[64:65], v[64:65], v[52:53] op_sel_hi:[1,0]
	v_cvt_pk_bf16_f32 v52, v60, v61
	v_cvt_pk_bf16_f32 v53, v54, v55
	v_cvt_pk_bf16_f32 v54, v64, v65
	v_cvt_pk_bf16_f32 v55, v62, v63
	global_store_dwordx4 v[146:147], v[52:55], off offset:256
	s_nop 0
	s_nop 0
	v_fmamk_f32 v52, v231, 0x3a000000, v164
	v_mul_f32_e32 v53, 0x4b800000, v52
	v_cmp_gt_f32_e32 vcc, s64, v52
	s_nop 1
	v_cndmask_b32_e32 v52, v52, v53, vcc
	v_rsq_f32_e32 v52, v52
	s_nop 0
	v_mul_f32_e32 v53, 0x45800000, v52
	v_cndmask_b32_e32 v52, v52, v53, vcc
	v_pk_mul_f32 v[54:55], v[58:59], v[52:53] op_sel_hi:[1,0]
	v_pk_mul_f32 v[56:57], v[56:57], v[52:53] op_sel_hi:[1,0]
	v_pk_mul_f32 v[58:59], v[50:51], v[52:53] op_sel_hi:[1,0]
	v_pk_mul_f32 v[50:51], v[48:49], v[52:53] op_sel_hi:[1,0]
	v_cvt_pk_bf16_f32 v48, v56, v57
	v_cvt_pk_bf16_f32 v49, v54, v55
	v_cvt_pk_bf16_f32 v50, v50, v51
	v_cvt_pk_bf16_f32 v51, v58, v59
	global_store_dwordx4 v[122:123], v[48:51], off offset:256
	s_nop 0
	s_nop 0
	v_fmamk_f32 v48, v232, 0x3a000000, v164
	v_mul_f32_e32 v49, 0x4b800000, v48
	v_cmp_gt_f32_e32 vcc, s64, v48
	s_nop 1
	v_cndmask_b32_e32 v48, v48, v49, vcc
	v_rsq_f32_e32 v48, v48
	s_nop 0
	v_mul_f32_e32 v49, 0x45800000, v48
	v_cndmask_b32_e32 v48, v48, v49, vcc
	v_pk_mul_f32 v[46:47], v[46:47], v[48:49] op_sel_hi:[1,0]
	v_pk_mul_f32 v[44:45], v[44:45], v[48:49] op_sel_hi:[1,0]
	v_pk_mul_f32 v[50:51], v[42:43], v[48:49] op_sel_hi:[1,0]
	v_pk_mul_f32 v[42:43], v[40:41], v[48:49] op_sel_hi:[1,0]
	v_cvt_pk_bf16_f32 v40, v44, v45
	v_cvt_pk_bf16_f32 v41, v46, v47
	v_cvt_pk_bf16_f32 v42, v42, v43
	v_cvt_pk_bf16_f32 v43, v50, v51
	global_store_dwordx4 v[114:115], v[40:43], off offset:256
	s_nop 0
	s_nop 0
	v_fmamk_f32 v40, v233, 0x3a000000, v164
	v_mul_f32_e32 v41, 0x4b800000, v40
	v_cmp_gt_f32_e32 vcc, s64, v40
	s_nop 1
	v_cndmask_b32_e32 v40, v40, v41, vcc
	v_rsq_f32_e32 v40, v40
	s_nop 0
	v_mul_f32_e32 v41, 0x45800000, v40
	v_cndmask_b32_e32 v40, v40, v41, vcc
	v_pk_mul_f32 v[38:39], v[38:39], v[40:41] op_sel_hi:[1,0]
	v_pk_mul_f32 v[36:37], v[36:37], v[40:41] op_sel_hi:[1,0]
	v_pk_mul_f32 v[42:43], v[34:35], v[40:41] op_sel_hi:[1,0]
	v_pk_mul_f32 v[34:35], v[32:33], v[40:41] op_sel_hi:[1,0]
	v_cvt_pk_bf16_f32 v32, v36, v37
	v_cvt_pk_bf16_f32 v33, v38, v39
	v_cvt_pk_bf16_f32 v34, v34, v35
	v_cvt_pk_bf16_f32 v35, v42, v43
	global_store_dwordx4 v[104:105], v[32:35], off offset:256
	s_nop 0
	s_nop 0
	v_fmamk_f32 v32, v234, 0x3a000000, v164
	v_mul_f32_e32 v33, 0x4b800000, v32
	v_cmp_gt_f32_e32 vcc, s64, v32
	s_nop 1
	v_cndmask_b32_e32 v32, v32, v33, vcc
	v_rsq_f32_e32 v34, v32
	v_lshl_add_u64 v[32:33], v[146:147], 0, s[0:1]
	v_mul_f32_e32 v35, 0x45800000, v34
	v_cndmask_b32_e32 v34, v34, v35, vcc
	v_pk_mul_f32 v[30:31], v[30:31], v[34:35] op_sel_hi:[1,0]
	v_pk_mul_f32 v[28:29], v[28:29], v[34:35] op_sel_hi:[1,0]
	v_pk_mul_f32 v[36:37], v[26:27], v[34:35] op_sel_hi:[1,0]
	v_pk_mul_f32 v[26:27], v[24:25], v[34:35] op_sel_hi:[1,0]
	v_cvt_pk_bf16_f32 v24, v28, v29
	v_cvt_pk_bf16_f32 v25, v30, v31
	v_cvt_pk_bf16_f32 v26, v26, v27
	v_cvt_pk_bf16_f32 v27, v36, v37
	global_store_dwordx4 v[32:33], v[24:27], off offset:256
	s_nop 0
	s_nop 0
	v_fmamk_f32 v24, v235, 0x3a000000, v164
	v_mul_f32_e32 v25, 0x4b800000, v24
	v_cmp_gt_f32_e32 vcc, s64, v24
	s_nop 1
	v_cndmask_b32_e32 v24, v24, v25, vcc
	v_rsq_f32_e32 v26, v24
	v_lshl_add_u64 v[24:25], v[146:147], 0, s[36:37]
	v_mul_f32_e32 v27, 0x45800000, v26
	v_cndmask_b32_e32 v26, v26, v27, vcc
	v_pk_mul_f32 v[22:23], v[22:23], v[26:27] op_sel_hi:[1,0]
	v_pk_mul_f32 v[20:21], v[20:21], v[26:27] op_sel_hi:[1,0]
	v_pk_mul_f32 v[28:29], v[18:19], v[26:27] op_sel_hi:[1,0]
	v_pk_mul_f32 v[18:19], v[16:17], v[26:27] op_sel_hi:[1,0]
	v_cvt_pk_bf16_f32 v16, v20, v21
	v_cvt_pk_bf16_f32 v17, v22, v23
	v_cvt_pk_bf16_f32 v18, v18, v19
	v_cvt_pk_bf16_f32 v19, v28, v29
	global_store_dwordx4 v[24:25], v[16:19], off offset:256
	s_nop 0
	s_nop 0
	v_fmamk_f32 v16, v236, 0x3a000000, v164
	v_mul_f32_e32 v17, 0x4b800000, v16
	v_cmp_gt_f32_e32 vcc, s64, v16
	s_nop 1
	v_cndmask_b32_e32 v16, v16, v17, vcc
	v_rsq_f32_e32 v18, v16
	v_lshl_add_u64 v[16:17], v[146:147], 0, s[38:39]
	v_mul_f32_e32 v19, 0x45800000, v18
	v_cndmask_b32_e32 v18, v18, v19, vcc
	v_pk_mul_f32 v[14:15], v[14:15], v[18:19] op_sel_hi:[1,0]
	v_pk_mul_f32 v[12:13], v[12:13], v[18:19] op_sel_hi:[1,0]
	v_pk_mul_f32 v[20:21], v[10:11], v[18:19] op_sel_hi:[1,0]
	v_pk_mul_f32 v[10:11], v[8:9], v[18:19] op_sel_hi:[1,0]
	v_cvt_pk_bf16_f32 v8, v12, v13
	v_cvt_pk_bf16_f32 v9, v14, v15
	v_cvt_pk_bf16_f32 v10, v10, v11
	v_cvt_pk_bf16_f32 v11, v20, v21
	global_store_dwordx4 v[16:17], v[8:11], off offset:256
	s_nop 0
	s_andn2_b64 vcc, exec, s[2:3]
	s_nop 0
	v_fmamk_f32 v8, v237, 0x3a000000, v164
	v_mul_f32_e32 v9, 0x4b800000, v8
	v_cmp_gt_f32_e64 s[0:1], s64, v8
	s_nop 1
	v_cndmask_b32_e64 v8, v8, v9, s[0:1]
	v_rsq_f32_e32 v10, v8
	v_lshl_add_u64 v[8:9], v[146:147], 0, s[42:43]
	v_mul_f32_e32 v11, 0x45800000, v10
	v_cndmask_b32_e64 v10, v10, v11, s[0:1]
	v_pk_mul_f32 v[6:7], v[6:7], v[10:11] op_sel_hi:[1,0]
	v_pk_mul_f32 v[4:5], v[4:5], v[10:11] op_sel_hi:[1,0]
	v_pk_mul_f32 v[12:13], v[2:3], v[10:11] op_sel_hi:[1,0]
	v_pk_mul_f32 v[2:3], v[0:1], v[10:11] op_sel_hi:[1,0]
	v_cvt_pk_bf16_f32 v0, v4, v5
	v_cvt_pk_bf16_f32 v1, v6, v7
	v_cvt_pk_bf16_f32 v2, v2, v3
	v_cvt_pk_bf16_f32 v3, v12, v13
	s_mov_b64 s[0:1], -1
	global_store_dwordx4 v[8:9], v[0:3], off offset:256
	s_cbranch_vccnz .LBB0_1292
	s_andn2_b64 vcc, exec, s[12:13]
	s_cbranch_vccnz .LBB0_1291
	s_barrier
	s_branch .LBB0_1291

; __device__ __forceinline__ unsigned pk2(float lo, float hi) { f32x2_t v = {lo, hi}; bf16x2_t b = __builtin_convertvector(v, bf16x2_t); return __builtin_bit_cast(unsigned, b); }
; __device__ __forceinline__ float xor16_sum(float v) { float a = v, b = v; swap16(a, b); return a + b; }
; __device__ __forceinline__ float xor32_sum(float v) { float a = v, b = v; swap32(a, b); return a + b; }
;     __device__ __forceinline__ void operator()(const f32x4 (&acc)[2][2][4][2], const Unit& u, int wr, int wc, int fr, int fq) const {
;     ...
;         for (int ai = 0; ai < 2; ++ai)
; #pragma unroll
;             for (int m = 0; m < 4; ++m) {
;                 const int row = row0 + ai * HALF + m * 16; float sq = 0.f;
; #pragma unroll
;                 for (int bj = 0; bj < 2; ++bj)
; #pragma unroll
;                     for (int n = 0; n < 2; ++n) {
;                         const size_t idx = (size_t)row * ldc + u.pn * BM + bj * HALF + wc * 32 + 8 * fq + 4 * n;
;                         const f32x4 b = *(const f32x4*)(base + idx);
;                         const f32x4 v = b + acc[ai][bj][m][n] * alpha;
;                         *(f32x4*)(out + idx) = v;
;                         if (NORM) { u32x2 w; w.x = pk2(v[0], v[1]); w.y = pk2(v[2], v[3]); *(u32x2*)(xb + idx) = w; sq += (v[0] * v[0] + v[1] * v[1]) + (v[2] * v[2] + v[3] * v[3]); }
;                     }
;                 if (NORM) { sq = xor16_sum(sq); sq = xor32_sum(sq); if (fq == 0) __hip_atomic_fetch_add(ss + row, sq, __ATOMIC_RELAXED, __HIP_MEMORY_SCOPE_AGENT); }
.LBB0_1605:
	v_lshl_add_u32 v148, s12, 8, v137
	s_lshl_b32 s12, s28, 8
	s_ashr_i32 s13, s12, 31
	v_ashrrev_i32_e32 v149, 31, v148
	v_mov_b32_e32 v147, s13
	v_or_b32_e32 v146, s12, v136
	v_lshlrev_b64 v[154:155], 11, v[148:149]
	v_lshl_add_u64 v[158:159], v[154:155], 0, v[146:147]
	v_lshl_add_u64 v[160:161], v[158:159], 2, s[30:31]
	v_mov_b32_e32 v232, v160
	v_mov_b32_e32 v233, v161
	v_mov_b32_e32 v231, 0
	v_mov_b32_e32 v230, 0x0
	v_lshl_add_u64 v[228:229], v[232:233], 0, v[230:231]
	global_load_dwordx4 v[164:167], v[228:229], off
	global_load_dwordx4 v[168:171], v[228:229], off offset:16
	global_load_dwordx4 v[172:175], v[228:229], off offset:512
	global_load_dwordx4 v[176:179], v[228:229], off offset:528
	v_mov_b32_e32 v230, 0x20000
	v_lshl_add_u64 v[228:229], v[232:233], 0, v[230:231]
	global_load_dwordx4 v[180:183], v[228:229], off
	global_load_dwordx4 v[188:191], v[228:229], off offset:16
	global_load_dwordx4 v[192:195], v[228:229], off offset:512
	global_load_dwordx4 v[196:199], v[228:229], off offset:528
	v_mov_b32_e32 v230, 0x40000
	v_lshl_add_u64 v[228:229], v[232:233], 0, v[230:231]
	global_load_dwordx4 v[200:203], v[228:229], off
	global_load_dwordx4 v[204:207], v[228:229], off offset:16
	global_load_dwordx4 v[208:211], v[228:229], off offset:512
	global_load_dwordx4 v[212:215], v[228:229], off offset:528
	v_mov_b32_e32 v230, 0x60000
	v_lshl_add_u64 v[228:229], v[232:233], 0, v[230:231]
	global_load_dwordx4 v[216:219], v[228:229], off
	global_load_dwordx4 v[220:223], v[228:229], off offset:16
	global_load_dwordx4 v[224:227], v[228:229], off offset:512
	global_load_dwordx4 v[234:237], v[228:229], off offset:528
	s_nop 0
	v_lshlrev_b64 v[158:159], 1, v[158:159]
	v_lshl_add_u64 v[162:163], s[40:41], 0, v[158:159]
	s_nop 0
	s_waitcnt vmcnt(12)
	v_pk_add_f32 v[126:127], v[126:127], v[166:167]
	v_pk_add_f32 v[124:125], v[124:125], v[164:165]
	v_cvt_pk_bf16_f32 v155, v126, v127
	v_cvt_pk_bf16_f32 v154, v124, v125
	global_store_dwordx4 v[160:161], v[124:127], off
	global_store_dwordx2 v[162:163], v[154:155], off
	s_nop 0
	v_or_b32_e32 v162, 8, v158
	v_mov_b32_e32 v163, v159
	v_lshl_add_u64 v[162:163], s[40:41], 0, v[162:163]
	v_mul_f32_e32 v125, v125, v125
	v_mul_f32_e32 v127, v127, v127
	v_fmac_f32_e32 v125, v124, v124
	v_fmac_f32_e32 v127, v126, v126
	v_add_f32_e32 v124, v125, v127
	s_nop 0
	v_pk_add_f32 v[122:123], v[122:123], v[170:171]
	v_pk_add_f32 v[120:121], v[120:121], v[168:169]
	v_cvt_pk_bf16_f32 v155, v122, v123
	v_cvt_pk_bf16_f32 v154, v120, v121
	global_store_dwordx4 v[160:161], v[120:123], off offset:16
	global_store_dwordx2 v[162:163], v[154:155], off
	s_nop 0
	v_or_b32_e32 v162, 0x100, v158
	v_mov_b32_e32 v163, v159
	v_lshl_add_u64 v[162:163], s[40:41], 0, v[162:163]
	v_mul_f32_e32 v121, v121, v121
	v_mul_f32_e32 v123, v123, v123
	v_fmac_f32_e32 v121, v120, v120
	v_fmac_f32_e32 v123, v122, v122
	v_add_f32_e32 v120, v121, v123
	v_add_f32_e32 v120, v124, v120
	v_or_b32_e32 v158, 0x108, v158
	v_lshl_add_u64 v[158:159], s[40:41], 0, v[158:159]
	s_nop 0
	v_pk_add_f32 v[118:119], v[118:119], v[174:175]
	v_pk_add_f32 v[116:117], v[116:117], v[172:173]
	v_cvt_pk_bf16_f32 v155, v118, v119
	v_cvt_pk_bf16_f32 v154, v116, v117
	global_store_dwordx4 v[160:161], v[116:119], off offset:512
	global_store_dwordx2 v[162:163], v[154:155], off
	s_nop 0
	v_mul_f32_e32 v117, v117, v117
	v_mul_f32_e32 v119, v119, v119
	v_fmac_f32_e32 v117, v116, v116
	v_fmac_f32_e32 v119, v118, v118
	v_add_f32_e32 v116, v117, v119
	v_add_f32_e32 v118, v120, v116
	s_nop 0
	v_pk_add_f32 v[114:115], v[114:115], v[178:179]
	v_pk_add_f32 v[112:113], v[112:113], v[176:177]
	v_mov_b32_e32 v230, 0x100000
	v_lshl_add_u64 v[228:229], v[232:233], 0, v[230:231]
	global_load_dwordx4 v[164:167], v[228:229], off
	global_load_dwordx4 v[168:171], v[228:229], off offset:16
	global_load_dwordx4 v[172:175], v[228:229], off offset:512
	global_load_dwordx4 v[176:179], v[228:229], off offset:528
	global_store_dwordx4 v[160:161], v[112:115], off offset:528
	v_cvt_pk_bf16_f32 v116, v112, v113
	v_cvt_pk_bf16_f32 v117, v114, v115
	v_mul_f32_e32 v113, v113, v113
	v_mul_f32_e32 v115, v115, v115
	v_fmac_f32_e32 v113, v112, v112
	v_fmac_f32_e32 v115, v114, v114
	v_add_f32_e32 v112, v113, v115
	v_add_f32_e32 v112, v118, v112
	v_mov_b32_e32 v113, v112
	s_nop 1
	v_permlane16_swap_b32 v113, v112
	global_store_dwordx2 v[158:159], v[116:117], off
	v_add_f32_e32 v112, v113, v112
	v_mov_b32_e32 v113, v112
	s_nop 1
	v_permlane32_swap_b32 v113, v112
	s_and_saveexec_b64 s[12:13], s[2:3]
	s_cbranch_execz .LBB0_1607
	v_lshl_add_u64 v[114:115], v[148:149], 2, s[6:7]
	v_add_f32_e32 v112, v113, v112
	global_atomic_add_f32 v[114:115], v112, off
; __device__ __forceinline__ unsigned pk2(float lo, float hi) { f32x2_t v = {lo, hi}; bf16x2_t b = __builtin_convertvector(v, bf16x2_t); return __builtin_bit_cast(unsigned, b); }
; __device__ __forceinline__ float xor16_sum(float v) { float a = v, b = v; swap16(a, b); return a + b; }
; __device__ __forceinline__ float xor32_sum(float v) { float a = v, b = v; swap32(a, b); return a + b; }
;     __device__ __forceinline__ void operator()(const f32x4 (&acc)[2][2][4][2], const Unit& u, int wr, int wc, int fr, int fq) const {
;     ...
;         for (int ai = 0; ai < 2; ++ai)
; #pragma unroll
;             for (int m = 0; m < 4; ++m) {
;                 const int row = row0 + ai * HALF + m * 16; float sq = 0.f;
; #pragma unroll
;                 for (int bj = 0; bj < 2; ++bj)
; #pragma unroll
;                     for (int n = 0; n < 2; ++n) {
;                         const size_t idx = (size_t)row * ldc + u.pn * BM + bj * HALF + wc * 32 + 8 * fq + 4 * n;
;                         const f32x4 b = *(const f32x4*)(base + idx);
;                         const f32x4 v = b + acc[ai][bj][m][n] * alpha;
;                         *(f32x4*)(out + idx) = v;
;                         if (NORM) { u32x2 w; w.x = pk2(v[0], v[1]); w.y = pk2(v[2], v[3]); *(u32x2*)(xb + idx) = w; sq += (v[0] * v[0] + v[1] * v[1]) + (v[2] * v[2] + v[3] * v[3]); }
;                     }
;                 if (NORM) { sq = xor16_sum(sq); sq = xor32_sum(sq); if (fq == 0) __hip_atomic_fetch_add(ss + row, sq, __ATOMIC_RELAXED, __HIP_MEMORY_SCOPE_AGENT); }
.LBB0_1607:
	s_or_b64 exec, exec, s[12:13]
	v_or_b32_e32 v112, 16, v148
	v_ashrrev_i32_e32 v113, 31, v112
	v_lshlrev_b64 v[114:115], 11, v[112:113]
	v_lshl_add_u64 v[118:119], v[114:115], 0, v[146:147]
	v_lshl_add_u64 v[120:121], v[118:119], 2, s[30:31]
	s_nop 0
	v_lshlrev_b64 v[118:119], 1, v[118:119]
	v_lshl_add_u64 v[122:123], s[40:41], 0, v[118:119]
	s_nop 0
	s_waitcnt vmcnt(20)
	v_pk_add_f32 v[110:111], v[110:111], v[182:183]
	v_pk_add_f32 v[108:109], v[108:109], v[180:181]
	v_cvt_pk_bf16_f32 v115, v110, v111
	v_cvt_pk_bf16_f32 v114, v108, v109
	global_store_dwordx4 v[120:121], v[108:111], off
	global_store_dwordx2 v[122:123], v[114:115], off
	s_nop 0
	v_or_b32_e32 v122, 8, v118
	v_mov_b32_e32 v123, v119
	v_lshl_add_u64 v[122:123], s[40:41], 0, v[122:123]
	v_mul_f32_e32 v109, v109, v109
	v_mul_f32_e32 v111, v111, v111
	v_fmac_f32_e32 v109, v108, v108
	v_fmac_f32_e32 v111, v110, v110
	v_add_f32_e32 v108, v109, v111
	s_nop 0
	v_pk_add_f32 v[106:107], v[106:107], v[190:191]
	v_pk_add_f32 v[104:105], v[104:105], v[188:189]
	v_cvt_pk_bf16_f32 v115, v106, v107
	v_cvt_pk_bf16_f32 v114, v104, v105
	global_store_dwordx4 v[120:121], v[104:107], off offset:16
	global_store_dwordx2 v[122:123], v[114:115], off
	s_nop 0
	v_or_b32_e32 v122, 0x100, v118
	v_mov_b32_e32 v123, v119
	v_lshl_add_u64 v[122:123], s[40:41], 0, v[122:123]
	v_mul_f32_e32 v105, v105, v105
	v_mul_f32_e32 v107, v107, v107
	v_fmac_f32_e32 v105, v104, v104
	v_fmac_f32_e32 v107, v106, v106
	v_add_f32_e32 v104, v105, v107
	v_add_f32_e32 v104, v108, v104
	v_or_b32_e32 v118, 0x108, v118
	v_lshl_add_u64 v[118:119], s[40:41], 0, v[118:119]
	s_nop 0
	v_pk_add_f32 v[102:103], v[102:103], v[194:195]
	v_pk_add_f32 v[100:101], v[100:101], v[192:193]
	v_cvt_pk_bf16_f32 v115, v102, v103
	v_cvt_pk_bf16_f32 v114, v100, v101
	global_store_dwordx4 v[120:121], v[100:103], off offset:512
	global_store_dwordx2 v[122:123], v[114:115], off
	s_nop 0
	v_mul_f32_e32 v101, v101, v101
	v_mul_f32_e32 v103, v103, v103
	v_fmac_f32_e32 v101, v100, v100
	v_fmac_f32_e32 v103, v102, v102
	v_add_f32_e32 v100, v101, v103
	v_add_f32_e32 v102, v104, v100
	s_nop 0
	v_pk_add_f32 v[98:99], v[98:99], v[198:199]
	v_pk_add_f32 v[96:97], v[96:97], v[196:197]
	v_mov_b32_e32 v230, 0x120000
	v_lshl_add_u64 v[228:229], v[232:233], 0, v[230:231]
	global_load_dwordx4 v[180:183], v[228:229], off
	global_load_dwordx4 v[188:191], v[228:229], off offset:16
	global_load_dwordx4 v[192:195], v[228:229], off offset:512
	global_load_dwordx4 v[196:199], v[228:229], off offset:528
	global_store_dwordx4 v[120:121], v[96:99], off offset:528
	v_cvt_pk_bf16_f32 v100, v96, v97
	v_cvt_pk_bf16_f32 v101, v98, v99
	v_mul_f32_e32 v97, v97, v97
	v_mul_f32_e32 v99, v99, v99
	v_fmac_f32_e32 v97, v96, v96
	v_fmac_f32_e32 v99, v98, v98
	v_add_f32_e32 v96, v97, v99
	v_add_f32_e32 v96, v102, v96
	v_mov_b32_e32 v97, v96
	s_nop 1
	v_permlane16_swap_b32 v96, v97
	global_store_dwordx2 v[118:119], v[100:101], off
	v_add_f32_e32 v96, v96, v97
	v_mov_b32_e32 v97, v96
	s_nop 1
	v_permlane32_swap_b32 v96, v97
	s_and_saveexec_b64 s[12:13], s[2:3]
	s_cbranch_execz .LBB0_1609
	v_lshl_add_u64 v[98:99], v[112:113], 2, s[6:7]
	v_add_f32_e32 v96, v96, v97
	global_atomic_add_f32 v[98:99], v96, off
.LBB0_1609:
	s_or_b64 exec, exec, s[12:13]
	v_or_b32_e32 v96, 32, v148
	v_ashrrev_i32_e32 v97, 31, v96
	v_lshlrev_b64 v[98:99], 11, v[96:97]
	v_lshl_add_u64 v[102:103], v[98:99], 0, v[146:147]
	v_lshl_add_u64 v[104:105], v[102:103], 2, s[30:31]
	s_nop 0
	v_lshlrev_b64 v[102:103], 1, v[102:103]
	v_lshl_add_u64 v[106:107], s[40:41], 0, v[102:103]
	s_nop 0
	s_waitcnt vmcnt(28)
	v_pk_add_f32 v[94:95], v[94:95], v[202:203]
	v_pk_add_f32 v[92:93], v[92:93], v[200:201]
	v_cvt_pk_bf16_f32 v99, v94, v95
	v_cvt_pk_bf16_f32 v98, v92, v93
	global_store_dwordx4 v[104:105], v[92:95], off
	global_store_dwordx2 v[106:107], v[98:99], off
	s_nop 0
	v_or_b32_e32 v106, 8, v102
	v_mov_b32_e32 v107, v103
	v_lshl_add_u64 v[106:107], s[40:41], 0, v[106:107]
	v_mul_f32_e32 v93, v93, v93
	v_mul_f32_e32 v95, v95, v95
	v_fmac_f32_e32 v93, v92, v92
	v_fmac_f32_e32 v95, v94, v94
	v_add_f32_e32 v92, v93, v95
	s_nop 0
	v_pk_add_f32 v[90:91], v[90:91], v[206:207]
	v_pk_add_f32 v[88:89], v[88:89], v[204:205]
	v_cvt_pk_bf16_f32 v99, v90, v91
	v_cvt_pk_bf16_f32 v98, v88, v89
	global_store_dwordx4 v[104:105], v[88:91], off offset:16
	global_store_dwordx2 v[106:107], v[98:99], off
	s_nop 0
	v_or_b32_e32 v106, 0x100, v102
	v_mov_b32_e32 v107, v103
	v_lshl_add_u64 v[106:107], s[40:41], 0, v[106:107]
	v_mul_f32_e32 v89, v89, v89
	v_mul_f32_e32 v91, v91, v91
	v_fmac_f32_e32 v89, v88, v88
	v_fmac_f32_e32 v91, v90, v90
	v_add_f32_e32 v88, v89, v91
	v_add_f32_e32 v88, v92, v88
	v_or_b32_e32 v102, 0x108, v102
	v_lshl_add_u64 v[102:103], s[40:41], 0, v[102:103]
	s_nop 0
	v_pk_add_f32 v[86:87], v[86:87], v[210:211]
	v_pk_add_f32 v[84:85], v[84:85], v[208:209]
	v_cvt_pk_bf16_f32 v99, v86, v87
	v_cvt_pk_bf16_f32 v98, v84, v85
	global_store_dwordx4 v[104:105], v[84:87], off offset:512
	global_store_dwordx2 v[106:107], v[98:99], off
	s_nop 0
	v_mul_f32_e32 v85, v85, v85
	v_mul_f32_e32 v87, v87, v87
	v_fmac_f32_e32 v85, v84, v84
	v_fmac_f32_e32 v87, v86, v86
	v_add_f32_e32 v84, v85, v87
	v_add_f32_e32 v86, v88, v84
	s_nop 0
	v_pk_add_f32 v[82:83], v[82:83], v[214:215]
	v_pk_add_f32 v[80:81], v[80:81], v[212:213]
	v_mov_b32_e32 v230, 0x140000
	v_lshl_add_u64 v[228:229], v[232:233], 0, v[230:231]
	global_load_dwordx4 v[200:203], v[228:229], off
	global_load_dwordx4 v[204:207], v[228:229], off offset:16
	global_load_dwordx4 v[208:211], v[228:229], off offset:512
	global_load_dwordx4 v[212:215], v[228:229], off offset:528
	global_store_dwordx4 v[104:105], v[80:83], off offset:528
	v_cvt_pk_bf16_f32 v84, v80, v81
	v_cvt_pk_bf16_f32 v85, v82, v83
	v_mul_f32_e32 v81, v81, v81
	v_mul_f32_e32 v83, v83, v83
	v_fmac_f32_e32 v81, v80, v80
	v_fmac_f32_e32 v83, v82, v82
	v_add_f32_e32 v80, v81, v83
	v_add_f32_e32 v80, v86, v80
	v_mov_b32_e32 v81, v80
	s_nop 1
	v_permlane16_swap_b32 v80, v81
	global_store_dwordx2 v[102:103], v[84:85], off
	v_add_f32_e32 v80, v80, v81
	v_mov_b32_e32 v81, v80
	s_nop 1
	v_permlane32_swap_b32 v80, v81
	s_and_saveexec_b64 s[12:13], s[2:3]
	s_cbranch_execz .LBB0_1611
	v_lshl_add_u64 v[82:83], v[96:97], 2, s[6:7]
	v_add_f32_e32 v80, v80, v81
	global_atomic_add_f32 v[82:83], v80, off
; __device__ __forceinline__ unsigned pk2(float lo, float hi) { f32x2_t v = {lo, hi}; bf16x2_t b = __builtin_convertvector(v, bf16x2_t); return __builtin_bit_cast(unsigned, b); }
; __device__ __forceinline__ float xor16_sum(float v) { float a = v, b = v; swap16(a, b); return a + b; }
; __device__ __forceinline__ float xor32_sum(float v) { float a = v, b = v; swap32(a, b); return a + b; }
;     __device__ __forceinline__ void operator()(const f32x4 (&acc)[2][2][4][2], const Unit& u, int wr, int wc, int fr, int fq) const {
;     ...
;         for (int ai = 0; ai < 2; ++ai)
; #pragma unroll
;             for (int m = 0; m < 4; ++m) {
;                 const int row = row0 + ai * HALF + m * 16; float sq = 0.f;
; #pragma unroll
;                 for (int bj = 0; bj < 2; ++bj)
; #pragma unroll
;                     for (int n = 0; n < 2; ++n) {
;                         const size_t idx = (size_t)row * ldc + u.pn * BM + bj * HALF + wc * 32 + 8 * fq + 4 * n;
;                         const f32x4 b = *(const f32x4*)(base + idx);
;                         const f32x4 v = b + acc[ai][bj][m][n] * alpha;
;                         *(f32x4*)(out + idx) = v;
;                         if (NORM) { u32x2 w; w.x = pk2(v[0], v[1]); w.y = pk2(v[2], v[3]); *(u32x2*)(xb + idx) = w; sq += (v[0] * v[0] + v[1] * v[1]) + (v[2] * v[2] + v[3] * v[3]); }
;                     }
;                 if (NORM) { sq = xor16_sum(sq); sq = xor32_sum(sq); if (fq == 0) __hip_atomic_fetch_add(ss + row, sq, __ATOMIC_RELAXED, __HIP_MEMORY_SCOPE_AGENT); }
.LBB0_1611:
	s_or_b64 exec, exec, s[12:13]
	v_or_b32_e32 v80, 48, v148
	v_ashrrev_i32_e32 v81, 31, v80
	v_lshlrev_b64 v[82:83], 11, v[80:81]
	v_lshl_add_u64 v[86:87], v[82:83], 0, v[146:147]
	v_lshl_add_u64 v[88:89], v[86:87], 2, s[30:31]
	s_nop 0
	v_lshlrev_b64 v[86:87], 1, v[86:87]
	v_lshl_add_u64 v[90:91], s[40:41], 0, v[86:87]
	s_nop 0
	s_waitcnt vmcnt(36)
	v_pk_add_f32 v[78:79], v[78:79], v[218:219]
	v_pk_add_f32 v[76:77], v[76:77], v[216:217]
	v_cvt_pk_bf16_f32 v83, v78, v79
	v_cvt_pk_bf16_f32 v82, v76, v77
	global_store_dwordx4 v[88:89], v[76:79], off
	global_store_dwordx2 v[90:91], v[82:83], off
	s_nop 0
	v_or_b32_e32 v90, 8, v86
	v_mov_b32_e32 v91, v87
	v_lshl_add_u64 v[90:91], s[40:41], 0, v[90:91]
	v_mul_f32_e32 v77, v77, v77
	v_mul_f32_e32 v79, v79, v79
	v_fmac_f32_e32 v77, v76, v76
	v_fmac_f32_e32 v79, v78, v78
	v_add_f32_e32 v76, v77, v79
	s_nop 0
	v_pk_add_f32 v[74:75], v[74:75], v[222:223]
	v_pk_add_f32 v[72:73], v[72:73], v[220:221]
	v_cvt_pk_bf16_f32 v83, v74, v75
	v_cvt_pk_bf16_f32 v82, v72, v73
	global_store_dwordx4 v[88:89], v[72:75], off offset:16
	global_store_dwordx2 v[90:91], v[82:83], off
	s_nop 0
	v_or_b32_e32 v90, 0x100, v86
	v_mov_b32_e32 v91, v87
	v_lshl_add_u64 v[90:91], s[40:41], 0, v[90:91]
	v_mul_f32_e32 v73, v73, v73
	v_mul_f32_e32 v75, v75, v75
	v_fmac_f32_e32 v73, v72, v72
	v_fmac_f32_e32 v75, v74, v74
	v_add_f32_e32 v72, v73, v75
	v_add_f32_e32 v72, v76, v72
	v_or_b32_e32 v86, 0x108, v86
	v_lshl_add_u64 v[86:87], s[40:41], 0, v[86:87]
	s_nop 0
	v_pk_add_f32 v[70:71], v[70:71], v[226:227]
	v_pk_add_f32 v[68:69], v[68:69], v[224:225]
	v_cvt_pk_bf16_f32 v83, v70, v71
	v_cvt_pk_bf16_f32 v82, v68, v69
	global_store_dwordx4 v[88:89], v[68:71], off offset:512
	global_store_dwordx2 v[90:91], v[82:83], off
	s_nop 0
	v_mul_f32_e32 v69, v69, v69
	v_mul_f32_e32 v71, v71, v71
	v_fmac_f32_e32 v69, v68, v68
	v_fmac_f32_e32 v71, v70, v70
	v_add_f32_e32 v68, v69, v71
	v_add_f32_e32 v70, v72, v68
	s_nop 0
	v_pk_add_f32 v[66:67], v[66:67], v[236:237]
	v_pk_add_f32 v[64:65], v[64:65], v[234:235]
	v_mov_b32_e32 v230, 0x160000
	v_lshl_add_u64 v[228:229], v[232:233], 0, v[230:231]
	global_load_dwordx4 v[216:219], v[228:229], off
	global_load_dwordx4 v[220:223], v[228:229], off offset:16
	global_load_dwordx4 v[224:227], v[228:229], off offset:512
	global_load_dwordx4 v[234:237], v[228:229], off offset:528
	global_store_dwordx4 v[88:89], v[64:67], off offset:528
	v_cvt_pk_bf16_f32 v68, v64, v65
	v_cvt_pk_bf16_f32 v69, v66, v67
	v_mul_f32_e32 v65, v65, v65
	v_mul_f32_e32 v67, v67, v67
	v_fmac_f32_e32 v65, v64, v64
	v_fmac_f32_e32 v67, v66, v66
	v_add_f32_e32 v64, v65, v67
	v_add_f32_e32 v64, v70, v64
	v_mov_b32_e32 v65, v64
	s_nop 1
	v_permlane16_swap_b32 v64, v65
	global_store_dwordx2 v[86:87], v[68:69], off
	v_add_f32_e32 v64, v64, v65
	v_mov_b32_e32 v65, v64
	s_nop 1
	v_permlane32_swap_b32 v64, v65
	s_and_saveexec_b64 s[12:13], s[2:3]
	s_cbranch_execz .LBB0_1613
	v_lshl_add_u64 v[66:67], v[80:81], 2, s[6:7]
	v_add_f32_e32 v64, v64, v65
	global_atomic_add_f32 v[66:67], v64, off
.LBB0_1613:
	s_or_b64 exec, exec, s[12:13]
	v_add_u32_e32 v64, 0x80, v148
	v_ashrrev_i32_e32 v65, 31, v64
	v_lshlrev_b64 v[66:67], 11, v[64:65]
	v_lshl_add_u64 v[70:71], v[66:67], 0, v[146:147]
	v_lshl_add_u64 v[72:73], v[70:71], 2, s[30:31]
	s_nop 0
	v_lshlrev_b64 v[70:71], 1, v[70:71]
	v_lshl_add_u64 v[74:75], s[40:41], 0, v[70:71]
	s_nop 0
	s_waitcnt vmcnt(38)
	v_pk_add_f32 v[62:63], v[62:63], v[166:167]
	v_pk_add_f32 v[60:61], v[60:61], v[164:165]
	v_cvt_pk_bf16_f32 v67, v62, v63
	v_cvt_pk_bf16_f32 v66, v60, v61
	global_store_dwordx4 v[72:73], v[60:63], off
	global_store_dwordx2 v[74:75], v[66:67], off
	s_nop 0
	v_or_b32_e32 v74, 8, v70
	v_mov_b32_e32 v75, v71
	v_lshl_add_u64 v[74:75], s[40:41], 0, v[74:75]
	v_mul_f32_e32 v61, v61, v61
	v_mul_f32_e32 v63, v63, v63
	v_fmac_f32_e32 v61, v60, v60
	v_fmac_f32_e32 v63, v62, v62
	v_add_f32_e32 v60, v61, v63
	s_nop 0
	v_pk_add_f32 v[58:59], v[58:59], v[170:171]
	v_pk_add_f32 v[56:57], v[56:57], v[168:169]
	v_cvt_pk_bf16_f32 v67, v58, v59
	v_cvt_pk_bf16_f32 v66, v56, v57
	global_store_dwordx4 v[72:73], v[56:59], off offset:16
	global_store_dwordx2 v[74:75], v[66:67], off
	s_nop 0
	v_or_b32_e32 v74, 0x100, v70
	v_mov_b32_e32 v75, v71
	v_lshl_add_u64 v[74:75], s[40:41], 0, v[74:75]
	v_mul_f32_e32 v57, v57, v57
	v_mul_f32_e32 v59, v59, v59
	v_fmac_f32_e32 v57, v56, v56
	v_fmac_f32_e32 v59, v58, v58
	v_add_f32_e32 v56, v57, v59
	v_add_f32_e32 v56, v60, v56
	v_or_b32_e32 v70, 0x108, v70
	v_lshl_add_u64 v[70:71], s[40:41], 0, v[70:71]
	s_nop 0
	v_pk_add_f32 v[54:55], v[54:55], v[174:175]
	v_pk_add_f32 v[52:53], v[52:53], v[172:173]
	v_cvt_pk_bf16_f32 v67, v54, v55
	v_cvt_pk_bf16_f32 v66, v52, v53
	global_store_dwordx4 v[72:73], v[52:55], off offset:512
	global_store_dwordx2 v[74:75], v[66:67], off
	s_nop 0
	v_mul_f32_e32 v53, v53, v53
	v_mul_f32_e32 v55, v55, v55
	v_fmac_f32_e32 v53, v52, v52
	v_fmac_f32_e32 v55, v54, v54
	v_add_f32_e32 v52, v53, v55
	v_add_f32_e32 v54, v56, v52
	s_nop 0
	v_pk_add_f32 v[50:51], v[50:51], v[178:179]
	v_pk_add_f32 v[48:49], v[48:49], v[176:177]
	global_store_dwordx4 v[72:73], v[48:51], off offset:528
	v_cvt_pk_bf16_f32 v52, v48, v49
	v_cvt_pk_bf16_f32 v53, v50, v51
	v_mul_f32_e32 v49, v49, v49
	v_mul_f32_e32 v51, v51, v51
	v_fmac_f32_e32 v49, v48, v48
	v_fmac_f32_e32 v51, v50, v50
	v_add_f32_e32 v48, v49, v51
	v_add_f32_e32 v48, v54, v48
	v_mov_b32_e32 v49, v48
	s_nop 1
	v_permlane16_swap_b32 v48, v49
	global_store_dwordx2 v[70:71], v[52:53], off
	v_add_f32_e32 v48, v48, v49
	v_mov_b32_e32 v49, v48
	s_nop 1
	v_permlane32_swap_b32 v48, v49
	s_and_saveexec_b64 s[12:13], s[2:3]
	s_cbranch_execz .LBB0_1615
	v_lshl_add_u64 v[50:51], v[64:65], 2, s[6:7]
	v_add_f32_e32 v48, v48, v49
	global_atomic_add_f32 v[50:51], v48, off
; __device__ __forceinline__ unsigned pk2(float lo, float hi) { f32x2_t v = {lo, hi}; bf16x2_t b = __builtin_convertvector(v, bf16x2_t); return __builtin_bit_cast(unsigned, b); }
; __device__ __forceinline__ float xor16_sum(float v) { float a = v, b = v; swap16(a, b); return a + b; }
; __device__ __forceinline__ float xor32_sum(float v) { float a = v, b = v; swap32(a, b); return a + b; }
;     __device__ __forceinline__ void operator()(const f32x4 (&acc)[2][2][4][2], const Unit& u, int wr, int wc, int fr, int fq) const {
;     ...
;         for (int ai = 0; ai < 2; ++ai)
; #pragma unroll
;             for (int m = 0; m < 4; ++m) {
;                 const int row = row0 + ai * HALF + m * 16; float sq = 0.f;
; #pragma unroll
;                 for (int bj = 0; bj < 2; ++bj)
; #pragma unroll
;                     for (int n = 0; n < 2; ++n) {
;                         const size_t idx = (size_t)row * ldc + u.pn * BM + bj * HALF + wc * 32 + 8 * fq + 4 * n;
;                         const f32x4 b = *(const f32x4*)(base + idx);
;                         const f32x4 v = b + acc[ai][bj][m][n] * alpha;
;                         *(f32x4*)(out + idx) = v;
;                         if (NORM) { u32x2 w; w.x = pk2(v[0], v[1]); w.y = pk2(v[2], v[3]); *(u32x2*)(xb + idx) = w; sq += (v[0] * v[0] + v[1] * v[1]) + (v[2] * v[2] + v[3] * v[3]); }
;                     }
;                 if (NORM) { sq = xor16_sum(sq); sq = xor32_sum(sq); if (fq == 0) __hip_atomic_fetch_add(ss + row, sq, __ATOMIC_RELAXED, __HIP_MEMORY_SCOPE_AGENT); }
.LBB0_1615:
	s_or_b64 exec, exec, s[12:13]
	v_add_u32_e32 v48, 0x90, v148
	v_ashrrev_i32_e32 v49, 31, v48
	v_lshlrev_b64 v[50:51], 11, v[48:49]
	v_lshl_add_u64 v[54:55], v[50:51], 0, v[146:147]
	v_lshl_add_u64 v[56:57], v[54:55], 2, s[30:31]
	s_nop 0
	v_lshlrev_b64 v[54:55], 1, v[54:55]
	v_lshl_add_u64 v[58:59], s[40:41], 0, v[54:55]
	s_nop 0
	s_waitcnt vmcnt(34)
	v_pk_add_f32 v[46:47], v[46:47], v[182:183]
	v_pk_add_f32 v[44:45], v[44:45], v[180:181]
	v_cvt_pk_bf16_f32 v51, v46, v47
	v_cvt_pk_bf16_f32 v50, v44, v45
	global_store_dwordx4 v[56:57], v[44:47], off
	global_store_dwordx2 v[58:59], v[50:51], off
	s_nop 0
	v_or_b32_e32 v58, 8, v54
	v_mov_b32_e32 v59, v55
	v_lshl_add_u64 v[58:59], s[40:41], 0, v[58:59]
	v_mul_f32_e32 v45, v45, v45
	v_mul_f32_e32 v47, v47, v47
	v_fmac_f32_e32 v45, v44, v44
	v_fmac_f32_e32 v47, v46, v46
	v_add_f32_e32 v44, v45, v47
	s_nop 0
	v_pk_add_f32 v[42:43], v[42:43], v[190:191]
	v_pk_add_f32 v[40:41], v[40:41], v[188:189]
	v_cvt_pk_bf16_f32 v51, v42, v43
	v_cvt_pk_bf16_f32 v50, v40, v41
	global_store_dwordx4 v[56:57], v[40:43], off offset:16
	global_store_dwordx2 v[58:59], v[50:51], off
	s_nop 0
	v_or_b32_e32 v58, 0x100, v54
	v_mov_b32_e32 v59, v55
	v_lshl_add_u64 v[58:59], s[40:41], 0, v[58:59]
	v_mul_f32_e32 v41, v41, v41
	v_mul_f32_e32 v43, v43, v43
	v_fmac_f32_e32 v41, v40, v40
	v_fmac_f32_e32 v43, v42, v42
	v_add_f32_e32 v40, v41, v43
	v_add_f32_e32 v40, v44, v40
	v_or_b32_e32 v54, 0x108, v54
	v_lshl_add_u64 v[54:55], s[40:41], 0, v[54:55]
	s_nop 0
	v_pk_add_f32 v[38:39], v[38:39], v[194:195]
	v_pk_add_f32 v[36:37], v[36:37], v[192:193]
	v_cvt_pk_bf16_f32 v51, v38, v39
	v_cvt_pk_bf16_f32 v50, v36, v37
	global_store_dwordx4 v[56:57], v[36:39], off offset:512
	global_store_dwordx2 v[58:59], v[50:51], off
	s_nop 0
	v_mul_f32_e32 v37, v37, v37
	v_mul_f32_e32 v39, v39, v39
	v_fmac_f32_e32 v37, v36, v36
	v_fmac_f32_e32 v39, v38, v38
	v_add_f32_e32 v36, v37, v39
	v_add_f32_e32 v38, v40, v36
	s_nop 0
	v_pk_add_f32 v[34:35], v[34:35], v[198:199]
	v_pk_add_f32 v[32:33], v[32:33], v[196:197]
	global_store_dwordx4 v[56:57], v[32:35], off offset:528
	v_cvt_pk_bf16_f32 v36, v32, v33
	v_cvt_pk_bf16_f32 v37, v34, v35
	v_mul_f32_e32 v33, v33, v33
	v_mul_f32_e32 v35, v35, v35
	v_fmac_f32_e32 v33, v32, v32
	v_fmac_f32_e32 v35, v34, v34
	v_add_f32_e32 v32, v33, v35
	v_add_f32_e32 v32, v38, v32
	v_mov_b32_e32 v33, v32
	s_nop 1
	v_permlane16_swap_b32 v32, v33
	global_store_dwordx2 v[54:55], v[36:37], off
	v_add_f32_e32 v32, v32, v33
	v_mov_b32_e32 v33, v32
	s_nop 1
	v_permlane32_swap_b32 v32, v33
	s_and_saveexec_b64 s[12:13], s[2:3]
	s_cbranch_execz .LBB0_1617
	v_lshl_add_u64 v[34:35], v[48:49], 2, s[6:7]
	v_add_f32_e32 v32, v32, v33
	global_atomic_add_f32 v[34:35], v32, off
; __device__ __forceinline__ unsigned pk2(float lo, float hi) { f32x2_t v = {lo, hi}; bf16x2_t b = __builtin_convertvector(v, bf16x2_t); return __builtin_bit_cast(unsigned, b); }
; __device__ __forceinline__ float xor16_sum(float v) { float a = v, b = v; swap16(a, b); return a + b; }
; __device__ __forceinline__ float xor32_sum(float v) { float a = v, b = v; swap32(a, b); return a + b; }
;     __device__ __forceinline__ void operator()(const f32x4 (&acc)[2][2][4][2], const Unit& u, int wr, int wc, int fr, int fq) const {
;     ...
;         for (int ai = 0; ai < 2; ++ai)
; #pragma unroll
;             for (int m = 0; m < 4; ++m) {
;                 const int row = row0 + ai * HALF + m * 16; float sq = 0.f;
; #pragma unroll
;                 for (int bj = 0; bj < 2; ++bj)
; #pragma unroll
;                     for (int n = 0; n < 2; ++n) {
;                         const size_t idx = (size_t)row * ldc + u.pn * BM + bj * HALF + wc * 32 + 8 * fq + 4 * n;
;                         const f32x4 b = *(const f32x4*)(base + idx);
;                         const f32x4 v = b + acc[ai][bj][m][n] * alpha;
;                         *(f32x4*)(out + idx) = v;
;                         if (NORM) { u32x2 w; w.x = pk2(v[0], v[1]); w.y = pk2(v[2], v[3]); *(u32x2*)(xb + idx) = w; sq += (v[0] * v[0] + v[1] * v[1]) + (v[2] * v[2] + v[3] * v[3]); }
;                     }
;                 if (NORM) { sq = xor16_sum(sq); sq = xor32_sum(sq); if (fq == 0) __hip_atomic_fetch_add(ss + row, sq, __ATOMIC_RELAXED, __HIP_MEMORY_SCOPE_AGENT); }
.LBB0_1617:
	s_or_b64 exec, exec, s[12:13]
	v_add_u32_e32 v32, 0xa0, v148
	v_ashrrev_i32_e32 v33, 31, v32
	v_lshlrev_b64 v[34:35], 11, v[32:33]
	v_lshl_add_u64 v[38:39], v[34:35], 0, v[146:147]
	v_lshl_add_u64 v[40:41], v[38:39], 2, s[30:31]
	s_nop 0
	v_lshlrev_b64 v[38:39], 1, v[38:39]
	v_lshl_add_u64 v[42:43], s[40:41], 0, v[38:39]
	s_nop 0
	s_waitcnt vmcnt(30)
	v_pk_add_f32 v[30:31], v[30:31], v[202:203]
	v_pk_add_f32 v[28:29], v[28:29], v[200:201]
	v_cvt_pk_bf16_f32 v35, v30, v31
	v_cvt_pk_bf16_f32 v34, v28, v29
	global_store_dwordx4 v[40:41], v[28:31], off
	global_store_dwordx2 v[42:43], v[34:35], off
	s_nop 0
	v_or_b32_e32 v42, 8, v38
	v_mov_b32_e32 v43, v39
	v_lshl_add_u64 v[42:43], s[40:41], 0, v[42:43]
	v_mul_f32_e32 v29, v29, v29
	v_mul_f32_e32 v31, v31, v31
	v_fmac_f32_e32 v29, v28, v28
	v_fmac_f32_e32 v31, v30, v30
	v_add_f32_e32 v28, v29, v31
	s_nop 0
	v_pk_add_f32 v[26:27], v[26:27], v[206:207]
	v_pk_add_f32 v[24:25], v[24:25], v[204:205]
	v_cvt_pk_bf16_f32 v35, v26, v27
	v_cvt_pk_bf16_f32 v34, v24, v25
	global_store_dwordx4 v[40:41], v[24:27], off offset:16
	global_store_dwordx2 v[42:43], v[34:35], off
	s_nop 0
	v_or_b32_e32 v42, 0x100, v38
	v_mov_b32_e32 v43, v39
	v_lshl_add_u64 v[42:43], s[40:41], 0, v[42:43]
	v_mul_f32_e32 v25, v25, v25
	v_mul_f32_e32 v27, v27, v27
	v_fmac_f32_e32 v25, v24, v24
	v_fmac_f32_e32 v27, v26, v26
	v_add_f32_e32 v24, v25, v27
	v_add_f32_e32 v24, v28, v24
	v_or_b32_e32 v38, 0x108, v38
	v_lshl_add_u64 v[38:39], s[40:41], 0, v[38:39]
	s_nop 0
	v_pk_add_f32 v[22:23], v[22:23], v[210:211]
	v_pk_add_f32 v[20:21], v[20:21], v[208:209]
	v_cvt_pk_bf16_f32 v35, v22, v23
	v_cvt_pk_bf16_f32 v34, v20, v21
	global_store_dwordx4 v[40:41], v[20:23], off offset:512
	global_store_dwordx2 v[42:43], v[34:35], off
	s_nop 0
	v_mul_f32_e32 v21, v21, v21
	v_mul_f32_e32 v23, v23, v23
	v_fmac_f32_e32 v21, v20, v20
	v_fmac_f32_e32 v23, v22, v22
	v_add_f32_e32 v20, v21, v23
	v_add_f32_e32 v22, v24, v20
	s_nop 0
	v_pk_add_f32 v[18:19], v[18:19], v[214:215]
	v_pk_add_f32 v[16:17], v[16:17], v[212:213]
	global_store_dwordx4 v[40:41], v[16:19], off offset:528
	v_cvt_pk_bf16_f32 v20, v16, v17
	v_cvt_pk_bf16_f32 v21, v18, v19
	v_mul_f32_e32 v17, v17, v17
	v_mul_f32_e32 v19, v19, v19
	v_fmac_f32_e32 v17, v16, v16
	v_fmac_f32_e32 v19, v18, v18
	v_add_f32_e32 v16, v17, v19
	v_add_f32_e32 v16, v22, v16
	v_mov_b32_e32 v17, v16
	s_nop 1
	v_permlane16_swap_b32 v16, v17
	global_store_dwordx2 v[38:39], v[20:21], off
	v_add_f32_e32 v16, v16, v17
	v_mov_b32_e32 v17, v16
	s_nop 1
	v_permlane32_swap_b32 v16, v17
	s_and_saveexec_b64 s[12:13], s[2:3]
	s_cbranch_execz .LBB0_1619
	v_lshl_add_u64 v[18:19], v[32:33], 2, s[6:7]
	v_add_f32_e32 v16, v16, v17
	global_atomic_add_f32 v[18:19], v16, off
.LBB0_1619:
	s_or_b64 exec, exec, s[12:13]
	v_add_u32_e32 v16, 0xb0, v148
	v_ashrrev_i32_e32 v17, 31, v16
	v_lshlrev_b64 v[18:19], 11, v[16:17]
	v_lshl_add_u64 v[22:23], v[18:19], 0, v[146:147]
	v_lshl_add_u64 v[24:25], v[22:23], 2, s[30:31]
	s_nop 0
	v_lshlrev_b64 v[22:23], 1, v[22:23]
	v_lshl_add_u64 v[26:27], s[40:41], 0, v[22:23]
	s_nop 0
	s_waitcnt vmcnt(26)
	v_pk_add_f32 v[14:15], v[14:15], v[218:219]
	v_pk_add_f32 v[12:13], v[12:13], v[216:217]
	v_cvt_pk_bf16_f32 v19, v14, v15
	v_cvt_pk_bf16_f32 v18, v12, v13
	global_store_dwordx4 v[24:25], v[12:15], off
	global_store_dwordx2 v[26:27], v[18:19], off
	s_nop 0
	v_or_b32_e32 v26, 8, v22
	v_mov_b32_e32 v27, v23
	v_lshl_add_u64 v[26:27], s[40:41], 0, v[26:27]
	v_mul_f32_e32 v13, v13, v13
	v_mul_f32_e32 v15, v15, v15
	v_fmac_f32_e32 v13, v12, v12
	v_fmac_f32_e32 v15, v14, v14
	v_add_f32_e32 v12, v13, v15
	s_nop 0
	v_pk_add_f32 v[10:11], v[10:11], v[222:223]
	v_pk_add_f32 v[8:9], v[8:9], v[220:221]
	v_cvt_pk_bf16_f32 v19, v10, v11
	v_cvt_pk_bf16_f32 v18, v8, v9
	global_store_dwordx4 v[24:25], v[8:11], off offset:16
	global_store_dwordx2 v[26:27], v[18:19], off
	s_nop 0
	v_or_b32_e32 v26, 0x100, v22
	v_mov_b32_e32 v27, v23
	v_lshl_add_u64 v[26:27], s[40:41], 0, v[26:27]
	v_mul_f32_e32 v9, v9, v9
	v_mul_f32_e32 v11, v11, v11
	v_fmac_f32_e32 v9, v8, v8
	v_fmac_f32_e32 v11, v10, v10
	v_add_f32_e32 v8, v9, v11
	v_add_f32_e32 v8, v12, v8
	v_or_b32_e32 v22, 0x108, v22
	v_lshl_add_u64 v[22:23], s[40:41], 0, v[22:23]
	s_nop 0
	v_pk_add_f32 v[6:7], v[6:7], v[226:227]
	v_pk_add_f32 v[4:5], v[4:5], v[224:225]
	v_cvt_pk_bf16_f32 v19, v6, v7
	v_cvt_pk_bf16_f32 v18, v4, v5
	global_store_dwordx4 v[24:25], v[4:7], off offset:512
	global_store_dwordx2 v[26:27], v[18:19], off
	s_nop 0
	v_mul_f32_e32 v5, v5, v5
	v_mul_f32_e32 v7, v7, v7
	v_fmac_f32_e32 v5, v4, v4
	v_fmac_f32_e32 v7, v6, v6
	v_add_f32_e32 v4, v5, v7
	v_add_f32_e32 v6, v8, v4
	s_nop 0
	v_pk_add_f32 v[2:3], v[2:3], v[236:237]
	v_pk_add_f32 v[0:1], v[0:1], v[234:235]
	global_store_dwordx4 v[24:25], v[0:3], off offset:528
	v_cvt_pk_bf16_f32 v4, v0, v1
	v_cvt_pk_bf16_f32 v5, v2, v3
	v_mul_f32_e32 v1, v1, v1
	v_mul_f32_e32 v3, v3, v3
	v_fmac_f32_e32 v1, v0, v0
	v_fmac_f32_e32 v3, v2, v2
	v_add_f32_e32 v0, v1, v3
	v_add_f32_e32 v0, v6, v0
	v_mov_b32_e32 v1, v0
	s_nop 1
	v_permlane16_swap_b32 v0, v1
	global_store_dwordx2 v[22:23], v[4:5], off
	v_add_f32_e32 v0, v0, v1
	v_mov_b32_e32 v1, v0
	s_nop 1
	v_permlane32_swap_b32 v0, v1
	s_and_saveexec_b64 s[12:13], s[2:3]
	s_cbranch_execz .LBB0_1621
	v_lshl_add_u64 v[2:3], v[16:17], 2, s[6:7]
	v_add_f32_e32 v0, v0, v1
	global_atomic_add_f32 v[2:3], v0, off

; __device__ __forceinline__ unsigned pk2(float lo, float hi) { f32x2_t v = {lo, hi}; bf16x2_t b = __builtin_convertvector(v, bf16x2_t); return __builtin_bit_cast(unsigned, b); }
; __device__ __forceinline__ float fast_silu(float g) { return g * __builtin_amdgcn_rcpf(1.f + __expf(-g)); }
;     __device__ __forceinline__ void operator()(const f32x4 (&acc)[2][2][4][2], const Unit& u, int wr, int wc, int fr, int fq) const {
;         const int row0 = u.pm * BM + wr * 64 + fr; const int dc = u.pn * HALF + wc * 32 + 8 * fq;
; #pragma unroll
;         for (int ai = 0; ai < 2; ++ai)
; #pragma unroll
;             for (int m = 0; m < 4; ++m) {
;                 const int row = row0 + ai * HALF + m * 16;
;                 const float rs = ss ? rsqrtf(ss[row] * (1.f / 2048.f) + EPS) : 1.f;
;                 const f32x4 g0 = acc[ai][0][m][0] * rs, g1 = acc[ai][0][m][1] * rs, u0 = acc[ai][1][m][0] * rs, u1 = acc[ai][1][m][1] * rs; u32x4 w;
;                 w.x = pk2(fast_silu(g0[0]) * u0[0], fast_silu(g0[1]) * u0[1]); w.y = pk2(fast_silu(g0[2]) * u0[2], fast_silu(g0[3]) * u0[3]);
;                 w.z = pk2(fast_silu(g1[0]) * u1[0], fast_silu(g1[1]) * u1[1]); w.w = pk2(fast_silu(g1[2]) * u1[2], fast_silu(g1[3]) * u1[3]);
;                 *(u32x4*)(O + (size_t)row * ldc + dc) = w;
.LBB0_1692:
	v_lshl_add_u32 v144, s0, 8, v152
	v_ashrrev_i32_e32 v145, 31, v144
	v_lshl_add_u64 v[150:151], v[144:145], 2, s[6:7]
	global_load_dword v230, v[150:151], off
	global_load_dword v231, v[150:151], off offset:64
	global_load_dword v232, v[150:151], off offset:128
	global_load_dword v233, v[150:151], off offset:192
	global_load_dword v234, v[150:151], off offset:512
	global_load_dword v235, v[150:151], off offset:576
	global_load_dword v236, v[150:151], off offset:640
	global_load_dword v237, v[150:151], off offset:704
	s_nop 0
	v_or_b32_e32 v162, 16, v144
	v_ashrrev_i32_e32 v163, 31, v162
	v_lshl_add_u64 v[164:165], v[162:163], 2, s[6:7]
	v_lshl_or_b32 v148, s1, 7, v154
	v_readlane_b32 s0, v238, 55
	v_readlane_b32 s1, v238, 56
	v_ashrrev_i32_e32 v149, 31, v148
	v_lshlrev_b64 v[148:149], 1, v[148:149]
	v_mov_b64_e32 v[146:147], s[0:1]
	v_mad_i64_i32 v[160:161], s[0:1], v144, s49, v[146:147]
	v_lshl_add_u64 v[160:161], v[160:161], 0, v[148:149]
	s_waitcnt vmcnt(7)
	v_fmamk_f32 v145, v230, 0x3a000000, v158
	v_mul_f32_e32 v159, 0x4b800000, v145
	v_cmp_gt_f32_e32 vcc, s48, v145
	s_nop 1
	v_cndmask_b32_e32 v145, v145, v159, vcc
	v_rsq_f32_e32 v145, v145
	s_nop 0
	v_mul_f32_e32 v159, 0x45800000, v145
	v_cndmask_b32_e32 v166, v145, v159, vcc
	v_pk_mul_f32 v[126:127], v[126:127], v[166:167] op_sel_hi:[1,0]
	v_pk_mul_f32 v[124:125], v[124:125], v[166:167] op_sel_hi:[1,0]
	v_pk_mul_f32 v[122:123], v[122:123], v[166:167] op_sel_hi:[1,0]
	v_pk_mul_f32 v[120:121], v[120:121], v[166:167] op_sel_hi:[1,0]
	v_pk_mul_f32 v[118:119], v[118:119], v[166:167] op_sel_hi:[1,0]
	v_pk_mul_f32 v[116:117], v[116:117], v[166:167] op_sel_hi:[1,0]
	v_pk_mul_f32 v[114:115], v[114:115], v[166:167] op_sel_hi:[1,0]
	v_pk_mul_f32 v[112:113], v[112:113], v[166:167] op_sel_hi:[1,0]
	v_mul_f32_e32 v145, 0xbfb8aa3b, v124
	v_mul_f32_e32 v159, 0xbfb8aa3b, v125
	v_mul_f32_e32 v163, 0xbfb8aa3b, v126
	v_mul_f32_e32 v166, 0xbfb8aa3b, v127
	v_mul_f32_e32 v167, 0xbfb8aa3b, v120
	v_mul_f32_e32 v168, 0xbfb8aa3b, v121
	v_mul_f32_e32 v169, 0xbfb8aa3b, v122
	v_mul_f32_e32 v170, 0xbfb8aa3b, v123
	v_exp_f32_e32 v145, v145
	v_exp_f32_e32 v159, v159
	v_exp_f32_e32 v163, v163
	v_exp_f32_e32 v166, v166
	v_exp_f32_e32 v167, v167
	v_exp_f32_e32 v168, v168
	v_exp_f32_e32 v169, v169
	v_exp_f32_e32 v170, v170
	v_add_f32_e32 v145, 1.0, v145
	v_add_f32_e32 v159, 1.0, v159
	v_add_f32_e32 v163, 1.0, v163
	v_add_f32_e32 v171, 1.0, v166
	v_add_f32_e32 v172, 1.0, v167
	v_add_f32_e32 v173, 1.0, v168
	v_add_f32_e32 v174, 1.0, v169
	v_add_f32_e32 v175, 1.0, v170
	v_rcp_f32_e32 v166, v145
	v_rcp_f32_e32 v167, v159
	v_rcp_f32_e32 v168, v163
	v_rcp_f32_e32 v169, v171
	v_rcp_f32_e32 v170, v172
	v_rcp_f32_e32 v171, v173
	v_rcp_f32_e32 v172, v174
	v_rcp_f32_e32 v173, v175
	v_pk_mul_f32 v[124:125], v[124:125], v[166:167]
	v_pk_mul_f32 v[126:127], v[126:127], v[168:169]
	v_pk_mul_f32 v[120:121], v[120:121], v[170:171]
	v_pk_mul_f32 v[122:123], v[122:123], v[172:173]
	v_pk_mul_f32 v[116:117], v[116:117], v[124:125]
	v_pk_mul_f32 v[118:119], v[118:119], v[126:127]
	v_pk_mul_f32 v[120:121], v[112:113], v[120:121]
	v_pk_mul_f32 v[122:123], v[114:115], v[122:123]
	v_cvt_pk_bf16_f32 v112, v116, v117
	v_cvt_pk_bf16_f32 v113, v118, v119
	v_cvt_pk_bf16_f32 v114, v120, v121
	v_cvt_pk_bf16_f32 v115, v122, v123
	global_store_dwordx4 v[160:161], v[112:115], off
	s_nop 0
	s_nop 0
	v_or_b32_e32 v112, 32, v144
	v_mad_i64_i32 v[114:115], s[0:1], v162, s49, v[146:147]
	v_lshl_add_u64 v[114:115], v[114:115], 0, v[148:149]
	s_waitcnt vmcnt(7)
	v_fmamk_f32 v113, v231, 0x3a000000, v158
	v_mul_f32_e32 v116, 0x4b800000, v113
	v_cmp_gt_f32_e32 vcc, s48, v113
	s_nop 1
	v_cndmask_b32_e32 v113, v113, v116, vcc
	v_rsq_f32_e32 v118, v113
	v_ashrrev_i32_e32 v113, 31, v112
	v_lshl_add_u64 v[116:117], v[112:113], 2, s[6:7]
	v_mul_f32_e32 v113, 0x45800000, v118
	v_cndmask_b32_e32 v118, v118, v113, vcc
	v_pk_mul_f32 v[110:111], v[110:111], v[118:119] op_sel_hi:[1,0]
	v_pk_mul_f32 v[108:109], v[108:109], v[118:119] op_sel_hi:[1,0]
	v_pk_mul_f32 v[106:107], v[106:107], v[118:119] op_sel_hi:[1,0]
	v_pk_mul_f32 v[104:105], v[104:105], v[118:119] op_sel_hi:[1,0]
	v_pk_mul_f32 v[102:103], v[102:103], v[118:119] op_sel_hi:[1,0]
	v_pk_mul_f32 v[100:101], v[100:101], v[118:119] op_sel_hi:[1,0]
	v_pk_mul_f32 v[98:99], v[98:99], v[118:119] op_sel_hi:[1,0]
	v_pk_mul_f32 v[96:97], v[96:97], v[118:119] op_sel_hi:[1,0]
	v_mul_f32_e32 v113, 0xbfb8aa3b, v108
	v_mul_f32_e32 v118, 0xbfb8aa3b, v109
	v_mul_f32_e32 v119, 0xbfb8aa3b, v110
	v_mul_f32_e32 v120, 0xbfb8aa3b, v111
	v_mul_f32_e32 v121, 0xbfb8aa3b, v104
	v_mul_f32_e32 v122, 0xbfb8aa3b, v105
	v_mul_f32_e32 v123, 0xbfb8aa3b, v106
	v_mul_f32_e32 v124, 0xbfb8aa3b, v107
	v_exp_f32_e32 v113, v113
	v_exp_f32_e32 v118, v118
	v_exp_f32_e32 v119, v119
	v_exp_f32_e32 v120, v120
	v_exp_f32_e32 v121, v121
	v_exp_f32_e32 v122, v122
	v_exp_f32_e32 v123, v123
	v_exp_f32_e32 v124, v124
	v_add_f32_e32 v113, 1.0, v113
	v_add_f32_e32 v125, 1.0, v118
	v_add_f32_e32 v126, 1.0, v119
	v_add_f32_e32 v127, 1.0, v120
	v_add_f32_e32 v145, 1.0, v121
	v_add_f32_e32 v159, 1.0, v122
	v_add_f32_e32 v160, 1.0, v123
	v_add_f32_e32 v161, 1.0, v124
	v_rcp_f32_e32 v118, v113
	v_rcp_f32_e32 v119, v125
	v_rcp_f32_e32 v120, v126
	v_rcp_f32_e32 v121, v127
	v_rcp_f32_e32 v122, v145
	v_rcp_f32_e32 v123, v159
	v_rcp_f32_e32 v124, v160
	v_rcp_f32_e32 v125, v161
	v_pk_mul_f32 v[108:109], v[108:109], v[118:119]
	v_pk_mul_f32 v[110:111], v[110:111], v[120:121]
	v_pk_mul_f32 v[104:105], v[104:105], v[122:123]
	v_pk_mul_f32 v[106:107], v[106:107], v[124:125]
	v_pk_mul_f32 v[100:101], v[100:101], v[108:109]
	v_pk_mul_f32 v[102:103], v[102:103], v[110:111]
	v_pk_mul_f32 v[104:105], v[96:97], v[104:105]
	v_pk_mul_f32 v[106:107], v[98:99], v[106:107]
	v_cvt_pk_bf16_f32 v96, v100, v101
	v_cvt_pk_bf16_f32 v97, v102, v103
	v_cvt_pk_bf16_f32 v98, v104, v105
	v_cvt_pk_bf16_f32 v99, v106, v107
	global_store_dwordx4 v[114:115], v[96:99], off
	s_nop 0
	s_nop 0
	v_or_b32_e32 v96, 48, v144
	v_mad_i64_i32 v[98:99], s[0:1], v112, s49, v[146:147]
	v_lshl_add_u64 v[98:99], v[98:99], 0, v[148:149]
	s_waitcnt vmcnt(7)
; __device__ __forceinline__ unsigned pk2(float lo, float hi) { f32x2_t v = {lo, hi}; bf16x2_t b = __builtin_convertvector(v, bf16x2_t); return __builtin_bit_cast(unsigned, b); }
; __device__ __forceinline__ float fast_silu(float g) { return g * __builtin_amdgcn_rcpf(1.f + __expf(-g)); }
;     __device__ __forceinline__ void operator()(const f32x4 (&acc)[2][2][4][2], const Unit& u, int wr, int wc, int fr, int fq) const {
;         const int row0 = u.pm * BM + wr * 64 + fr; const int dc = u.pn * HALF + wc * 32 + 8 * fq;
; #pragma unroll
;         for (int ai = 0; ai < 2; ++ai)
; #pragma unroll
;             for (int m = 0; m < 4; ++m) {
;                 const int row = row0 + ai * HALF + m * 16;
;                 const float rs = ss ? rsqrtf(ss[row] * (1.f / 2048.f) + EPS) : 1.f;
;                 const f32x4 g0 = acc[ai][0][m][0] * rs, g1 = acc[ai][0][m][1] * rs, u0 = acc[ai][1][m][0] * rs, u1 = acc[ai][1][m][1] * rs; u32x4 w;
;                 w.x = pk2(fast_silu(g0[0]) * u0[0], fast_silu(g0[1]) * u0[1]); w.y = pk2(fast_silu(g0[2]) * u0[2], fast_silu(g0[3]) * u0[3]);
;                 w.z = pk2(fast_silu(g1[0]) * u1[0], fast_silu(g1[1]) * u1[1]); w.w = pk2(fast_silu(g1[2]) * u1[2], fast_silu(g1[3]) * u1[3]);
;                 *(u32x4*)(O + (size_t)row * ldc + dc) = w;
	v_fmamk_f32 v97, v232, 0x3a000000, v158
	v_mul_f32_e32 v100, 0x4b800000, v97
	v_cmp_gt_f32_e32 vcc, s48, v97
	s_nop 1
	v_cndmask_b32_e32 v97, v97, v100, vcc
	v_rsq_f32_e32 v102, v97
	v_ashrrev_i32_e32 v97, 31, v96
	v_lshl_add_u64 v[100:101], v[96:97], 2, s[6:7]
	v_mul_f32_e32 v97, 0x45800000, v102
	v_cndmask_b32_e32 v102, v102, v97, vcc
	v_pk_mul_f32 v[94:95], v[94:95], v[102:103] op_sel_hi:[1,0]
	v_pk_mul_f32 v[92:93], v[92:93], v[102:103] op_sel_hi:[1,0]
	v_pk_mul_f32 v[90:91], v[90:91], v[102:103] op_sel_hi:[1,0]
	v_pk_mul_f32 v[88:89], v[88:89], v[102:103] op_sel_hi:[1,0]
	v_pk_mul_f32 v[86:87], v[86:87], v[102:103] op_sel_hi:[1,0]
	v_pk_mul_f32 v[84:85], v[84:85], v[102:103] op_sel_hi:[1,0]
	v_pk_mul_f32 v[82:83], v[82:83], v[102:103] op_sel_hi:[1,0]
	v_pk_mul_f32 v[80:81], v[80:81], v[102:103] op_sel_hi:[1,0]
	v_mul_f32_e32 v97, 0xbfb8aa3b, v92
	v_mul_f32_e32 v102, 0xbfb8aa3b, v93
	v_mul_f32_e32 v103, 0xbfb8aa3b, v94
	v_mul_f32_e32 v104, 0xbfb8aa3b, v95
	v_mul_f32_e32 v105, 0xbfb8aa3b, v88
	v_mul_f32_e32 v106, 0xbfb8aa3b, v89
	v_mul_f32_e32 v107, 0xbfb8aa3b, v90
	v_mul_f32_e32 v108, 0xbfb8aa3b, v91
	v_exp_f32_e32 v97, v97
	v_exp_f32_e32 v102, v102
	v_exp_f32_e32 v103, v103
	v_exp_f32_e32 v104, v104
	v_exp_f32_e32 v105, v105
	v_exp_f32_e32 v106, v106
	v_exp_f32_e32 v107, v107
	v_exp_f32_e32 v108, v108
	v_add_f32_e32 v97, 1.0, v97
	v_add_f32_e32 v109, 1.0, v102
	v_add_f32_e32 v110, 1.0, v103
	v_add_f32_e32 v111, 1.0, v104
	v_add_f32_e32 v112, 1.0, v105
	v_add_f32_e32 v113, 1.0, v106
	v_add_f32_e32 v114, 1.0, v107
	v_add_f32_e32 v115, 1.0, v108
	v_rcp_f32_e32 v102, v97
	v_rcp_f32_e32 v103, v109
	v_rcp_f32_e32 v104, v110
	v_rcp_f32_e32 v105, v111
	v_rcp_f32_e32 v106, v112
	v_rcp_f32_e32 v107, v113
	v_rcp_f32_e32 v108, v114
	v_rcp_f32_e32 v109, v115
	v_pk_mul_f32 v[92:93], v[92:93], v[102:103]
	v_pk_mul_f32 v[94:95], v[94:95], v[104:105]
	v_pk_mul_f32 v[88:89], v[88:89], v[106:107]
	v_pk_mul_f32 v[90:91], v[90:91], v[108:109]
	v_pk_mul_f32 v[84:85], v[84:85], v[92:93]
	v_pk_mul_f32 v[86:87], v[86:87], v[94:95]
	v_pk_mul_f32 v[88:89], v[80:81], v[88:89]
	v_pk_mul_f32 v[90:91], v[82:83], v[90:91]
	v_cvt_pk_bf16_f32 v80, v84, v85
	v_cvt_pk_bf16_f32 v81, v86, v87
	v_cvt_pk_bf16_f32 v82, v88, v89
	v_cvt_pk_bf16_f32 v83, v90, v91
	global_store_dwordx4 v[98:99], v[80:83], off
	s_nop 0
	s_waitcnt vmcnt(7)
	v_fmamk_f32 v80, v233, 0x3a000000, v158
	v_mul_f32_e32 v81, 0x4b800000, v80
	v_cmp_gt_f32_e32 vcc, s48, v80
	s_nop 1
	v_cndmask_b32_e32 v80, v80, v81, vcc
	v_rsq_f32_e32 v82, v80
	v_mad_i64_i32 v[80:81], s[0:1], v96, s49, v[146:147]
	v_lshl_add_u64 v[80:81], v[80:81], 0, v[148:149]
	v_mul_f32_e32 v83, 0x45800000, v82
	v_cndmask_b32_e32 v82, v82, v83, vcc
	v_pk_mul_f32 v[78:79], v[78:79], v[82:83] op_sel_hi:[1,0]
	v_pk_mul_f32 v[76:77], v[76:77], v[82:83] op_sel_hi:[1,0]
	v_pk_mul_f32 v[74:75], v[74:75], v[82:83] op_sel_hi:[1,0]
	v_pk_mul_f32 v[72:73], v[72:73], v[82:83] op_sel_hi:[1,0]
	v_pk_mul_f32 v[70:71], v[70:71], v[82:83] op_sel_hi:[1,0]
	v_pk_mul_f32 v[68:69], v[68:69], v[82:83] op_sel_hi:[1,0]
	v_pk_mul_f32 v[66:67], v[66:67], v[82:83] op_sel_hi:[1,0]
	v_pk_mul_f32 v[64:65], v[64:65], v[82:83] op_sel_hi:[1,0]
	v_mul_f32_e32 v82, 0xbfb8aa3b, v76
	v_mul_f32_e32 v83, 0xbfb8aa3b, v77
	v_mul_f32_e32 v84, 0xbfb8aa3b, v78
	v_mul_f32_e32 v85, 0xbfb8aa3b, v79
	v_mul_f32_e32 v86, 0xbfb8aa3b, v72
	v_mul_f32_e32 v87, 0xbfb8aa3b, v73
	v_mul_f32_e32 v88, 0xbfb8aa3b, v74
	v_mul_f32_e32 v89, 0xbfb8aa3b, v75
	v_exp_f32_e32 v82, v82
	v_exp_f32_e32 v83, v83
	v_exp_f32_e32 v84, v84
	v_exp_f32_e32 v85, v85
	v_exp_f32_e32 v86, v86
	v_exp_f32_e32 v87, v87
	v_exp_f32_e32 v88, v88
	v_exp_f32_e32 v89, v89
	v_add_f32_e32 v82, 1.0, v82
	v_add_f32_e32 v83, 1.0, v83
	v_add_f32_e32 v84, 1.0, v84
	v_add_f32_e32 v85, 1.0, v85
	v_add_f32_e32 v86, 1.0, v86
	v_add_f32_e32 v87, 1.0, v87
	v_add_f32_e32 v88, 1.0, v88
	v_add_f32_e32 v89, 1.0, v89
	v_rcp_f32_e32 v82, v82
	v_rcp_f32_e32 v83, v83
	v_rcp_f32_e32 v84, v84
	v_rcp_f32_e32 v85, v85
	v_rcp_f32_e32 v86, v86
	v_rcp_f32_e32 v87, v87
	v_rcp_f32_e32 v88, v88
	v_rcp_f32_e32 v89, v89
	v_pk_mul_f32 v[76:77], v[76:77], v[82:83]
	v_pk_mul_f32 v[78:79], v[78:79], v[84:85]
	v_pk_mul_f32 v[72:73], v[72:73], v[86:87]
	v_pk_mul_f32 v[74:75], v[74:75], v[88:89]
	v_pk_mul_f32 v[68:69], v[68:69], v[76:77]
	v_pk_mul_f32 v[70:71], v[70:71], v[78:79]
	v_pk_mul_f32 v[72:73], v[64:65], v[72:73]
	v_pk_mul_f32 v[74:75], v[66:67], v[74:75]
	v_cvt_pk_bf16_f32 v64, v68, v69
	v_cvt_pk_bf16_f32 v65, v70, v71
	v_cvt_pk_bf16_f32 v66, v72, v73
	v_cvt_pk_bf16_f32 v67, v74, v75
	global_store_dwordx4 v[80:81], v[64:67], off
	s_nop 0
	s_nop 0
	v_add_u32_e32 v65, 0x80, v144
	s_waitcnt vmcnt(7)
; __device__ __forceinline__ unsigned pk2(float lo, float hi) { f32x2_t v = {lo, hi}; bf16x2_t b = __builtin_convertvector(v, bf16x2_t); return __builtin_bit_cast(unsigned, b); }
; __device__ __forceinline__ float fast_silu(float g) { return g * __builtin_amdgcn_rcpf(1.f + __expf(-g)); }
;     __device__ __forceinline__ void operator()(const f32x4 (&acc)[2][2][4][2], const Unit& u, int wr, int wc, int fr, int fq) const {
;         const int row0 = u.pm * BM + wr * 64 + fr; const int dc = u.pn * HALF + wc * 32 + 8 * fq;
; #pragma unroll
;         for (int ai = 0; ai < 2; ++ai)
; #pragma unroll
;             for (int m = 0; m < 4; ++m) {
;                 const int row = row0 + ai * HALF + m * 16;
;                 const float rs = ss ? rsqrtf(ss[row] * (1.f / 2048.f) + EPS) : 1.f;
;                 const f32x4 g0 = acc[ai][0][m][0] * rs, g1 = acc[ai][0][m][1] * rs, u0 = acc[ai][1][m][0] * rs, u1 = acc[ai][1][m][1] * rs; u32x4 w;
;                 w.x = pk2(fast_silu(g0[0]) * u0[0], fast_silu(g0[1]) * u0[1]); w.y = pk2(fast_silu(g0[2]) * u0[2], fast_silu(g0[3]) * u0[3]);
;                 w.z = pk2(fast_silu(g1[0]) * u1[0], fast_silu(g1[1]) * u1[1]); w.w = pk2(fast_silu(g1[2]) * u1[2], fast_silu(g1[3]) * u1[3]);
;                 *(u32x4*)(O + (size_t)row * ldc + dc) = w;
	v_fmamk_f32 v64, v234, 0x3a000000, v158
	v_mul_f32_e32 v66, 0x4b800000, v64
	v_cmp_gt_f32_e32 vcc, s48, v64
	s_nop 1
	v_cndmask_b32_e32 v64, v64, v66, vcc
	v_rsq_f32_e32 v66, v64
	v_mad_i64_i32 v[64:65], s[0:1], v65, s49, v[146:147]
	v_lshl_add_u64 v[64:65], v[64:65], 0, v[148:149]
	v_mul_f32_e32 v67, 0x45800000, v66
	v_cndmask_b32_e32 v66, v66, v67, vcc
	v_pk_mul_f32 v[62:63], v[62:63], v[66:67] op_sel_hi:[1,0]
	v_pk_mul_f32 v[60:61], v[60:61], v[66:67] op_sel_hi:[1,0]
	v_pk_mul_f32 v[58:59], v[58:59], v[66:67] op_sel_hi:[1,0]
	v_pk_mul_f32 v[56:57], v[56:57], v[66:67] op_sel_hi:[1,0]
	v_pk_mul_f32 v[54:55], v[54:55], v[66:67] op_sel_hi:[1,0]
	v_pk_mul_f32 v[52:53], v[52:53], v[66:67] op_sel_hi:[1,0]
	v_pk_mul_f32 v[50:51], v[50:51], v[66:67] op_sel_hi:[1,0]
	v_pk_mul_f32 v[48:49], v[48:49], v[66:67] op_sel_hi:[1,0]
	v_mul_f32_e32 v66, 0xbfb8aa3b, v60
	v_mul_f32_e32 v67, 0xbfb8aa3b, v61
	v_mul_f32_e32 v68, 0xbfb8aa3b, v62
	v_mul_f32_e32 v69, 0xbfb8aa3b, v63
	v_mul_f32_e32 v70, 0xbfb8aa3b, v56
	v_mul_f32_e32 v71, 0xbfb8aa3b, v57
	v_mul_f32_e32 v72, 0xbfb8aa3b, v58
	v_mul_f32_e32 v73, 0xbfb8aa3b, v59
	v_exp_f32_e32 v66, v66
	v_exp_f32_e32 v67, v67
	v_exp_f32_e32 v68, v68
	v_exp_f32_e32 v69, v69
	v_exp_f32_e32 v70, v70
	v_exp_f32_e32 v71, v71
	v_exp_f32_e32 v72, v72
	v_exp_f32_e32 v73, v73
	v_add_f32_e32 v66, 1.0, v66
	v_add_f32_e32 v67, 1.0, v67
	v_add_f32_e32 v68, 1.0, v68
	v_add_f32_e32 v69, 1.0, v69
	v_add_f32_e32 v70, 1.0, v70
	v_add_f32_e32 v71, 1.0, v71
	v_add_f32_e32 v72, 1.0, v72
	v_add_f32_e32 v73, 1.0, v73
	v_rcp_f32_e32 v66, v66
	v_rcp_f32_e32 v67, v67
	v_rcp_f32_e32 v68, v68
	v_rcp_f32_e32 v69, v69
	v_rcp_f32_e32 v70, v70
	v_rcp_f32_e32 v71, v71
	v_rcp_f32_e32 v72, v72
	v_rcp_f32_e32 v73, v73
	v_pk_mul_f32 v[60:61], v[60:61], v[66:67]
	v_pk_mul_f32 v[62:63], v[62:63], v[68:69]
	v_pk_mul_f32 v[56:57], v[56:57], v[70:71]
	v_pk_mul_f32 v[58:59], v[58:59], v[72:73]
	v_pk_mul_f32 v[52:53], v[52:53], v[60:61]
	v_pk_mul_f32 v[54:55], v[54:55], v[62:63]
	v_pk_mul_f32 v[56:57], v[48:49], v[56:57]
	v_pk_mul_f32 v[58:59], v[50:51], v[58:59]
	v_cvt_pk_bf16_f32 v48, v52, v53
	v_cvt_pk_bf16_f32 v49, v54, v55
	v_cvt_pk_bf16_f32 v50, v56, v57
	v_cvt_pk_bf16_f32 v51, v58, v59
	global_store_dwordx4 v[64:65], v[48:51], off
	s_nop 0
	s_nop 0
	v_add_u32_e32 v49, 0x90, v144
	s_waitcnt vmcnt(7)
	v_fmamk_f32 v48, v235, 0x3a000000, v158
	v_mul_f32_e32 v50, 0x4b800000, v48
	v_cmp_gt_f32_e32 vcc, s48, v48
	s_nop 1
	v_cndmask_b32_e32 v48, v48, v50, vcc
	v_rsq_f32_e32 v50, v48
	v_mad_i64_i32 v[48:49], s[0:1], v49, s49, v[146:147]
	v_lshl_add_u64 v[48:49], v[48:49], 0, v[148:149]
	v_mul_f32_e32 v51, 0x45800000, v50
	v_cndmask_b32_e32 v50, v50, v51, vcc
	v_pk_mul_f32 v[46:47], v[46:47], v[50:51] op_sel_hi:[1,0]
	v_pk_mul_f32 v[44:45], v[44:45], v[50:51] op_sel_hi:[1,0]
	v_pk_mul_f32 v[42:43], v[42:43], v[50:51] op_sel_hi:[1,0]
	v_pk_mul_f32 v[40:41], v[40:41], v[50:51] op_sel_hi:[1,0]
	v_pk_mul_f32 v[38:39], v[38:39], v[50:51] op_sel_hi:[1,0]
	v_pk_mul_f32 v[36:37], v[36:37], v[50:51] op_sel_hi:[1,0]
	v_pk_mul_f32 v[34:35], v[34:35], v[50:51] op_sel_hi:[1,0]
	v_pk_mul_f32 v[32:33], v[32:33], v[50:51] op_sel_hi:[1,0]
	v_mul_f32_e32 v50, 0xbfb8aa3b, v44
	v_mul_f32_e32 v51, 0xbfb8aa3b, v45
	v_mul_f32_e32 v52, 0xbfb8aa3b, v46
	v_mul_f32_e32 v53, 0xbfb8aa3b, v47
	v_mul_f32_e32 v54, 0xbfb8aa3b, v40
	v_mul_f32_e32 v55, 0xbfb8aa3b, v41
	v_mul_f32_e32 v56, 0xbfb8aa3b, v42
	v_mul_f32_e32 v57, 0xbfb8aa3b, v43
	v_exp_f32_e32 v50, v50
	v_exp_f32_e32 v51, v51
	v_exp_f32_e32 v52, v52
	v_exp_f32_e32 v53, v53
	v_exp_f32_e32 v54, v54
	v_exp_f32_e32 v55, v55
	v_exp_f32_e32 v56, v56
	v_exp_f32_e32 v57, v57
	v_add_f32_e32 v50, 1.0, v50
	v_add_f32_e32 v51, 1.0, v51
	v_add_f32_e32 v52, 1.0, v52
	v_add_f32_e32 v53, 1.0, v53
	v_add_f32_e32 v54, 1.0, v54
	v_add_f32_e32 v55, 1.0, v55
	v_add_f32_e32 v56, 1.0, v56
	v_add_f32_e32 v57, 1.0, v57
	v_rcp_f32_e32 v50, v50
	v_rcp_f32_e32 v51, v51
	v_rcp_f32_e32 v52, v52
	v_rcp_f32_e32 v53, v53
	v_rcp_f32_e32 v54, v54
	v_rcp_f32_e32 v55, v55
	v_rcp_f32_e32 v56, v56
	v_rcp_f32_e32 v57, v57
	v_pk_mul_f32 v[44:45], v[44:45], v[50:51]
	v_pk_mul_f32 v[46:47], v[46:47], v[52:53]
	v_pk_mul_f32 v[40:41], v[40:41], v[54:55]
	v_pk_mul_f32 v[42:43], v[42:43], v[56:57]
	v_pk_mul_f32 v[36:37], v[36:37], v[44:45]
	v_pk_mul_f32 v[38:39], v[38:39], v[46:47]
	v_pk_mul_f32 v[40:41], v[32:33], v[40:41]
	v_pk_mul_f32 v[42:43], v[34:35], v[42:43]
	v_cvt_pk_bf16_f32 v32, v36, v37
	v_cvt_pk_bf16_f32 v33, v38, v39
	v_cvt_pk_bf16_f32 v34, v40, v41
	v_cvt_pk_bf16_f32 v35, v42, v43
	global_store_dwordx4 v[48:49], v[32:35], off
	s_nop 0
	s_nop 0
	v_add_u32_e32 v33, 0xa0, v144
	s_waitcnt vmcnt(7)
; __device__ __forceinline__ unsigned pk2(float lo, float hi) { f32x2_t v = {lo, hi}; bf16x2_t b = __builtin_convertvector(v, bf16x2_t); return __builtin_bit_cast(unsigned, b); }
; __device__ __forceinline__ float fast_silu(float g) { return g * __builtin_amdgcn_rcpf(1.f + __expf(-g)); }
;     __device__ __forceinline__ void operator()(const f32x4 (&acc)[2][2][4][2], const Unit& u, int wr, int wc, int fr, int fq) const {
;         const int row0 = u.pm * BM + wr * 64 + fr; const int dc = u.pn * HALF + wc * 32 + 8 * fq;
; #pragma unroll
;         for (int ai = 0; ai < 2; ++ai)
; #pragma unroll
;             for (int m = 0; m < 4; ++m) {
;                 const int row = row0 + ai * HALF + m * 16;
;                 const float rs = ss ? rsqrtf(ss[row] * (1.f / 2048.f) + EPS) : 1.f;
;                 const f32x4 g0 = acc[ai][0][m][0] * rs, g1 = acc[ai][0][m][1] * rs, u0 = acc[ai][1][m][0] * rs, u1 = acc[ai][1][m][1] * rs; u32x4 w;
;                 w.x = pk2(fast_silu(g0[0]) * u0[0], fast_silu(g0[1]) * u0[1]); w.y = pk2(fast_silu(g0[2]) * u0[2], fast_silu(g0[3]) * u0[3]);
;                 w.z = pk2(fast_silu(g1[0]) * u1[0], fast_silu(g1[1]) * u1[1]); w.w = pk2(fast_silu(g1[2]) * u1[2], fast_silu(g1[3]) * u1[3]);
;                 *(u32x4*)(O + (size_t)row * ldc + dc) = w;
	v_fmamk_f32 v32, v236, 0x3a000000, v158
	v_mul_f32_e32 v34, 0x4b800000, v32
	v_cmp_gt_f32_e32 vcc, s48, v32
	s_nop 1
	v_cndmask_b32_e32 v32, v32, v34, vcc
	v_rsq_f32_e32 v34, v32
	v_mad_i64_i32 v[32:33], s[0:1], v33, s49, v[146:147]
	v_lshl_add_u64 v[32:33], v[32:33], 0, v[148:149]
	v_mul_f32_e32 v35, 0x45800000, v34
	v_cndmask_b32_e32 v34, v34, v35, vcc
	v_pk_mul_f32 v[30:31], v[30:31], v[34:35] op_sel_hi:[1,0]
	v_pk_mul_f32 v[28:29], v[28:29], v[34:35] op_sel_hi:[1,0]
	v_pk_mul_f32 v[26:27], v[26:27], v[34:35] op_sel_hi:[1,0]
	v_pk_mul_f32 v[24:25], v[24:25], v[34:35] op_sel_hi:[1,0]
	v_pk_mul_f32 v[22:23], v[22:23], v[34:35] op_sel_hi:[1,0]
	v_pk_mul_f32 v[20:21], v[20:21], v[34:35] op_sel_hi:[1,0]
	v_pk_mul_f32 v[18:19], v[18:19], v[34:35] op_sel_hi:[1,0]
	v_pk_mul_f32 v[16:17], v[16:17], v[34:35] op_sel_hi:[1,0]
	v_mul_f32_e32 v34, 0xbfb8aa3b, v28
	v_mul_f32_e32 v35, 0xbfb8aa3b, v29
	v_mul_f32_e32 v36, 0xbfb8aa3b, v30
	v_mul_f32_e32 v37, 0xbfb8aa3b, v31
	v_mul_f32_e32 v38, 0xbfb8aa3b, v24
	v_mul_f32_e32 v39, 0xbfb8aa3b, v25
	v_mul_f32_e32 v40, 0xbfb8aa3b, v26
	v_mul_f32_e32 v41, 0xbfb8aa3b, v27
	v_exp_f32_e32 v34, v34
	v_exp_f32_e32 v35, v35
	v_exp_f32_e32 v36, v36
	v_exp_f32_e32 v37, v37
	v_exp_f32_e32 v38, v38
	v_exp_f32_e32 v39, v39
	v_exp_f32_e32 v40, v40
	v_exp_f32_e32 v41, v41
	v_add_f32_e32 v34, 1.0, v34
	v_add_f32_e32 v35, 1.0, v35
	v_add_f32_e32 v36, 1.0, v36
	v_add_f32_e32 v37, 1.0, v37
	v_add_f32_e32 v38, 1.0, v38
	v_add_f32_e32 v39, 1.0, v39
	v_add_f32_e32 v40, 1.0, v40
	v_add_f32_e32 v41, 1.0, v41
	v_rcp_f32_e32 v34, v34
	v_rcp_f32_e32 v35, v35
	v_rcp_f32_e32 v36, v36
	v_rcp_f32_e32 v37, v37
	v_rcp_f32_e32 v38, v38
	v_rcp_f32_e32 v39, v39
	v_rcp_f32_e32 v40, v40
	v_rcp_f32_e32 v41, v41
	v_pk_mul_f32 v[28:29], v[28:29], v[34:35]
	v_pk_mul_f32 v[30:31], v[30:31], v[36:37]
	v_pk_mul_f32 v[24:25], v[24:25], v[38:39]
	v_pk_mul_f32 v[26:27], v[26:27], v[40:41]
	v_pk_mul_f32 v[20:21], v[20:21], v[28:29]
	v_pk_mul_f32 v[22:23], v[22:23], v[30:31]
	v_pk_mul_f32 v[24:25], v[16:17], v[24:25]
	v_pk_mul_f32 v[26:27], v[18:19], v[26:27]
	v_cvt_pk_bf16_f32 v16, v20, v21
	v_cvt_pk_bf16_f32 v17, v22, v23
	v_cvt_pk_bf16_f32 v18, v24, v25
	v_cvt_pk_bf16_f32 v19, v26, v27
	global_store_dwordx4 v[32:33], v[16:19], off
	s_nop 0
	s_andn2_b64 vcc, exec, s[2:3]
	v_add_u32_e32 v17, 0xb0, v144
	s_waitcnt vmcnt(7)
	v_fmamk_f32 v16, v237, 0x3a000000, v158
	v_mul_f32_e32 v18, 0x4b800000, v16
	v_cmp_gt_f32_e64 s[0:1], s48, v16
	s_nop 1
	v_cndmask_b32_e64 v16, v16, v18, s[0:1]
	v_rsq_f32_e32 v18, v16
	v_mad_i64_i32 v[16:17], s[12:13], v17, s49, v[146:147]
	v_lshl_add_u64 v[16:17], v[16:17], 0, v[148:149]
	v_mul_f32_e32 v19, 0x45800000, v18
	v_cndmask_b32_e64 v18, v18, v19, s[0:1]
	v_pk_mul_f32 v[14:15], v[14:15], v[18:19] op_sel_hi:[1,0]
	v_pk_mul_f32 v[12:13], v[12:13], v[18:19] op_sel_hi:[1,0]
	v_pk_mul_f32 v[10:11], v[10:11], v[18:19] op_sel_hi:[1,0]
	v_pk_mul_f32 v[8:9], v[8:9], v[18:19] op_sel_hi:[1,0]
	v_pk_mul_f32 v[6:7], v[6:7], v[18:19] op_sel_hi:[1,0]
	v_pk_mul_f32 v[4:5], v[4:5], v[18:19] op_sel_hi:[1,0]
	v_pk_mul_f32 v[2:3], v[2:3], v[18:19] op_sel_hi:[1,0]
	v_pk_mul_f32 v[0:1], v[0:1], v[18:19] op_sel_hi:[1,0]
	v_mul_f32_e32 v18, 0xbfb8aa3b, v12
	v_mul_f32_e32 v19, 0xbfb8aa3b, v13
	v_mul_f32_e32 v20, 0xbfb8aa3b, v14
	v_mul_f32_e32 v21, 0xbfb8aa3b, v15
	v_mul_f32_e32 v22, 0xbfb8aa3b, v8
	v_mul_f32_e32 v23, 0xbfb8aa3b, v9
	v_mul_f32_e32 v24, 0xbfb8aa3b, v10
	v_mul_f32_e32 v25, 0xbfb8aa3b, v11
	v_exp_f32_e32 v18, v18
	v_exp_f32_e32 v19, v19
	v_exp_f32_e32 v20, v20
	v_exp_f32_e32 v21, v21
	v_exp_f32_e32 v22, v22
	v_exp_f32_e32 v23, v23
	v_exp_f32_e32 v24, v24
	v_exp_f32_e32 v25, v25
	v_add_f32_e32 v18, 1.0, v18
	v_add_f32_e32 v19, 1.0, v19
	v_add_f32_e32 v20, 1.0, v20
	v_add_f32_e32 v21, 1.0, v21
	v_add_f32_e32 v22, 1.0, v22
	v_add_f32_e32 v23, 1.0, v23
	v_add_f32_e32 v24, 1.0, v24
	v_add_f32_e32 v25, 1.0, v25
	v_rcp_f32_e32 v18, v18
	v_rcp_f32_e32 v19, v19
	v_rcp_f32_e32 v20, v20
	v_rcp_f32_e32 v21, v21
	v_rcp_f32_e32 v22, v22
	v_rcp_f32_e32 v23, v23
	v_rcp_f32_e32 v24, v24
	v_rcp_f32_e32 v25, v25
	v_pk_mul_f32 v[12:13], v[12:13], v[18:19]
	v_pk_mul_f32 v[14:15], v[14:15], v[20:21]
	v_pk_mul_f32 v[8:9], v[8:9], v[22:23]
	v_pk_mul_f32 v[10:11], v[10:11], v[24:25]
	v_pk_mul_f32 v[4:5], v[4:5], v[12:13]
	v_pk_mul_f32 v[6:7], v[6:7], v[14:15]
	v_pk_mul_f32 v[8:9], v[0:1], v[8:9]
	v_pk_mul_f32 v[10:11], v[2:3], v[10:11]
	v_cvt_pk_bf16_f32 v0, v4, v5
	v_cvt_pk_bf16_f32 v1, v6, v7
	v_cvt_pk_bf16_f32 v2, v8, v9
	v_cvt_pk_bf16_f32 v3, v10, v11
	s_mov_b64 s[0:1], -1
	global_store_dwordx4 v[16:17], v[0:3], off
	s_cbranch_vccnz .LBB0_1685
	s_andn2_b64 vcc, exec, s[8:9]
	s_cbranch_vccnz .LBB0_1684
	s_barrier
	s_branch .LBB0_1684

; __device__ __forceinline__ unsigned pk2(float lo, float hi) { f32x2_t v = {lo, hi}; bf16x2_t b = __builtin_convertvector(v, bf16x2_t); return __builtin_bit_cast(unsigned, b); }
;     __device__ __forceinline__ void operator()(const f32x4 (&acc)[2][2][4][2], const Unit& u, int wr, int wc, int fr, int fq) const {
;     ...
;         for (int ai = 0; ai < 2; ++ai)
; #pragma unroll
;             for (int m = 0; m < 4; ++m) {
;                 const int row = row0 + ai * HALF + m * 16; float sq = 0.f;
; #pragma unroll
;                 for (int bj = 0; bj < 2; ++bj)
; #pragma unroll
;                     for (int n = 0; n < 2; ++n) {
;                         const size_t idx = (size_t)row * ldc + u.pn * BM + bj * HALF + wc * 32 + 8 * fq + 4 * n;
;                         const f32x4 b = *(const f32x4*)(base + idx);
;                         const f32x4 v = b + acc[ai][bj][m][n] * alpha;
;                         *(f32x4*)(out + idx) = v;
;                         if (NORM) { u32x2 w; w.x = pk2(v[0], v[1]); w.y = pk2(v[2], v[3]); *(u32x2*)(xb + idx) = w; sq += (v[0] * v[0] + v[1] * v[1]) + (v[2] * v[2] + v[3] * v[3]); }
;                     }
.LBB0_1775:
	v_lshl_add_u32 v148, s14, 8, v137
	s_lshl_b32 s14, s49, 8
	s_ashr_i32 s24, s14, 31
	v_ashrrev_i32_e32 v149, 31, v148
	v_mov_b32_e32 v147, s24
	v_or_b32_e32 v146, s14, v136
	v_lshlrev_b64 v[150:151], 13, v[148:149]
	v_lshl_add_u64 v[156:157], s[30:31], 0, v[150:151]
	v_lshlrev_b64 v[150:151], 2, v[146:147]
	v_lshl_add_u64 v[146:147], v[156:157], 0, v[150:151]
	v_mov_b32_e32 v232, v146
	v_mov_b32_e32 v233, v147
	v_mov_b32_e32 v231, 0
	v_mov_b32_e32 v230, 0x0
	v_lshl_add_u64 v[228:229], v[232:233], 0, v[230:231]
	global_load_dwordx4 v[164:167], v[228:229], off
	global_load_dwordx4 v[168:171], v[228:229], off offset:16
	global_load_dwordx4 v[172:175], v[228:229], off offset:512
	global_load_dwordx4 v[176:179], v[228:229], off offset:528
	v_mov_b32_e32 v230, 0x20000
	v_lshl_add_u64 v[228:229], v[232:233], 0, v[230:231]
	global_load_dwordx4 v[180:183], v[228:229], off
	global_load_dwordx4 v[188:191], v[228:229], off offset:16
	global_load_dwordx4 v[192:195], v[228:229], off offset:512
	global_load_dwordx4 v[196:199], v[228:229], off offset:528
	v_mov_b32_e32 v230, 0x40000
	v_lshl_add_u64 v[228:229], v[232:233], 0, v[230:231]
	global_load_dwordx4 v[200:203], v[228:229], off
	global_load_dwordx4 v[204:207], v[228:229], off offset:16
	global_load_dwordx4 v[208:211], v[228:229], off offset:512
	global_load_dwordx4 v[212:215], v[228:229], off offset:528
	v_mov_b32_e32 v230, 0x60000
	v_lshl_add_u64 v[228:229], v[232:233], 0, v[230:231]
	global_load_dwordx4 v[216:219], v[228:229], off
	global_load_dwordx4 v[220:223], v[228:229], off offset:16
	global_load_dwordx4 v[224:227], v[228:229], off offset:512
	global_load_dwordx4 v[234:237], v[228:229], off offset:528
	s_nop 0
	s_nop 0
	s_mov_b64 s[24:25], -1
	s_nop 0
	s_waitcnt vmcnt(12)
	v_pk_fma_f32 v[122:123], v[122:123], 0.5, v[170:171] op_sel_hi:[1,0,1]
	v_pk_fma_f32 v[126:127], v[126:127], 0.5, v[166:167] op_sel_hi:[1,0,1]
	v_pk_fma_f32 v[124:125], v[124:125], 0.5, v[164:165] op_sel_hi:[1,0,1]
	v_pk_fma_f32 v[120:121], v[120:121], 0.5, v[168:169] op_sel_hi:[1,0,1]
	global_store_dwordx4 v[146:147], v[124:127], off
	global_store_dwordx4 v[146:147], v[120:123], off offset:16
	s_nop 0
	s_nop 0
	s_nop 0
	s_nop 0
	v_pk_fma_f32 v[114:115], v[114:115], 0.5, v[178:179] op_sel_hi:[1,0,1]
	v_pk_fma_f32 v[112:113], v[112:113], 0.5, v[176:177] op_sel_hi:[1,0,1]
	global_store_dwordx4 v[146:147], v[112:115], off offset:528
	s_nop 0
	v_pk_fma_f32 v[118:119], v[118:119], 0.5, v[174:175] op_sel_hi:[1,0,1]
	v_pk_fma_f32 v[116:117], v[116:117], 0.5, v[172:173] op_sel_hi:[1,0,1]
	v_mov_b32_e32 v230, 0x100000
	v_lshl_add_u64 v[228:229], v[232:233], 0, v[230:231]
	global_load_dwordx4 v[164:167], v[228:229], off
	global_load_dwordx4 v[168:171], v[228:229], off offset:16
	global_load_dwordx4 v[172:175], v[228:229], off offset:512
	global_load_dwordx4 v[176:179], v[228:229], off offset:528
	v_or_b32_e32 v112, 16, v148
	v_ashrrev_i32_e32 v113, 31, v112
	v_lshlrev_b64 v[112:113], 13, v[112:113]
	v_lshl_add_u64 v[112:113], s[30:31], 0, v[112:113]
	global_store_dwordx4 v[146:147], v[116:119], off offset:512
	v_lshl_add_u64 v[120:121], v[112:113], 0, v[150:151]
	s_nop 0
	s_nop 0
	s_nop 0
	s_waitcnt vmcnt(16)
	v_pk_fma_f32 v[106:107], v[106:107], 0.5, v[190:191] op_sel_hi:[1,0,1]
	s_nop 0
	v_pk_fma_f32 v[110:111], v[110:111], 0.5, v[182:183] op_sel_hi:[1,0,1]
	v_pk_fma_f32 v[108:109], v[108:109], 0.5, v[180:181] op_sel_hi:[1,0,1]
	v_pk_fma_f32 v[104:105], v[104:105], 0.5, v[188:189] op_sel_hi:[1,0,1]
	global_store_dwordx4 v[120:121], v[108:111], off
	global_store_dwordx4 v[120:121], v[104:107], off offset:16
	s_nop 0
	s_nop 0
	s_nop 0
	s_nop 0
	v_pk_fma_f32 v[98:99], v[98:99], 0.5, v[198:199] op_sel_hi:[1,0,1]
	v_pk_fma_f32 v[96:97], v[96:97], 0.5, v[196:197] op_sel_hi:[1,0,1]
	global_store_dwordx4 v[120:121], v[96:99], off offset:528
	s_nop 0
	v_pk_fma_f32 v[102:103], v[102:103], 0.5, v[194:195] op_sel_hi:[1,0,1]
	v_pk_fma_f32 v[100:101], v[100:101], 0.5, v[192:193] op_sel_hi:[1,0,1]
	v_mov_b32_e32 v230, 0x120000
	v_lshl_add_u64 v[228:229], v[232:233], 0, v[230:231]
	global_load_dwordx4 v[180:183], v[228:229], off
	global_load_dwordx4 v[188:191], v[228:229], off offset:16
	global_load_dwordx4 v[192:195], v[228:229], off offset:512
	global_load_dwordx4 v[196:199], v[228:229], off offset:528
	v_or_b32_e32 v96, 32, v148
	v_ashrrev_i32_e32 v97, 31, v96
	v_lshlrev_b64 v[96:97], 13, v[96:97]
	v_lshl_add_u64 v[96:97], s[30:31], 0, v[96:97]
	global_store_dwordx4 v[120:121], v[100:103], off offset:512
	v_lshl_add_u64 v[104:105], v[96:97], 0, v[150:151]
	s_nop 0
	s_nop 0
	s_nop 0
	s_waitcnt vmcnt(20)
	v_pk_fma_f32 v[90:91], v[90:91], 0.5, v[206:207] op_sel_hi:[1,0,1]
	s_nop 0
	v_pk_fma_f32 v[94:95], v[94:95], 0.5, v[202:203] op_sel_hi:[1,0,1]
	v_pk_fma_f32 v[92:93], v[92:93], 0.5, v[200:201] op_sel_hi:[1,0,1]
	v_pk_fma_f32 v[88:89], v[88:89], 0.5, v[204:205] op_sel_hi:[1,0,1]
	global_store_dwordx4 v[104:105], v[92:95], off
	global_store_dwordx4 v[104:105], v[88:91], off offset:16
	s_nop 0
	s_nop 0
	s_nop 0
	s_nop 0
	v_pk_fma_f32 v[82:83], v[82:83], 0.5, v[214:215] op_sel_hi:[1,0,1]
	v_pk_fma_f32 v[80:81], v[80:81], 0.5, v[212:213] op_sel_hi:[1,0,1]
	global_store_dwordx4 v[104:105], v[80:83], off offset:528
	s_nop 0
	v_pk_fma_f32 v[86:87], v[86:87], 0.5, v[210:211] op_sel_hi:[1,0,1]
	v_pk_fma_f32 v[84:85], v[84:85], 0.5, v[208:209] op_sel_hi:[1,0,1]
	v_mov_b32_e32 v230, 0x140000
	v_lshl_add_u64 v[228:229], v[232:233], 0, v[230:231]
	global_load_dwordx4 v[200:203], v[228:229], off
	global_load_dwordx4 v[204:207], v[228:229], off offset:16
	global_load_dwordx4 v[208:211], v[228:229], off offset:512
	global_load_dwordx4 v[212:215], v[228:229], off offset:528
	v_or_b32_e32 v80, 48, v148
	v_ashrrev_i32_e32 v81, 31, v80
	v_lshlrev_b64 v[80:81], 13, v[80:81]
	v_lshl_add_u64 v[80:81], s[30:31], 0, v[80:81]
	global_store_dwordx4 v[104:105], v[84:87], off offset:512
	v_lshl_add_u64 v[88:89], v[80:81], 0, v[150:151]
	s_nop 0
	s_nop 0
	s_nop 0
	s_waitcnt vmcnt(24)
; __device__ __forceinline__ unsigned pk2(float lo, float hi) { f32x2_t v = {lo, hi}; bf16x2_t b = __builtin_convertvector(v, bf16x2_t); return __builtin_bit_cast(unsigned, b); }
;     __device__ __forceinline__ void operator()(const f32x4 (&acc)[2][2][4][2], const Unit& u, int wr, int wc, int fr, int fq) const {
;     ...
;                 const int row = row0 + ai * HALF + m * 16; float sq = 0.f;
; #pragma unroll
;                 for (int bj = 0; bj < 2; ++bj)
; #pragma unroll
;                     for (int n = 0; n < 2; ++n) {
;                         const size_t idx = (size_t)row * ldc + u.pn * BM + bj * HALF + wc * 32 + 8 * fq + 4 * n;
;                         const f32x4 b = *(const f32x4*)(base + idx);
;                         const f32x4 v = b + acc[ai][bj][m][n] * alpha;
;                         *(f32x4*)(out + idx) = v;
;                         if (NORM) { u32x2 w; w.x = pk2(v[0], v[1]); w.y = pk2(v[2], v[3]); *(u32x2*)(xb + idx) = w; sq += (v[0] * v[0] + v[1] * v[1]) + (v[2] * v[2] + v[3] * v[3]); }
;                     }
	v_pk_fma_f32 v[74:75], v[74:75], 0.5, v[222:223] op_sel_hi:[1,0,1]
	s_nop 0
	v_pk_fma_f32 v[78:79], v[78:79], 0.5, v[218:219] op_sel_hi:[1,0,1]
	v_pk_fma_f32 v[76:77], v[76:77], 0.5, v[216:217] op_sel_hi:[1,0,1]
	v_pk_fma_f32 v[72:73], v[72:73], 0.5, v[220:221] op_sel_hi:[1,0,1]
	global_store_dwordx4 v[88:89], v[76:79], off
	global_store_dwordx4 v[88:89], v[72:75], off offset:16
	s_nop 0
	s_nop 0
	s_nop 0
	s_nop 0
	v_pk_fma_f32 v[66:67], v[66:67], 0.5, v[236:237] op_sel_hi:[1,0,1]
	s_nop 0
	v_pk_fma_f32 v[70:71], v[70:71], 0.5, v[226:227] op_sel_hi:[1,0,1]
	v_pk_fma_f32 v[68:69], v[68:69], 0.5, v[224:225] op_sel_hi:[1,0,1]
	v_pk_fma_f32 v[64:65], v[64:65], 0.5, v[234:235] op_sel_hi:[1,0,1]
	v_mov_b32_e32 v230, 0x160000
	v_lshl_add_u64 v[228:229], v[232:233], 0, v[230:231]
	global_load_dwordx4 v[216:219], v[228:229], off
	global_load_dwordx4 v[220:223], v[228:229], off offset:16
	global_load_dwordx4 v[224:227], v[228:229], off offset:512
	global_load_dwordx4 v[234:237], v[228:229], off offset:528
	v_add_co_u32_e32 v74, vcc, s43, v146
	global_store_dwordx4 v[88:89], v[68:71], off offset:512
	global_store_dwordx4 v[88:89], v[64:67], off offset:528
	v_addc_co_u32_e32 v75, vcc, 0, v147, vcc
	v_lshl_add_u64 v[72:73], v[146:147], 0, s[12:13]
	s_nop 0
	s_nop 0
	s_nop 0
	s_waitcnt vmcnt(25)
	v_pk_fma_f32 v[62:63], v[62:63], 0.5, v[166:167] op_sel_hi:[1,0,1]
	v_pk_fma_f32 v[60:61], v[60:61], 0.5, v[164:165] op_sel_hi:[1,0,1]
	s_nop 0
	v_pk_fma_f32 v[58:59], v[58:59], 0.5, v[170:171] op_sel_hi:[1,0,1]
	v_pk_fma_f32 v[56:57], v[56:57], 0.5, v[168:169] op_sel_hi:[1,0,1]
	global_store_dwordx4 v[74:75], v[60:63], off
	global_store_dwordx4 v[72:73], v[56:59], off offset:16
	s_nop 0
	s_nop 0
	s_nop 0
	s_nop 0
	v_pk_fma_f32 v[50:51], v[50:51], 0.5, v[178:179] op_sel_hi:[1,0,1]
	s_nop 0
	v_pk_fma_f32 v[54:55], v[54:55], 0.5, v[174:175] op_sel_hi:[1,0,1]
	v_pk_fma_f32 v[52:53], v[52:53], 0.5, v[172:173] op_sel_hi:[1,0,1]
	v_pk_fma_f32 v[48:49], v[48:49], 0.5, v[176:177] op_sel_hi:[1,0,1]
	v_add_co_u32_e32 v58, vcc, s44, v146
	global_store_dwordx4 v[72:73], v[52:55], off offset:512
	global_store_dwordx4 v[72:73], v[48:51], off offset:528
	v_addc_co_u32_e32 v59, vcc, 0, v147, vcc
	v_lshl_add_u64 v[56:57], v[146:147], 0, s[18:19]
	s_nop 0
	s_nop 0
	s_nop 0
	s_waitcnt vmcnt(21)
	v_pk_fma_f32 v[46:47], v[46:47], 0.5, v[182:183] op_sel_hi:[1,0,1]
	v_pk_fma_f32 v[44:45], v[44:45], 0.5, v[180:181] op_sel_hi:[1,0,1]
	s_nop 0
	v_pk_fma_f32 v[42:43], v[42:43], 0.5, v[190:191] op_sel_hi:[1,0,1]
	v_pk_fma_f32 v[40:41], v[40:41], 0.5, v[188:189] op_sel_hi:[1,0,1]
	global_store_dwordx4 v[58:59], v[44:47], off
	global_store_dwordx4 v[56:57], v[40:43], off offset:16
	s_nop 0
	s_nop 0
	s_nop 0
	s_nop 0
	v_pk_fma_f32 v[34:35], v[34:35], 0.5, v[198:199] op_sel_hi:[1,0,1]
	s_nop 0
	v_pk_fma_f32 v[38:39], v[38:39], 0.5, v[194:195] op_sel_hi:[1,0,1]
	v_pk_fma_f32 v[36:37], v[36:37], 0.5, v[192:193] op_sel_hi:[1,0,1]
	v_pk_fma_f32 v[32:33], v[32:33], 0.5, v[196:197] op_sel_hi:[1,0,1]
	v_add_co_u32_e32 v42, vcc, s45, v146
	global_store_dwordx4 v[56:57], v[36:39], off offset:512
	global_store_dwordx4 v[56:57], v[32:35], off offset:528
	v_addc_co_u32_e32 v43, vcc, 0, v147, vcc
	v_lshl_add_u64 v[40:41], v[146:147], 0, s[20:21]
	s_nop 0
	s_nop 0
	s_nop 0
	s_waitcnt vmcnt(17)
	v_pk_fma_f32 v[30:31], v[30:31], 0.5, v[202:203] op_sel_hi:[1,0,1]
	v_pk_fma_f32 v[28:29], v[28:29], 0.5, v[200:201] op_sel_hi:[1,0,1]
	s_nop 0
	v_pk_fma_f32 v[26:27], v[26:27], 0.5, v[206:207] op_sel_hi:[1,0,1]
	v_pk_fma_f32 v[24:25], v[24:25], 0.5, v[204:205] op_sel_hi:[1,0,1]
	global_store_dwordx4 v[42:43], v[28:31], off
	global_store_dwordx4 v[40:41], v[24:27], off offset:16
	s_nop 0
	s_nop 0
	s_nop 0
	s_nop 0
	v_pk_fma_f32 v[18:19], v[18:19], 0.5, v[214:215] op_sel_hi:[1,0,1]
	s_nop 0
	v_pk_fma_f32 v[22:23], v[22:23], 0.5, v[210:211] op_sel_hi:[1,0,1]
	v_pk_fma_f32 v[20:21], v[20:21], 0.5, v[208:209] op_sel_hi:[1,0,1]
	v_pk_fma_f32 v[16:17], v[16:17], 0.5, v[212:213] op_sel_hi:[1,0,1]
	v_add_co_u32_e32 v26, vcc, s46, v146
	global_store_dwordx4 v[40:41], v[20:23], off offset:512
	global_store_dwordx4 v[40:41], v[16:19], off offset:528
	v_addc_co_u32_e32 v27, vcc, 0, v147, vcc
	s_nop 0
	v_lshl_add_u64 v[16:17], v[146:147], 0, s[4:5]
	s_nop 0
	s_nop 0
	s_and_b64 vcc, exec, s[0:1]
	s_nop 0
	s_waitcnt vmcnt(14)
	v_pk_fma_f32 v[14:15], v[14:15], 0.5, v[218:219] op_sel_hi:[1,0,1]
	v_pk_fma_f32 v[12:13], v[12:13], 0.5, v[216:217] op_sel_hi:[1,0,1]
	s_nop 0
	v_pk_fma_f32 v[10:11], v[10:11], 0.5, v[222:223] op_sel_hi:[1,0,1]
	v_pk_fma_f32 v[8:9], v[8:9], 0.5, v[220:221] op_sel_hi:[1,0,1]
	global_store_dwordx4 v[26:27], v[12:15], off
	global_store_dwordx4 v[16:17], v[8:11], off offset:16
	s_nop 0
	s_nop 0
	s_nop 0
	s_nop 0
	v_pk_fma_f32 v[2:3], v[2:3], 0.5, v[236:237] op_sel_hi:[1,0,1]
	s_nop 0
	v_pk_fma_f32 v[6:7], v[6:7], 0.5, v[226:227] op_sel_hi:[1,0,1]
	v_pk_fma_f32 v[4:5], v[4:5], 0.5, v[224:225] op_sel_hi:[1,0,1]
	v_pk_fma_f32 v[0:1], v[0:1], 0.5, v[234:235] op_sel_hi:[1,0,1]
	global_store_dwordx4 v[16:17], v[4:7], off offset:512
	global_store_dwordx4 v[16:17], v[0:3], off offset:528
	s_cbranch_vccnz .LBB0_1760
	s_andn2_b64 vcc, exec, s[6:7]
	s_cbranch_vccnz .LBB0_1759
	s_barrier
	s_branch .LBB0_1759
